# stack4 + write-through AO (P3) and XC/SG (P5) stores; grid barriers after P3, P4, P5 without the L2 write-back (everything those phases publish is written through)
# speedup vs baseline: 1.0050x; 1.0019x over previous
.LBB0_507:
	s_or_b64 exec, exec, s[6:7]
	v_add_u32_e32 v74, s29, v195
	s_waitcnt vmcnt(0) lgkmcnt(0)
	s_waitcnt lgkmcnt(0)
	s_barrier
	ds_read_b128 v[66:69], v74
	ds_read_b128 v[70:73], v74 offset:32
	s_add_u32 s6, s52, s70
	s_addc_u32 s7, s53, s71
	s_lshl_b64 s[98:99], s[10:11], 12
	s_add_u32 s98, s6, s98
	s_addc_u32 s99, s7, s99
	s_mov_b64 s[100:101], 0x4000
	v_lshl_add_u64 v[116:117], s[98:99], 0, v[178:179]
	v_lshlrev_b32_e32 v118, 1, v180
	v_mov_b32_e32 v119, v179
	v_lshl_add_u64 v[116:117], v[116:117], 0, v[118:119]
	global_load_dwordx4 v[84:87], v[116:117], off
	v_lshl_add_u64 v[116:117], v[116:117], 0, s[100:101]
	global_load_dwordx4 v[88:91], v[116:117], off
	v_lshl_add_u64 v[116:117], v[116:117], 0, s[100:101]
	global_load_dwordx4 v[92:95], v[116:117], off
	v_lshl_add_u64 v[116:117], v[116:117], 0, s[100:101]
	global_load_dwordx4 v[96:99], v[116:117], off
	v_lshl_add_u64 v[116:117], v[116:117], 0, s[100:101]
	global_load_dwordx4 v[100:103], v[116:117], off
	v_lshl_add_u64 v[116:117], v[116:117], 0, s[100:101]
	global_load_dwordx4 v[104:107], v[116:117], off
	v_lshl_add_u64 v[116:117], v[116:117], 0, s[100:101]
	global_load_dwordx4 v[108:111], v[116:117], off
	v_lshl_add_u64 v[116:117], v[116:117], 0, s[100:101]
	global_load_dwordx4 v[112:115], v[116:117], off
	s_lshl_b32 s28, s28, 13
	s_waitcnt lgkmcnt(1)
	v_rcp_f32_e32 v75, v66
	s_add_i32 s28, s28, 0
	v_rcp_f32_e32 v76, v67
	v_rcp_f32_e32 v77, v68
	v_mul_f32_e32 v2, v2, v75
	v_rcp_f32_e32 v78, v69
	s_waitcnt lgkmcnt(0)
	v_rcp_f32_e32 v79, v70
	ds_read_b128 v[66:69], v74 offset:64
	v_rcp_f32_e32 v80, v71
	v_rcp_f32_e32 v81, v72
	v_rcp_f32_e32 v82, v73
	ds_read_b128 v[70:73], v74 offset:96
	v_add3_u32 v74, s28, v197, v198
	v_cvt_pk_bf16_f32 v2, v2, v2
	ds_write_b16 v74, v2
	v_mul_f32_e32 v2, v50, v75
	v_cvt_pk_bf16_f32 v2, v2, v2
	ds_write_b16 v74, v2 offset:64
	v_mul_f32_e32 v2, v34, v75
	v_cvt_pk_bf16_f32 v2, v2, v2
	ds_write_b16 v74, v2 offset:128
	v_mul_f32_e32 v2, v18, v75
	v_cvt_pk_bf16_f32 v2, v2, v2
	ds_write_b16 v74, v2 offset:192
	v_mul_f32_e32 v2, v3, v76
	v_cvt_pk_bf16_f32 v2, v2, v2
	ds_write_b16 v74, v2 offset:256
	v_mul_f32_e32 v2, v51, v76
	v_cvt_pk_bf16_f32 v2, v2, v2
	ds_write_b16 v74, v2 offset:320
	v_mul_f32_e32 v2, v35, v76
	v_cvt_pk_bf16_f32 v2, v2, v2
	ds_write_b16 v74, v2 offset:384
	v_mul_f32_e32 v2, v19, v76
	v_cvt_pk_bf16_f32 v2, v2, v2
	ds_write_b16 v74, v2 offset:448
	v_mul_f32_e32 v2, v4, v77
	v_cvt_pk_bf16_f32 v2, v2, v2
	ds_write_b16 v74, v2 offset:512
	v_mul_f32_e32 v2, v52, v77
	v_cvt_pk_bf16_f32 v2, v2, v2
	ds_write_b16 v74, v2 offset:576
	v_mul_f32_e32 v2, v36, v77
	v_cvt_pk_bf16_f32 v2, v2, v2
	ds_write_b16 v74, v2 offset:640
	v_mul_f32_e32 v2, v20, v77
	v_cvt_pk_bf16_f32 v2, v2, v2
	ds_write_b16 v74, v2 offset:704
	v_mul_f32_e32 v2, v5, v78
	v_cvt_pk_bf16_f32 v2, v2, v2
	ds_write_b16 v74, v2 offset:768
	v_mul_f32_e32 v2, v53, v78
	v_cvt_pk_bf16_f32 v2, v2, v2
	ds_write_b16 v74, v2 offset:832
	v_mul_f32_e32 v2, v37, v78
	v_cvt_pk_bf16_f32 v2, v2, v2
	ds_write_b16 v74, v2 offset:896
	v_mul_f32_e32 v2, v21, v78
	v_cvt_pk_bf16_f32 v2, v2, v2
	ds_write_b16 v74, v2 offset:960
	v_mul_f32_e32 v2, v6, v79
	v_cvt_pk_bf16_f32 v2, v2, v2
	ds_write_b16 v74, v2 offset:2048
	v_mul_f32_e32 v2, v54, v79
	v_cvt_pk_bf16_f32 v2, v2, v2
	ds_write_b16 v74, v2 offset:2112
	v_mul_f32_e32 v2, v38, v79
	v_cvt_pk_bf16_f32 v2, v2, v2
	ds_write_b16 v74, v2 offset:2176
	v_mul_f32_e32 v2, v22, v79
	v_cvt_pk_bf16_f32 v2, v2, v2
	ds_write_b16 v74, v2 offset:2240
	v_mul_f32_e32 v2, v7, v80
	v_cvt_pk_bf16_f32 v2, v2, v2
	ds_write_b16 v74, v2 offset:2304
	v_mul_f32_e32 v2, v55, v80
	v_cvt_pk_bf16_f32 v2, v2, v2
	ds_write_b16 v74, v2 offset:2368
	v_mul_f32_e32 v2, v39, v80
	v_cvt_pk_bf16_f32 v2, v2, v2
	ds_write_b16 v74, v2 offset:2432
	v_mul_f32_e32 v2, v23, v80
	v_cvt_pk_bf16_f32 v2, v2, v2
	ds_write_b16 v74, v2 offset:2496
	v_mul_f32_e32 v2, v8, v81
	v_cvt_pk_bf16_f32 v2, v2, v2
	ds_write_b16 v74, v2 offset:2560
	v_mul_f32_e32 v2, v56, v81
	v_cvt_pk_bf16_f32 v2, v2, v2
	ds_write_b16 v74, v2 offset:2624
	v_mul_f32_e32 v2, v40, v81
	v_cvt_pk_bf16_f32 v2, v2, v2
	ds_write_b16 v74, v2 offset:2688
	v_mul_f32_e32 v2, v24, v81
	v_cvt_pk_bf16_f32 v2, v2, v2
	ds_write_b16 v74, v2 offset:2752
	v_mul_f32_e32 v2, v9, v82
	v_cvt_pk_bf16_f32 v2, v2, v2
	ds_write_b16 v74, v2 offset:2816
	v_mul_f32_e32 v2, v57, v82
	v_cvt_pk_bf16_f32 v2, v2, v2
	s_waitcnt lgkmcnt(14)
	v_rcp_f32_e32 v66, v66
	ds_write_b16 v74, v2 offset:2880
	v_mul_f32_e32 v2, v41, v82
	v_cvt_pk_bf16_f32 v2, v2, v2
	ds_write_b16 v74, v2 offset:2944
	v_mul_f32_e32 v2, v25, v82
	v_cvt_pk_bf16_f32 v2, v2, v2
	ds_write_b16 v74, v2 offset:3008
	v_mul_f32_e32 v2, v10, v66
	v_cvt_pk_bf16_f32 v2, v2, v2
	ds_write_b16 v74, v2 offset:4096
	v_mul_f32_e32 v2, v58, v66
	v_cvt_pk_bf16_f32 v2, v2, v2
	v_rcp_f32_e32 v67, v67
	ds_write_b16 v74, v2 offset:4160
	v_mul_f32_e32 v2, v42, v66
	v_cvt_pk_bf16_f32 v2, v2, v2
	ds_write_b16 v74, v2 offset:4224
	v_mul_f32_e32 v2, v26, v66
	v_cvt_pk_bf16_f32 v2, v2, v2
	ds_write_b16 v74, v2 offset:4288
	v_mul_f32_e32 v2, v11, v67
	v_cvt_pk_bf16_f32 v2, v2, v2
	ds_write_b16 v74, v2 offset:4352
	v_mul_f32_e32 v2, v59, v67
	v_cvt_pk_bf16_f32 v2, v2, v2
	v_rcp_f32_e32 v68, v68
	ds_write_b16 v74, v2 offset:4416
	v_mul_f32_e32 v2, v43, v67
	v_cvt_pk_bf16_f32 v2, v2, v2
	ds_write_b16 v74, v2 offset:4480
	v_mul_f32_e32 v2, v27, v67
	v_cvt_pk_bf16_f32 v2, v2, v2
	ds_write_b16 v74, v2 offset:4544
	v_mul_f32_e32 v2, v12, v68
	v_cvt_pk_bf16_f32 v2, v2, v2
	ds_write_b16 v74, v2 offset:4608
	v_mul_f32_e32 v2, v60, v68
	v_cvt_pk_bf16_f32 v2, v2, v2
	v_rcp_f32_e32 v69, v69
	ds_write_b16 v74, v2 offset:4672
	v_mul_f32_e32 v2, v44, v68
	v_cvt_pk_bf16_f32 v2, v2, v2
	ds_write_b16 v74, v2 offset:4736
	v_mul_f32_e32 v2, v28, v68
	v_cvt_pk_bf16_f32 v2, v2, v2
	ds_write_b16 v74, v2 offset:4800
	v_mul_f32_e32 v2, v13, v69
	v_cvt_pk_bf16_f32 v2, v2, v2
	ds_write_b16 v74, v2 offset:4864
	v_mul_f32_e32 v2, v61, v69
	v_cvt_pk_bf16_f32 v2, v2, v2
	v_rcp_f32_e32 v70, v70
	ds_write_b16 v74, v2 offset:4928
	v_mul_f32_e32 v2, v45, v69
	v_cvt_pk_bf16_f32 v2, v2, v2
	ds_write_b16 v74, v2 offset:4992
	v_mul_f32_e32 v2, v29, v69
	v_cvt_pk_bf16_f32 v2, v2, v2
	ds_write_b16 v74, v2 offset:5056
	v_mul_f32_e32 v2, v14, v70
	v_cvt_pk_bf16_f32 v2, v2, v2
	ds_write_b16 v74, v2 offset:6144
	v_mul_f32_e32 v2, v62, v70
	v_cvt_pk_bf16_f32 v2, v2, v2
	v_rcp_f32_e32 v71, v71
	ds_write_b16 v74, v2 offset:6208
	v_mul_f32_e32 v2, v46, v70
	v_cvt_pk_bf16_f32 v2, v2, v2
	ds_write_b16 v74, v2 offset:6272
	v_mul_f32_e32 v2, v30, v70
	v_cvt_pk_bf16_f32 v2, v2, v2
	ds_write_b16 v74, v2 offset:6336
	v_mul_f32_e32 v2, v15, v71
	v_cvt_pk_bf16_f32 v2, v2, v2
	ds_write_b16 v74, v2 offset:6400
	v_mul_f32_e32 v2, v63, v71
	v_cvt_pk_bf16_f32 v2, v2, v2
	v_rcp_f32_e32 v72, v72
	ds_write_b16 v74, v2 offset:6464
	v_mul_f32_e32 v2, v47, v71
	v_cvt_pk_bf16_f32 v2, v2, v2
	ds_write_b16 v74, v2 offset:6528
	v_mul_f32_e32 v2, v31, v71
	v_cvt_pk_bf16_f32 v2, v2, v2
	ds_write_b16 v74, v2 offset:6592
	v_mul_f32_e32 v2, v16, v72
	v_cvt_pk_bf16_f32 v2, v2, v2
	ds_write_b16 v74, v2 offset:6656
	v_mul_f32_e32 v2, v64, v72
	v_cvt_pk_bf16_f32 v2, v2, v2
	v_rcp_f32_e32 v73, v73
	ds_write_b16 v74, v2 offset:6720
	v_mul_f32_e32 v2, v48, v72
	v_cvt_pk_bf16_f32 v2, v2, v2
	ds_write_b16 v74, v2 offset:6784
	v_mul_f32_e32 v2, v32, v72
	v_cvt_pk_bf16_f32 v2, v2, v2
	ds_write_b16 v74, v2 offset:6848
	v_mul_f32_e32 v2, v17, v73
	v_cvt_pk_bf16_f32 v2, v2, v2
	ds_write_b16 v74, v2 offset:6912
	v_mul_f32_e32 v2, v65, v73
	v_cvt_pk_bf16_f32 v2, v2, v2
	ds_write_b16 v74, v2 offset:6976
	v_mul_f32_e32 v2, v49, v73
	v_cvt_pk_bf16_f32 v2, v2, v2
	s_lshl_b64 s[30:31], s[10:11], 12
	ds_write_b16 v74, v2 offset:7040
	v_mul_f32_e32 v2, v33, v73
	s_add_u32 s6, s6, s30
	v_cvt_pk_bf16_f32 v2, v2, v2
	s_addc_u32 s7, s7, s31
	ds_write_b16 v74, v2 offset:7104
	v_lshl_add_u64 v[2:3], s[6:7], 0, v[178:179]
	v_lshlrev_b32_e32 v4, 1, v180
	v_mov_b32_e32 v5, v179
	s_waitcnt lgkmcnt(0)
	v_lshl_add_u64 v[2:3], v[2:3], 0, v[4:5]
	s_nop 0
	v_add3_u32 v4, s28, v199, v200
	ds_read_b128 v[10:13], v4
	s_add_i32 s6, s10, s68
	s_mov_b64 s[36:37], 0
	s_waitcnt lgkmcnt(0)
	v_lshlrev_b32_e32 v14, 16, v10
	v_and_b32_e32 v10, 0xffff0000, v10
	s_waitcnt vmcnt(0)
	v_lshlrev_b32_e32 v5, 16, v84
	v_and_b32_e32 v6, 0xffff0000, v84
	v_mul_f32_e32 v5, v5, v14
	v_mul_f32_e32 v6, v6, v10
	v_cvt_pk_bf16_f32 v10, v5, v6
	v_lshlrev_b32_e32 v5, 16, v85
	v_lshlrev_b32_e32 v6, 16, v11
	v_mul_f32_e32 v5, v5, v6
	v_and_b32_e32 v6, 0xffff0000, v85
	v_and_b32_e32 v7, 0xffff0000, v11
	v_mul_f32_e32 v6, v6, v7
	v_cvt_pk_bf16_f32 v11, v5, v6
	v_lshlrev_b32_e32 v5, 16, v86
	v_lshlrev_b32_e32 v6, 16, v12
	v_mul_f32_e32 v5, v5, v6
	v_and_b32_e32 v6, 0xffff0000, v86
	v_and_b32_e32 v7, 0xffff0000, v12
	v_mul_f32_e32 v6, v6, v7
	v_cvt_pk_bf16_f32 v12, v5, v6
	v_lshlrev_b32_e32 v5, 16, v87
	v_lshlrev_b32_e32 v6, 16, v13
	v_mul_f32_e32 v5, v5, v6
	v_and_b32_e32 v6, 0xffff0000, v87
	v_and_b32_e32 v7, 0xffff0000, v13
	v_mul_f32_e32 v6, v6, v7
	v_cvt_pk_bf16_f32 v13, v5, v6
	v_add_co_u32_e32 v6, vcc, s14, v2
	v_or_b32_e32 v5, s25, v180
	s_nop 0
	v_addc_co_u32_e32 v7, vcc, 0, v3, vcc
	s_nop 0
	v_add_u32_e32 v6, s6, v1
	v_lshlrev_b32_e32 v18, 2, v6
	v_and_b32_e32 v22, 32, v18
	ds_read_b128 v[18:21], v4 offset:1024
	v_lshrrev_b32_e32 v5, 6, v5
	v_lshrrev_b32_e32 v7, 2, v6
	v_lshrrev_b32_e32 v8, 3, v6
	v_lshlrev_b32_e32 v9, 6, v6
	v_and_or_b32 v7, v7, s21, v5
	v_and_or_b32 v8, v8, 14, v201
	v_and_b32_e32 v9, 0x3c0, v9
	v_lshlrev_b32_e32 v7, 14, v7
	v_lshlrev_b32_e32 v8, 10, v8
	v_bitop3_b32 v9, v9, v22, v202 bitop3:0x36
	v_or3_b32 v7, v9, v8, v7
	global_store_dwordx4 v7, v[10:13], s[58:59] sc1
	s_waitcnt lgkmcnt(0)
	v_lshlrev_b32_e32 v8, 16, v18
	v_and_b32_e32 v9, 0xffff0000, v18
	v_and_b32_e32 v10, 0xffff0000, v19
	v_and_b32_e32 v11, 0xffff0000, v20
	v_and_b32_e32 v12, 0xffff0000, v21
	s_nop 0
	v_lshlrev_b32_e32 v7, 16, v88
	v_mul_f32_e32 v7, v7, v8
	v_and_b32_e32 v8, 0xffff0000, v88
	v_mul_f32_e32 v8, v8, v9
	v_cvt_pk_bf16_f32 v8, v7, v8
	v_lshlrev_b32_e32 v7, 16, v89
	v_lshlrev_b32_e32 v9, 16, v19
	v_mul_f32_e32 v7, v7, v9
	v_and_b32_e32 v9, 0xffff0000, v89
	v_mul_f32_e32 v9, v9, v10
	v_cvt_pk_bf16_f32 v9, v7, v9
	v_lshlrev_b32_e32 v7, 16, v90
	v_lshlrev_b32_e32 v10, 16, v20
	v_mul_f32_e32 v7, v7, v10
	v_and_b32_e32 v10, 0xffff0000, v90
	v_mul_f32_e32 v10, v10, v11
	v_cvt_pk_bf16_f32 v10, v7, v10
	v_lshlrev_b32_e32 v7, 16, v91
	v_lshlrev_b32_e32 v11, 16, v21
	v_mul_f32_e32 v7, v7, v11
	v_and_b32_e32 v11, 0xffff0000, v91
	v_mul_f32_e32 v11, v11, v12
	v_add_co_u32_e32 v12, vcc, s1, v2
	v_cvt_pk_bf16_f32 v11, v7, v11
	v_add_u32_e32 v7, 4, v6
	s_nop 0
	v_addc_co_u32_e32 v13, vcc, 0, v3, vcc
	s_nop 0
	v_lshrrev_b32_e32 v16, 2, v7
	v_and_or_b32 v16, v16, s21, v5
	v_lshlrev_b32_e32 v20, 14, v16
	v_lshrrev_b32_e32 v16, 3, v7
	v_and_or_b32 v16, v16, 14, v201
	v_lshlrev_b32_e32 v17, 6, v7
	v_and_b32_e32 v21, 0x3c0, v17
	v_lshlrev_b32_e32 v22, 10, v16
	ds_read_b128 v[16:19], v4 offset:2048
	v_lshlrev_b32_e32 v7, 2, v7
	v_and_b32_e32 v7, 32, v7
	v_bitop3_b32 v7, v21, v7, v202 bitop3:0x36
	v_or3_b32 v7, v7, v22, v20
	global_store_dwordx4 v7, v[8:11], s[58:59] sc1
	s_nop 0
	v_lshlrev_b32_e32 v7, 16, v92
	s_waitcnt lgkmcnt(0)
	v_lshlrev_b32_e32 v8, 16, v16
	v_mul_f32_e32 v7, v7, v8
	v_and_b32_e32 v8, 0xffff0000, v92
	v_and_b32_e32 v9, 0xffff0000, v16
	v_mul_f32_e32 v8, v8, v9
	v_cvt_pk_bf16_f32 v8, v7, v8
	v_lshlrev_b32_e32 v7, 16, v93
	v_lshlrev_b32_e32 v9, 16, v17
	v_mul_f32_e32 v7, v7, v9
	v_and_b32_e32 v9, 0xffff0000, v93
	v_and_b32_e32 v10, 0xffff0000, v17
	v_mul_f32_e32 v9, v9, v10
	v_cvt_pk_bf16_f32 v9, v7, v9
	v_lshlrev_b32_e32 v7, 16, v94
	v_lshlrev_b32_e32 v10, 16, v18
	v_mul_f32_e32 v7, v7, v10
	v_and_b32_e32 v10, 0xffff0000, v94
	v_and_b32_e32 v11, 0xffff0000, v18
	v_mul_f32_e32 v10, v10, v11
	v_cvt_pk_bf16_f32 v10, v7, v10
	v_lshlrev_b32_e32 v7, 16, v95
	v_lshlrev_b32_e32 v11, 16, v19
	v_mul_f32_e32 v7, v7, v11
	v_and_b32_e32 v11, 0xffff0000, v95
	v_and_b32_e32 v12, 0xffff0000, v19
	v_mul_f32_e32 v11, v11, v12
	v_add_co_u32_e32 v12, vcc, s2, v2
	v_cvt_pk_bf16_f32 v11, v7, v11
	v_add_u32_e32 v7, 8, v6
	s_nop 0
	v_addc_co_u32_e32 v13, vcc, 0, v3, vcc
	s_nop 0
	v_lshrrev_b32_e32 v16, 2, v7
	v_lshrrev_b32_e32 v17, 3, v7
	v_lshlrev_b32_e32 v18, 6, v7
	v_and_or_b32 v16, v16, s21, v5
	v_and_or_b32 v20, v17, 14, v201
	v_and_b32_e32 v21, 0x3c0, v18
	v_lshlrev_b32_e32 v22, 14, v16
	ds_read_b128 v[16:19], v4 offset:3072
	v_lshlrev_b32_e32 v7, 2, v7
	v_and_b32_e32 v7, 32, v7
	v_lshlrev_b32_e32 v20, 10, v20
	v_bitop3_b32 v7, v21, v7, v202 bitop3:0x36
	v_or3_b32 v7, v7, v20, v22
	global_store_dwordx4 v7, v[8:11], s[58:59] sc1
	s_waitcnt lgkmcnt(0)
	v_lshlrev_b32_e32 v7, 16, v16
	s_nop 0
	v_lshlrev_b32_e32 v20, 16, v97
	v_and_b32_e32 v8, 0xffff0000, v16
	v_lshlrev_b32_e32 v9, 16, v17
	v_and_b32_e32 v10, 0xffff0000, v17
	v_lshlrev_b32_e32 v11, 16, v18
	v_and_b32_e32 v16, 0xffff0000, v18
	v_lshlrev_b32_e32 v17, 16, v19
	v_and_b32_e32 v18, 0xffff0000, v19
	v_lshlrev_b32_e32 v19, 16, v96
	v_and_b32_e32 v12, 0xffff0000, v96
	v_and_b32_e32 v13, 0xffff0000, v97
	v_lshlrev_b32_e32 v21, 16, v98
	v_and_b32_e32 v14, 0xffff0000, v98
	v_lshlrev_b32_e32 v22, 16, v99
	v_mul_f32_e32 v8, v12, v8
	v_mul_f32_e32 v9, v20, v9
	v_mul_f32_e32 v10, v13, v10
	v_mul_f32_e32 v12, v14, v16
	v_and_b32_e32 v15, 0xffff0000, v99
	v_mul_f32_e32 v7, v19, v7
	v_mul_f32_e32 v11, v21, v11
	v_mul_f32_e32 v13, v22, v17
	v_cvt_pk_bf16_f32 v8, v7, v8
	v_cvt_pk_bf16_f32 v9, v9, v10
	v_cvt_pk_bf16_f32 v10, v11, v12
	v_add_co_u32_e32 v12, vcc, s13, v2
	v_mul_f32_e32 v7, v15, v18
	v_cvt_pk_bf16_f32 v11, v13, v7
	s_nop 0
	v_addc_co_u32_e32 v13, vcc, 0, v3, vcc
	s_nop 0
	v_add_u32_e32 v7, 12, v6
	v_lshrrev_b32_e32 v16, 2, v7
	v_lshrrev_b32_e32 v17, 3, v7
	v_lshlrev_b32_e32 v18, 6, v7
	v_and_or_b32 v16, v16, s21, v5
	v_and_or_b32 v22, v17, 14, v201
	v_and_b32_e32 v23, 0x3c0, v18
	v_lshlrev_b32_e32 v24, 14, v16
	ds_read_b128 v[16:19], v4 offset:4096
	v_lshlrev_b32_e32 v7, 2, v7
	v_and_b32_e32 v7, 32, v7
	v_lshlrev_b32_e32 v22, 10, v22
	v_bitop3_b32 v7, v23, v7, v202 bitop3:0x36
	v_or3_b32 v7, v7, v22, v24
	v_add_co_u32_e32 v20, vcc, s3, v2
	global_store_dwordx4 v7, v[8:11], s[58:59] sc1
	s_waitcnt lgkmcnt(0)
	v_lshlrev_b32_e32 v7, 16, v16
	v_addc_co_u32_e32 v21, vcc, 0, v3, vcc
	v_and_b32_e32 v8, 0xffff0000, v16
	v_lshlrev_b32_e32 v9, 16, v17
	v_and_b32_e32 v10, 0xffff0000, v17
	v_lshlrev_b32_e32 v11, 16, v18
	v_and_b32_e32 v16, 0xffff0000, v18
	v_lshlrev_b32_e32 v17, 16, v19
	v_and_b32_e32 v18, 0xffff0000, v19
	s_nop 0
	v_lshlrev_b32_e32 v19, 16, v100
	v_and_b32_e32 v12, 0xffff0000, v100
	v_lshlrev_b32_e32 v22, 16, v101
	v_and_b32_e32 v13, 0xffff0000, v101
	v_lshlrev_b32_e32 v23, 16, v102
	v_and_b32_e32 v14, 0xffff0000, v102
	v_lshlrev_b32_e32 v24, 16, v103
	v_and_b32_e32 v15, 0xffff0000, v103
	v_mul_f32_e32 v8, v12, v8
	v_mul_f32_e32 v9, v22, v9
	v_mul_f32_e32 v10, v13, v10
	v_mul_f32_e32 v11, v23, v11
	v_mul_f32_e32 v12, v14, v16
	v_mul_f32_e32 v13, v24, v17
	v_mul_f32_e32 v14, v15, v18
	v_mul_f32_e32 v7, v19, v7
	v_cvt_pk_bf16_f32 v8, v7, v8
	v_cvt_pk_bf16_f32 v9, v9, v10
	v_cvt_pk_bf16_f32 v10, v11, v12
	v_cvt_pk_bf16_f32 v11, v13, v14
	s_nop 0
	v_add_u32_e32 v7, 16, v6
	v_lshrrev_b32_e32 v16, 2, v7
	v_lshrrev_b32_e32 v17, 3, v7
	v_lshlrev_b32_e32 v18, 6, v7
	v_and_or_b32 v16, v16, s21, v5
	v_and_or_b32 v22, v17, 14, v201
	v_and_b32_e32 v23, 0x3c0, v18
	v_lshlrev_b32_e32 v24, 14, v16
	ds_read_b128 v[16:19], v4 offset:5120
	v_lshlrev_b32_e32 v7, 2, v7
	v_and_b32_e32 v7, 32, v7
	v_lshlrev_b32_e32 v22, 10, v22
	v_bitop3_b32 v7, v23, v7, v202 bitop3:0x36
	v_or3_b32 v7, v7, v22, v24
	v_add_co_u32_e32 v20, vcc, s22, v2
	global_store_dwordx4 v7, v[8:11], s[58:59] sc1
	s_waitcnt lgkmcnt(0)
	v_lshlrev_b32_e32 v7, 16, v16
	v_addc_co_u32_e32 v21, vcc, 0, v3, vcc
	v_and_b32_e32 v8, 0xffff0000, v16
	v_lshlrev_b32_e32 v9, 16, v17
	v_and_b32_e32 v10, 0xffff0000, v17
	v_lshlrev_b32_e32 v11, 16, v18
	v_and_b32_e32 v16, 0xffff0000, v18
	v_lshlrev_b32_e32 v17, 16, v19
	v_and_b32_e32 v18, 0xffff0000, v19
	v_add_co_u32_e32 v2, vcc, s23, v2
	s_nop 0
	v_lshlrev_b32_e32 v19, 16, v104
	v_and_b32_e32 v12, 0xffff0000, v104
	v_lshlrev_b32_e32 v22, 16, v105
	v_and_b32_e32 v13, 0xffff0000, v105
	v_lshlrev_b32_e32 v23, 16, v106
	v_and_b32_e32 v14, 0xffff0000, v106
	v_lshlrev_b32_e32 v24, 16, v107
	v_and_b32_e32 v15, 0xffff0000, v107
	v_mul_f32_e32 v8, v12, v8
	v_mul_f32_e32 v9, v22, v9
	v_mul_f32_e32 v10, v13, v10
	v_mul_f32_e32 v11, v23, v11
	v_mul_f32_e32 v12, v14, v16
	v_mul_f32_e32 v13, v24, v17
	v_mul_f32_e32 v14, v15, v18
	v_mul_f32_e32 v7, v19, v7
	v_cvt_pk_bf16_f32 v8, v7, v8
	v_cvt_pk_bf16_f32 v9, v9, v10
	v_cvt_pk_bf16_f32 v10, v11, v12
	v_cvt_pk_bf16_f32 v11, v13, v14
	s_nop 0
	v_add_u32_e32 v7, 20, v6
	v_lshrrev_b32_e32 v16, 2, v7
	v_lshrrev_b32_e32 v17, 3, v7
	v_lshlrev_b32_e32 v18, 6, v7
	v_and_or_b32 v16, v16, s21, v5
	v_and_or_b32 v20, v17, 14, v201
	v_and_b32_e32 v21, 0x3c0, v18
	v_lshlrev_b32_e32 v22, 14, v16
	ds_read_b128 v[16:19], v4 offset:6144
	v_lshlrev_b32_e32 v7, 2, v7
	v_and_b32_e32 v7, 32, v7
	v_lshlrev_b32_e32 v20, 10, v20
	v_bitop3_b32 v7, v21, v7, v202 bitop3:0x36
	v_or3_b32 v7, v7, v20, v22
	global_store_dwordx4 v7, v[8:11], s[58:59] sc1
	s_waitcnt lgkmcnt(0)
	v_lshlrev_b32_e32 v7, 16, v16
	v_addc_co_u32_e32 v3, vcc, 0, v3, vcc
	v_and_b32_e32 v8, 0xffff0000, v16
	v_lshlrev_b32_e32 v9, 16, v17
	v_and_b32_e32 v10, 0xffff0000, v17
	v_lshlrev_b32_e32 v11, 16, v18
	v_and_b32_e32 v16, 0xffff0000, v18
	v_lshlrev_b32_e32 v17, 16, v19
	v_and_b32_e32 v18, 0xffff0000, v19
	s_and_b64 vcc, exec, s[66:67]
	s_nop 0
	v_lshlrev_b32_e32 v19, 16, v108
	v_and_b32_e32 v12, 0xffff0000, v108
	v_lshlrev_b32_e32 v20, 16, v109
	v_and_b32_e32 v13, 0xffff0000, v109
	v_lshlrev_b32_e32 v21, 16, v110
	v_and_b32_e32 v14, 0xffff0000, v110
	v_lshlrev_b32_e32 v22, 16, v111
	v_and_b32_e32 v15, 0xffff0000, v111
	v_mul_f32_e32 v8, v12, v8
	v_mul_f32_e32 v9, v20, v9
	v_mul_f32_e32 v10, v13, v10
	v_mul_f32_e32 v11, v21, v11
	v_mul_f32_e32 v12, v14, v16
	v_mul_f32_e32 v13, v22, v17
	v_mul_f32_e32 v14, v15, v18
	v_mul_f32_e32 v7, v19, v7
	v_cvt_pk_bf16_f32 v8, v7, v8
	v_cvt_pk_bf16_f32 v9, v9, v10
	v_cvt_pk_bf16_f32 v10, v11, v12
	v_cvt_pk_bf16_f32 v11, v13, v14
	s_nop 0
	v_add_u32_e32 v2, 24, v6
	v_add_u32_e32 v3, 28, v6
	v_lshrrev_b32_e32 v6, 2, v2
	v_lshrrev_b32_e32 v7, 3, v2
	v_lshlrev_b32_e32 v16, 6, v2
	v_lshlrev_b32_e32 v2, 2, v2
	v_lshrrev_b32_e32 v17, 2, v3
	v_lshrrev_b32_e32 v18, 3, v3
	v_lshlrev_b32_e32 v19, 6, v3
	v_lshlrev_b32_e32 v3, 2, v3
	v_and_or_b32 v6, v6, s21, v5
	v_and_b32_e32 v16, 0x3c0, v16
	v_and_b32_e32 v2, 32, v2
	v_and_or_b32 v5, v17, s21, v5
	v_and_or_b32 v17, v18, 14, v201
	v_and_b32_e32 v18, 0x3c0, v19
	v_and_b32_e32 v19, 32, v3
	v_bitop3_b32 v16, v16, v2, v202 bitop3:0x36
	v_lshlrev_b32_e32 v20, 14, v5
	ds_read_b128 v[2:5], v4 offset:7168
	v_and_or_b32 v7, v7, 14, v201
	v_lshlrev_b32_e32 v6, 14, v6
	v_lshlrev_b32_e32 v7, 10, v7
	v_lshlrev_b32_e32 v17, 10, v17
	v_bitop3_b32 v18, v18, v19, v202 bitop3:0x36
	v_or3_b32 v6, v16, v7, v6
	v_or3_b32 v7, v18, v17, v20
	global_store_dwordx4 v6, v[8:11], s[58:59] sc1
	s_waitcnt lgkmcnt(0)
	v_lshlrev_b32_e32 v6, 16, v2
	v_and_b32_e32 v2, 0xffff0000, v2
	v_lshlrev_b32_e32 v8, 16, v3
	v_and_b32_e32 v3, 0xffff0000, v3
	v_lshlrev_b32_e32 v9, 16, v4
	v_and_b32_e32 v4, 0xffff0000, v4
	v_lshlrev_b32_e32 v10, 16, v5
	v_and_b32_e32 v5, 0xffff0000, v5
	s_nop 0
	v_lshlrev_b32_e32 v11, 16, v112
	v_and_b32_e32 v12, 0xffff0000, v112
	v_lshlrev_b32_e32 v16, 16, v113
	v_and_b32_e32 v13, 0xffff0000, v113
	v_lshlrev_b32_e32 v17, 16, v114
	v_and_b32_e32 v14, 0xffff0000, v114
	v_lshlrev_b32_e32 v18, 16, v115
	v_and_b32_e32 v15, 0xffff0000, v115
	v_mul_f32_e32 v2, v12, v2
	v_mul_f32_e32 v3, v13, v3
	v_mul_f32_e32 v4, v14, v4
	v_mul_f32_e32 v5, v15, v5
	v_mul_f32_e32 v6, v11, v6
	v_mul_f32_e32 v8, v16, v8
	v_mul_f32_e32 v9, v17, v9
	v_mul_f32_e32 v10, v18, v10
	v_cvt_pk_bf16_f32 v2, v6, v2
	v_cvt_pk_bf16_f32 v3, v8, v3
	v_cvt_pk_bf16_f32 v4, v9, v4
	v_cvt_pk_bf16_f32 v5, v10, v5
	global_store_dwordx4 v7, v[2:5], s[58:59] sc1
	s_waitcnt lgkmcnt(0)
	s_barrier
	s_cbranch_vccnz .LBB0_505

.LBB0_556:
	s_or_b64 exec, exec, s[4:5]
	v_cvt_f32_u32_e32 v5, v2
	s_waitcnt vmcnt(0)
	v_readfirstlane_b32 s0, v4
	v_sub_u32_e32 v6, 0, v2
	v_cmp_lt_u32_e64 s[4:5], 1, v2
	v_rcp_iflag_f32_e32 v5, v5
	v_add_u32_e32 v4, s0, v3
	v_mul_f32_e32 v5, 0x4f7ffffe, v5
	v_cvt_u32_f32_e32 v5, v5
	v_mul_lo_u32 v3, v6, v5
	v_mul_hi_u32 v3, v5, v3
	v_add_u32_e32 v3, v5, v3
	v_mul_hi_u32 v3, v4, v3
	v_mul_lo_u32 v5, v3, v2
	v_sub_u32_e32 v5, v4, v5
	v_add_u32_e32 v6, 1, v3
	v_cmp_ge_u32_e32 vcc, v5, v2
	s_nop 1
	v_cndmask_b32_e32 v3, v3, v6, vcc
	v_sub_u32_e32 v6, v5, v2
	v_cndmask_b32_e32 v5, v5, v6, vcc
	v_add_u32_e32 v6, 1, v3
	v_cmp_ge_u32_e32 vcc, v5, v2
	s_nop 1
	v_cndmask_b32_e32 v3, v3, v6, vcc
	v_mul_lo_u32 v5, v3, v2
	v_cmp_eq_u32_e32 vcc, v4, v5
	s_and_b64 s[0:1], s[4:5], vcc
	s_and_saveexec_b64 s[4:5], s[0:1]
	s_cbranch_execz .LBB0_558
	s_nop 0
.LBB0_558:
	s_or_b64 exec, exec, s[4:5]
	v_add_u32_e32 v4, 1, v4
	v_add_u32_e32 v2, v5, v2
	v_cmp_eq_u32_e32 vcc, v4, v2
	s_and_saveexec_b64 s[4:5], vcc
	s_cbranch_execz .LBB0_561
	s_mov_b64 s[10:11], exec
	v_mbcnt_lo_u32_b32 v2, s10, 0
	s_nop 0
	s_waitcnt lgkmcnt(0)
	s_waitcnt vmcnt(0)
	v_mbcnt_hi_u32_b32 v2, s11, v2
	v_cmp_eq_u32_e32 vcc, 0, v2
	s_and_b64 s[0:1], exec, vcc
	s_mov_b64 exec, s[0:1]
	s_cbranch_execz .LBB0_561
	s_bcnt1_i32_b64 s0, s[10:11]
	v_mov_b32_e32 v2, 0x3000
	v_mov_b32_e32 v4, s0
	global_atomic_add v2, v4, s[26:27] offset:1024

.LBB0_759:
	s_lshl_b32 s2, s0, 8
	v_lshlrev_b32_e32 v211, 4, v209
	s_add_i32 s2, s2, s16
	v_and_b32_e32 v211, 48, v211
	v_ashrrev_i32_e32 v212, 2, v209
	v_add3_u32 v219, s2, v212, v211
	v_lshlrev_b32_e32 v211, 1, v192
	s_waitcnt vmcnt(0)
	v_pk_fma_f32 v[214:215], v[128:129], v[168:169], v[160:161]
	v_pk_fma_f32 v[216:217], v[126:127], v[166:167], v[158:159]
	v_and_b32_e32 v228, 48, v211
	v_mov_b32_e32 v211, v214
	v_mov_b32_e32 v212, v217
	s_waitcnt lgkmcnt(0)
	s_nop 1
	v_fmac_f32_dpp v216, v126, v146 row_shr:1 row_mask:0xf bank_mask:0xf
	v_fmac_f32_dpp v212, v127, v147 row_shr:1 row_mask:0xf bank_mask:0xf
	v_fmac_f32_dpp v211, v128, v148 row_shr:1 row_mask:0xf bank_mask:0xf
	v_fmac_f32_dpp v215, v129, v149 row_shr:1 row_mask:0xf bank_mask:0xf
	v_fmac_f32_dpp v216, v178, v146 row_shl:15 row_mask:0xf bank_mask:0xf
	v_fmac_f32_dpp v212, v179, v147 row_shl:15 row_mask:0xf bank_mask:0xf
	v_fmac_f32_dpp v211, v180, v148 row_shl:15 row_mask:0xf bank_mask:0xf
	v_fmac_f32_dpp v215, v181, v149 row_shl:15 row_mask:0xf bank_mask:0xf
	v_fmac_f32_dpp v216, v126, v154 row_shl:1 row_mask:0xf bank_mask:0xf
	v_fmac_f32_dpp v212, v127, v155 row_shl:1 row_mask:0xf bank_mask:0xf
	v_fmac_f32_dpp v211, v128, v156 row_shl:1 row_mask:0xf bank_mask:0xf
	v_fmac_f32_dpp v215, v129, v157 row_shl:1 row_mask:0xf bank_mask:0xf
	v_fmac_f32_dpp v216, v110, v154 row_shr:15 row_mask:0xf bank_mask:0xf
	v_fmac_f32_dpp v212, v111, v155 row_shr:15 row_mask:0xf bank_mask:0xf
	v_fmac_f32_dpp v211, v112, v156 row_shr:15 row_mask:0xf bank_mask:0xf
	v_fmac_f32_dpp v215, v113, v157 row_shr:15 row_mask:0xf bank_mask:0xf
	v_fmac_f32_dpp v216, v126, v162 row_shl:2 row_mask:0xf bank_mask:0xf
	v_fmac_f32_dpp v212, v127, v163 row_shl:2 row_mask:0xf bank_mask:0xf
	v_fmac_f32_dpp v211, v128, v164 row_shl:2 row_mask:0xf bank_mask:0xf
	v_fmac_f32_dpp v215, v129, v165 row_shl:2 row_mask:0xf bank_mask:0xf
	v_fmac_f32_dpp v216, v110, v162 row_shr:14 row_mask:0xf bank_mask:0xf
	v_fmac_f32_dpp v212, v111, v163 row_shr:14 row_mask:0xf bank_mask:0xf
	v_fmac_f32_dpp v211, v112, v164 row_shr:14 row_mask:0xf bank_mask:0xf
	v_fmac_f32_dpp v215, v113, v165 row_shr:14 row_mask:0xf bank_mask:0xf
	v_pk_fma_f32 v[180:181], v[124:125], v[152:153], v[140:141]
	v_pk_fma_f32 v[222:223], v[122:123], v[150:151], v[138:139]
	v_mov_b32_e32 v217, v180
	v_mov_b32_e32 v214, v222
	v_bfe_u32 v225, v192, 5, 1
	s_nop 1
	v_fmac_f32_dpp v214, v122, v130 row_shr:1 row_mask:0xf bank_mask:0xf
	v_fmac_f32_dpp v223, v123, v131 row_shr:1 row_mask:0xf bank_mask:0xf
	v_fmac_f32_dpp v217, v124, v132 row_shr:1 row_mask:0xf bank_mask:0xf
	v_fmac_f32_dpp v181, v125, v133 row_shr:1 row_mask:0xf bank_mask:0xf
	v_fmac_f32_dpp v214, v182, v130 row_shl:15 row_mask:0xf bank_mask:0xf
	v_fmac_f32_dpp v223, v183, v131 row_shl:15 row_mask:0xf bank_mask:0xf
	v_fmac_f32_dpp v217, v184, v132 row_shl:15 row_mask:0xf bank_mask:0xf
	v_fmac_f32_dpp v181, v185, v133 row_shl:15 row_mask:0xf bank_mask:0xf
	v_fmac_f32_dpp v214, v122, v134 row_shl:1 row_mask:0xf bank_mask:0xf
	v_fmac_f32_dpp v223, v123, v135 row_shl:1 row_mask:0xf bank_mask:0xf
	v_fmac_f32_dpp v217, v124, v136 row_shl:1 row_mask:0xf bank_mask:0xf
	v_fmac_f32_dpp v181, v125, v137 row_shl:1 row_mask:0xf bank_mask:0xf
	v_fmac_f32_dpp v214, v106, v134 row_shr:15 row_mask:0xf bank_mask:0xf
	v_fmac_f32_dpp v223, v107, v135 row_shr:15 row_mask:0xf bank_mask:0xf
	v_fmac_f32_dpp v217, v108, v136 row_shr:15 row_mask:0xf bank_mask:0xf
	v_fmac_f32_dpp v181, v109, v137 row_shr:15 row_mask:0xf bank_mask:0xf
	v_fmac_f32_dpp v214, v122, v142 row_shl:2 row_mask:0xf bank_mask:0xf
	v_fmac_f32_dpp v223, v123, v143 row_shl:2 row_mask:0xf bank_mask:0xf
	v_fmac_f32_dpp v217, v124, v144 row_shl:2 row_mask:0xf bank_mask:0xf
	v_fmac_f32_dpp v181, v125, v145 row_shl:2 row_mask:0xf bank_mask:0xf
	v_fmac_f32_dpp v214, v106, v142 row_shr:14 row_mask:0xf bank_mask:0xf
	v_fmac_f32_dpp v223, v107, v143 row_shr:14 row_mask:0xf bank_mask:0xf
	v_fmac_f32_dpp v217, v108, v144 row_shr:14 row_mask:0xf bank_mask:0xf
	v_fmac_f32_dpp v181, v109, v145 row_shr:14 row_mask:0xf bank_mask:0xf
	v_lshrrev_b32_e32 v183, 3, v219
	v_and_or_b32 v183, v183, 14, v225
	v_ashrrev_i32_e32 v182, 2, v219
	v_lshlrev_b32_e32 v184, 6, v219
	v_lshlrev_b32_e32 v221, 10, v183
	v_lshlrev_b32_e32 v183, 2, v219
	v_ashrrev_i32_e32 v229, 6, v192
	v_cvt_pk_bf16_f32 v178, v216, v212
	v_cvt_pk_bf16_f32 v179, v211, v215
	v_and_b32_e32 v211, 0xffffffe0, v182
	v_and_or_b32 v184, v184, s96, v228
	v_and_b32_e32 v183, 32, v183
	v_add_u32_e32 v182, v229, v211
	v_bitop3_b32 v212, v184, v221, v183 bitop3:0xde
	v_cvt_pk_bf16_f32 v180, v214, v223
	v_cvt_pk_bf16_f32 v181, v217, v181
	v_lshl_or_b32 v182, v182, 14, v212
	global_store_dwordx4 v182, v[178:181], s[36:37] sc1
	v_pk_fma_f32 v[182:183], v[108:109], v[152:153], v[140:141]
	v_pk_fma_f32 v[184:185], v[106:107], v[150:151], v[138:139]
	v_pk_fma_f32 v[180:181], v[112:113], v[168:169], v[160:161]
	v_pk_fma_f32 v[178:179], v[110:111], v[166:167], v[158:159]
	s_andn2_b64 vcc, exec, s[48:49]
	s_nop 1
	v_fmac_f32_dpp v178, v110, v146 row_shr:1 row_mask:0xf bank_mask:0xf
	v_fmac_f32_dpp v179, v111, v147 row_shr:1 row_mask:0xf bank_mask:0xf
	v_fmac_f32_dpp v180, v112, v148 row_shr:1 row_mask:0xf bank_mask:0xf
	v_fmac_f32_dpp v181, v113, v149 row_shr:1 row_mask:0xf bank_mask:0xf
	v_fmac_f32_dpp v178, v126, v146 row_shl:15 row_mask:0xf bank_mask:0xf
	v_fmac_f32_dpp v179, v127, v147 row_shl:15 row_mask:0xf bank_mask:0xf
	v_fmac_f32_dpp v180, v128, v148 row_shl:15 row_mask:0xf bank_mask:0xf
	v_fmac_f32_dpp v181, v129, v149 row_shl:15 row_mask:0xf bank_mask:0xf
	v_fmac_f32_dpp v178, v110, v154 row_shl:1 row_mask:0xf bank_mask:0xf
	v_fmac_f32_dpp v179, v111, v155 row_shl:1 row_mask:0xf bank_mask:0xf
	v_fmac_f32_dpp v180, v112, v156 row_shl:1 row_mask:0xf bank_mask:0xf
	v_fmac_f32_dpp v181, v113, v157 row_shl:1 row_mask:0xf bank_mask:0xf
	v_fmac_f32_dpp v178, v94, v154 row_shr:15 row_mask:0xf bank_mask:0xf
	v_fmac_f32_dpp v179, v95, v155 row_shr:15 row_mask:0xf bank_mask:0xf
	v_fmac_f32_dpp v180, v96, v156 row_shr:15 row_mask:0xf bank_mask:0xf
	v_fmac_f32_dpp v181, v97, v157 row_shr:15 row_mask:0xf bank_mask:0xf
	v_fmac_f32_dpp v178, v110, v162 row_shl:2 row_mask:0xf bank_mask:0xf
	v_fmac_f32_dpp v179, v111, v163 row_shl:2 row_mask:0xf bank_mask:0xf
	v_fmac_f32_dpp v180, v112, v164 row_shl:2 row_mask:0xf bank_mask:0xf
	v_fmac_f32_dpp v181, v113, v165 row_shl:2 row_mask:0xf bank_mask:0xf
	v_fmac_f32_dpp v178, v94, v162 row_shr:14 row_mask:0xf bank_mask:0xf
	v_fmac_f32_dpp v179, v95, v163 row_shr:14 row_mask:0xf bank_mask:0xf
	v_fmac_f32_dpp v180, v96, v164 row_shr:14 row_mask:0xf bank_mask:0xf
	v_fmac_f32_dpp v181, v97, v165 row_shr:14 row_mask:0xf bank_mask:0xf
	s_nop 1
	v_fmac_f32_dpp v184, v106, v130 row_shr:1 row_mask:0xf bank_mask:0xf
	v_fmac_f32_dpp v185, v107, v131 row_shr:1 row_mask:0xf bank_mask:0xf
	v_fmac_f32_dpp v182, v108, v132 row_shr:1 row_mask:0xf bank_mask:0xf
	v_fmac_f32_dpp v183, v109, v133 row_shr:1 row_mask:0xf bank_mask:0xf
	v_fmac_f32_dpp v184, v122, v130 row_shl:15 row_mask:0xf bank_mask:0xf
	v_fmac_f32_dpp v185, v123, v131 row_shl:15 row_mask:0xf bank_mask:0xf
	v_fmac_f32_dpp v182, v124, v132 row_shl:15 row_mask:0xf bank_mask:0xf
	v_fmac_f32_dpp v183, v125, v133 row_shl:15 row_mask:0xf bank_mask:0xf
	v_fmac_f32_dpp v184, v106, v134 row_shl:1 row_mask:0xf bank_mask:0xf
	v_fmac_f32_dpp v185, v107, v135 row_shl:1 row_mask:0xf bank_mask:0xf
	v_fmac_f32_dpp v182, v108, v136 row_shl:1 row_mask:0xf bank_mask:0xf
	v_fmac_f32_dpp v183, v109, v137 row_shl:1 row_mask:0xf bank_mask:0xf
	v_fmac_f32_dpp v184, v90, v134 row_shr:15 row_mask:0xf bank_mask:0xf
	v_fmac_f32_dpp v185, v91, v135 row_shr:15 row_mask:0xf bank_mask:0xf
	v_fmac_f32_dpp v182, v92, v136 row_shr:15 row_mask:0xf bank_mask:0xf
	v_fmac_f32_dpp v183, v93, v137 row_shr:15 row_mask:0xf bank_mask:0xf
	v_fmac_f32_dpp v184, v106, v142 row_shl:2 row_mask:0xf bank_mask:0xf
	v_fmac_f32_dpp v185, v107, v143 row_shl:2 row_mask:0xf bank_mask:0xf
	v_fmac_f32_dpp v182, v108, v144 row_shl:2 row_mask:0xf bank_mask:0xf
	v_fmac_f32_dpp v183, v109, v145 row_shl:2 row_mask:0xf bank_mask:0xf
	v_fmac_f32_dpp v184, v90, v142 row_shr:14 row_mask:0xf bank_mask:0xf
	v_fmac_f32_dpp v185, v91, v143 row_shr:14 row_mask:0xf bank_mask:0xf
	v_fmac_f32_dpp v182, v92, v144 row_shr:14 row_mask:0xf bank_mask:0xf
	v_fmac_f32_dpp v183, v93, v145 row_shr:14 row_mask:0xf bank_mask:0xf
	s_nop 0
	v_cvt_pk_bf16_f32 v178, v178, v179
	v_cvt_pk_bf16_f32 v179, v180, v181
	v_cvt_pk_bf16_f32 v180, v184, v185
	v_cvt_pk_bf16_f32 v181, v182, v183
	v_add_u32_e32 v182, 4, v219
	v_lshrrev_b32_e32 v184, 3, v182
	v_ashrrev_i32_e32 v183, 2, v182
	v_and_or_b32 v184, v184, 14, v225
	v_lshlrev_b32_e32 v185, 6, v182
	v_lshlrev_b32_e32 v182, 2, v182
	v_and_b32_e32 v214, 0xffffffe0, v183
	v_and_or_b32 v185, v185, s96, v228
	v_lshlrev_b32_e32 v184, 10, v184
	v_and_b32_e32 v182, 32, v182
	v_add_u32_e32 v183, v229, v214
	v_bitop3_b32 v215, v185, v184, v182 bitop3:0xde
	v_lshl_or_b32 v182, v183, 14, v215
	global_store_dwordx4 v182, v[178:181], s[36:37] sc1
	v_pk_fma_f32 v[182:183], v[92:93], v[152:153], v[140:141]
	v_pk_fma_f32 v[184:185], v[90:91], v[150:151], v[138:139]
	v_pk_fma_f32 v[180:181], v[96:97], v[168:169], v[160:161]
	v_pk_fma_f32 v[178:179], v[94:95], v[166:167], v[158:159]
	s_nop 0
	s_nop 1
	v_fmac_f32_dpp v178, v94, v146 row_shr:1 row_mask:0xf bank_mask:0xf
	v_fmac_f32_dpp v179, v95, v147 row_shr:1 row_mask:0xf bank_mask:0xf
	v_fmac_f32_dpp v180, v96, v148 row_shr:1 row_mask:0xf bank_mask:0xf
	v_fmac_f32_dpp v181, v97, v149 row_shr:1 row_mask:0xf bank_mask:0xf
	v_fmac_f32_dpp v178, v110, v146 row_shl:15 row_mask:0xf bank_mask:0xf
	v_fmac_f32_dpp v179, v111, v147 row_shl:15 row_mask:0xf bank_mask:0xf
	v_fmac_f32_dpp v180, v112, v148 row_shl:15 row_mask:0xf bank_mask:0xf
	v_fmac_f32_dpp v181, v113, v149 row_shl:15 row_mask:0xf bank_mask:0xf
	v_fmac_f32_dpp v178, v94, v154 row_shl:1 row_mask:0xf bank_mask:0xf
	v_fmac_f32_dpp v179, v95, v155 row_shl:1 row_mask:0xf bank_mask:0xf
	v_fmac_f32_dpp v180, v96, v156 row_shl:1 row_mask:0xf bank_mask:0xf
	v_fmac_f32_dpp v181, v97, v157 row_shl:1 row_mask:0xf bank_mask:0xf
	v_fmac_f32_dpp v178, v78, v154 row_shr:15 row_mask:0xf bank_mask:0xf
	v_fmac_f32_dpp v179, v79, v155 row_shr:15 row_mask:0xf bank_mask:0xf
	v_fmac_f32_dpp v180, v80, v156 row_shr:15 row_mask:0xf bank_mask:0xf
	v_fmac_f32_dpp v181, v81, v157 row_shr:15 row_mask:0xf bank_mask:0xf
	v_fmac_f32_dpp v178, v94, v162 row_shl:2 row_mask:0xf bank_mask:0xf
	v_fmac_f32_dpp v179, v95, v163 row_shl:2 row_mask:0xf bank_mask:0xf
	v_fmac_f32_dpp v180, v96, v164 row_shl:2 row_mask:0xf bank_mask:0xf
	v_fmac_f32_dpp v181, v97, v165 row_shl:2 row_mask:0xf bank_mask:0xf
	v_fmac_f32_dpp v178, v78, v162 row_shr:14 row_mask:0xf bank_mask:0xf
	v_fmac_f32_dpp v179, v79, v163 row_shr:14 row_mask:0xf bank_mask:0xf
	v_fmac_f32_dpp v180, v80, v164 row_shr:14 row_mask:0xf bank_mask:0xf
	v_fmac_f32_dpp v181, v81, v165 row_shr:14 row_mask:0xf bank_mask:0xf
	s_nop 1
	v_fmac_f32_dpp v184, v90, v130 row_shr:1 row_mask:0xf bank_mask:0xf
	v_fmac_f32_dpp v185, v91, v131 row_shr:1 row_mask:0xf bank_mask:0xf
	v_fmac_f32_dpp v182, v92, v132 row_shr:1 row_mask:0xf bank_mask:0xf
	v_fmac_f32_dpp v183, v93, v133 row_shr:1 row_mask:0xf bank_mask:0xf
	v_fmac_f32_dpp v184, v106, v130 row_shl:15 row_mask:0xf bank_mask:0xf
	v_fmac_f32_dpp v185, v107, v131 row_shl:15 row_mask:0xf bank_mask:0xf
	v_fmac_f32_dpp v182, v108, v132 row_shl:15 row_mask:0xf bank_mask:0xf
	v_fmac_f32_dpp v183, v109, v133 row_shl:15 row_mask:0xf bank_mask:0xf
	v_fmac_f32_dpp v184, v90, v134 row_shl:1 row_mask:0xf bank_mask:0xf
	v_fmac_f32_dpp v185, v91, v135 row_shl:1 row_mask:0xf bank_mask:0xf
	v_fmac_f32_dpp v182, v92, v136 row_shl:1 row_mask:0xf bank_mask:0xf
	v_fmac_f32_dpp v183, v93, v137 row_shl:1 row_mask:0xf bank_mask:0xf
	v_fmac_f32_dpp v184, v74, v134 row_shr:15 row_mask:0xf bank_mask:0xf
	v_fmac_f32_dpp v185, v75, v135 row_shr:15 row_mask:0xf bank_mask:0xf
	v_fmac_f32_dpp v182, v76, v136 row_shr:15 row_mask:0xf bank_mask:0xf
	v_fmac_f32_dpp v183, v77, v137 row_shr:15 row_mask:0xf bank_mask:0xf
	v_fmac_f32_dpp v184, v90, v142 row_shl:2 row_mask:0xf bank_mask:0xf
	v_fmac_f32_dpp v185, v91, v143 row_shl:2 row_mask:0xf bank_mask:0xf
	v_fmac_f32_dpp v182, v92, v144 row_shl:2 row_mask:0xf bank_mask:0xf
	v_fmac_f32_dpp v183, v93, v145 row_shl:2 row_mask:0xf bank_mask:0xf
	v_fmac_f32_dpp v184, v74, v142 row_shr:14 row_mask:0xf bank_mask:0xf
	v_fmac_f32_dpp v185, v75, v143 row_shr:14 row_mask:0xf bank_mask:0xf
	v_fmac_f32_dpp v182, v76, v144 row_shr:14 row_mask:0xf bank_mask:0xf
	v_fmac_f32_dpp v183, v77, v145 row_shr:14 row_mask:0xf bank_mask:0xf
	s_nop 0
	v_cvt_pk_bf16_f32 v178, v178, v179
	v_cvt_pk_bf16_f32 v179, v180, v181
	v_cvt_pk_bf16_f32 v180, v184, v185
	v_cvt_pk_bf16_f32 v181, v182, v183
	v_add_u32_e32 v182, 8, v219
	v_lshrrev_b32_e32 v184, 3, v182
	v_ashrrev_i32_e32 v183, 2, v182
	v_and_or_b32 v184, v184, 14, v225
	v_lshlrev_b32_e32 v185, 6, v182
	v_lshlrev_b32_e32 v182, 2, v182
	v_and_b32_e32 v216, 0xffffffe0, v183
	v_and_or_b32 v185, v185, s96, v228
	v_lshlrev_b32_e32 v184, 10, v184
	v_and_b32_e32 v182, 32, v182
	v_add_u32_e32 v183, v229, v216
	v_bitop3_b32 v217, v185, v184, v182 bitop3:0xde
	v_lshl_or_b32 v182, v183, 14, v217
	global_store_dwordx4 v182, v[178:181], s[36:37] sc1
	v_pk_fma_f32 v[182:183], v[74:75], v[150:151], v[138:139]
	s_nop 0
	v_pk_fma_f32 v[178:179], v[80:81], v[168:169], v[160:161]
	v_pk_fma_f32 v[180:181], v[78:79], v[166:167], v[158:159]
	s_nop 0
	s_nop 1
	v_fmac_f32_dpp v180, v78, v146 row_shr:1 row_mask:0xf bank_mask:0xf
	v_fmac_f32_dpp v181, v79, v147 row_shr:1 row_mask:0xf bank_mask:0xf
	v_fmac_f32_dpp v178, v80, v148 row_shr:1 row_mask:0xf bank_mask:0xf
	v_fmac_f32_dpp v179, v81, v149 row_shr:1 row_mask:0xf bank_mask:0xf
	v_fmac_f32_dpp v180, v94, v146 row_shl:15 row_mask:0xf bank_mask:0xf
	v_fmac_f32_dpp v181, v95, v147 row_shl:15 row_mask:0xf bank_mask:0xf
	v_fmac_f32_dpp v178, v96, v148 row_shl:15 row_mask:0xf bank_mask:0xf
	v_fmac_f32_dpp v179, v97, v149 row_shl:15 row_mask:0xf bank_mask:0xf
	v_fmac_f32_dpp v180, v78, v154 row_shl:1 row_mask:0xf bank_mask:0xf
	v_fmac_f32_dpp v181, v79, v155 row_shl:1 row_mask:0xf bank_mask:0xf
	v_fmac_f32_dpp v178, v80, v156 row_shl:1 row_mask:0xf bank_mask:0xf
	v_fmac_f32_dpp v179, v81, v157 row_shl:1 row_mask:0xf bank_mask:0xf
	v_fmac_f32_dpp v180, v170, v154 row_shr:15 row_mask:0xf bank_mask:0xf
	v_fmac_f32_dpp v181, v171, v155 row_shr:15 row_mask:0xf bank_mask:0xf
	v_fmac_f32_dpp v178, v172, v156 row_shr:15 row_mask:0xf bank_mask:0xf
	v_fmac_f32_dpp v179, v173, v157 row_shr:15 row_mask:0xf bank_mask:0xf
	v_fmac_f32_dpp v180, v78, v162 row_shl:2 row_mask:0xf bank_mask:0xf
	v_fmac_f32_dpp v181, v79, v163 row_shl:2 row_mask:0xf bank_mask:0xf
	v_fmac_f32_dpp v178, v80, v164 row_shl:2 row_mask:0xf bank_mask:0xf
	v_fmac_f32_dpp v179, v81, v165 row_shl:2 row_mask:0xf bank_mask:0xf
	v_fmac_f32_dpp v180, v170, v162 row_shr:14 row_mask:0xf bank_mask:0xf
	v_fmac_f32_dpp v181, v171, v163 row_shr:14 row_mask:0xf bank_mask:0xf
	v_fmac_f32_dpp v178, v172, v164 row_shr:14 row_mask:0xf bank_mask:0xf
	v_fmac_f32_dpp v179, v173, v165 row_shr:14 row_mask:0xf bank_mask:0xf
	v_pk_fma_f32 v[172:173], v[76:77], v[152:153], v[140:141]
	s_nop 0
	v_mov_b32_e32 v184, v172
	s_nop 1
	v_fmac_f32_dpp v182, v74, v130 row_shr:1 row_mask:0xf bank_mask:0xf
	v_fmac_f32_dpp v183, v75, v131 row_shr:1 row_mask:0xf bank_mask:0xf
	v_fmac_f32_dpp v184, v76, v132 row_shr:1 row_mask:0xf bank_mask:0xf
	v_fmac_f32_dpp v173, v77, v133 row_shr:1 row_mask:0xf bank_mask:0xf
	v_fmac_f32_dpp v182, v90, v130 row_shl:15 row_mask:0xf bank_mask:0xf
	v_fmac_f32_dpp v183, v91, v131 row_shl:15 row_mask:0xf bank_mask:0xf
	v_fmac_f32_dpp v184, v92, v132 row_shl:15 row_mask:0xf bank_mask:0xf
	v_fmac_f32_dpp v173, v93, v133 row_shl:15 row_mask:0xf bank_mask:0xf
	v_fmac_f32_dpp v182, v74, v134 row_shl:1 row_mask:0xf bank_mask:0xf
	v_fmac_f32_dpp v183, v75, v135 row_shl:1 row_mask:0xf bank_mask:0xf
	v_fmac_f32_dpp v184, v76, v136 row_shl:1 row_mask:0xf bank_mask:0xf
	v_fmac_f32_dpp v173, v77, v137 row_shl:1 row_mask:0xf bank_mask:0xf
	v_fmac_f32_dpp v182, v174, v134 row_shr:15 row_mask:0xf bank_mask:0xf
	v_fmac_f32_dpp v183, v175, v135 row_shr:15 row_mask:0xf bank_mask:0xf
	v_fmac_f32_dpp v184, v176, v136 row_shr:15 row_mask:0xf bank_mask:0xf
	v_fmac_f32_dpp v173, v177, v137 row_shr:15 row_mask:0xf bank_mask:0xf
	v_fmac_f32_dpp v182, v74, v142 row_shl:2 row_mask:0xf bank_mask:0xf
	v_fmac_f32_dpp v183, v75, v143 row_shl:2 row_mask:0xf bank_mask:0xf
	v_fmac_f32_dpp v184, v76, v144 row_shl:2 row_mask:0xf bank_mask:0xf
	v_fmac_f32_dpp v173, v77, v145 row_shl:2 row_mask:0xf bank_mask:0xf
	v_fmac_f32_dpp v182, v174, v142 row_shr:14 row_mask:0xf bank_mask:0xf
	v_fmac_f32_dpp v183, v175, v143 row_shr:14 row_mask:0xf bank_mask:0xf
	v_fmac_f32_dpp v184, v176, v144 row_shr:14 row_mask:0xf bank_mask:0xf
	v_fmac_f32_dpp v173, v177, v145 row_shr:14 row_mask:0xf bank_mask:0xf
	v_add_u32_e32 v174, 12, v219
	v_lshrrev_b32_e32 v176, 3, v174
	v_ashrrev_i32_e32 v175, 2, v174
	v_and_or_b32 v176, v176, 14, v225
	v_lshlrev_b32_e32 v177, 6, v174
	v_lshlrev_b32_e32 v174, 2, v174
	v_and_b32_e32 v218, 0xffffffe0, v175
	v_and_or_b32 v177, v177, s96, v228
	v_lshlrev_b32_e32 v176, 10, v176
	v_and_b32_e32 v174, 32, v174
	v_add_u32_e32 v175, v229, v218
	v_bitop3_b32 v222, v177, v176, v174 bitop3:0xde
	v_cvt_pk_bf16_f32 v170, v180, v181
	v_cvt_pk_bf16_f32 v171, v178, v179
	v_lshl_or_b32 v174, v175, 14, v222
	v_cvt_pk_bf16_f32 v172, v182, v183
	v_cvt_pk_bf16_f32 v173, v184, v173
	global_store_dwordx4 v174, v[170:173], s[36:37] sc1
	v_mov_b32_e32 v174, 0
	v_mov_b32_e32 v175, 0
	v_add_u32_e32 v171, s68, v213
	ds_read_b128 v[182:185], v171
	v_add_lshl_u32 v170, v220, s22, 10
	v_cndmask_b32_e64 v172, 0, 1, s[48:49]
	v_add3_u32 v213, s35, v170, v213
	v_mov_b32_e32 v170, 0
	v_cmp_ne_u32_e64 s[10:11], 1, v172
	v_mov_b32_e32 v176, 0
	v_mov_b32_e32 v177, 0
	s_cbranch_vccnz .LBB0_761
	ds_read_b128 v[174:177], v213

.LBB0_763:
	v_pk_fma_f32 v[226:227], v[64:65], v[168:169], v[160:161]
	v_pk_fma_f32 v[230:231], v[62:63], v[166:167], v[158:159]
	v_mov_b32_e32 v224, v227
	v_mov_b32_e32 v220, v231
	s_waitcnt lgkmcnt(1)
	s_nop 1
	v_fmac_f32_dpp v230, v62, v146 row_shr:1 row_mask:0xf bank_mask:0xf
	v_fmac_f32_dpp v220, v63, v147 row_shr:1 row_mask:0xf bank_mask:0xf
	v_fmac_f32_dpp v226, v64, v148 row_shr:1 row_mask:0xf bank_mask:0xf
	v_fmac_f32_dpp v224, v65, v149 row_shr:1 row_mask:0xf bank_mask:0xf
	v_fmac_f32_dpp v230, v182, v146 row_shl:15 row_mask:0xf bank_mask:0xf
	v_fmac_f32_dpp v220, v183, v147 row_shl:15 row_mask:0xf bank_mask:0xf
	v_fmac_f32_dpp v226, v184, v148 row_shl:15 row_mask:0xf bank_mask:0xf
	v_fmac_f32_dpp v224, v185, v149 row_shl:15 row_mask:0xf bank_mask:0xf
	v_fmac_f32_dpp v230, v62, v154 row_shl:1 row_mask:0xf bank_mask:0xf
	v_fmac_f32_dpp v220, v63, v155 row_shl:1 row_mask:0xf bank_mask:0xf
	v_fmac_f32_dpp v226, v64, v156 row_shl:1 row_mask:0xf bank_mask:0xf
	v_fmac_f32_dpp v224, v65, v157 row_shl:1 row_mask:0xf bank_mask:0xf
	v_fmac_f32_dpp v230, v46, v154 row_shr:15 row_mask:0xf bank_mask:0xf
	v_fmac_f32_dpp v220, v47, v155 row_shr:15 row_mask:0xf bank_mask:0xf
	v_fmac_f32_dpp v226, v48, v156 row_shr:15 row_mask:0xf bank_mask:0xf
	v_fmac_f32_dpp v224, v49, v157 row_shr:15 row_mask:0xf bank_mask:0xf
	v_fmac_f32_dpp v230, v62, v162 row_shl:2 row_mask:0xf bank_mask:0xf
	v_fmac_f32_dpp v220, v63, v163 row_shl:2 row_mask:0xf bank_mask:0xf
	v_fmac_f32_dpp v226, v64, v164 row_shl:2 row_mask:0xf bank_mask:0xf
	v_fmac_f32_dpp v224, v65, v165 row_shl:2 row_mask:0xf bank_mask:0xf
	v_fmac_f32_dpp v230, v46, v162 row_shr:14 row_mask:0xf bank_mask:0xf
	v_fmac_f32_dpp v220, v47, v163 row_shr:14 row_mask:0xf bank_mask:0xf
	v_fmac_f32_dpp v226, v48, v164 row_shr:14 row_mask:0xf bank_mask:0xf
	v_fmac_f32_dpp v224, v49, v165 row_shr:14 row_mask:0xf bank_mask:0xf
	v_pk_fma_f32 v[182:183], v[60:61], v[152:153], v[140:141]
	v_pk_fma_f32 v[184:185], v[58:59], v[150:151], v[138:139]
	v_add_u32_e32 v223, 0x80, v219
	s_waitcnt lgkmcnt(0)
	s_nop 1
	v_fmac_f32_dpp v184, v58, v130 row_shr:1 row_mask:0xf bank_mask:0xf
	v_fmac_f32_dpp v185, v59, v131 row_shr:1 row_mask:0xf bank_mask:0xf
	v_fmac_f32_dpp v182, v60, v132 row_shr:1 row_mask:0xf bank_mask:0xf
	v_fmac_f32_dpp v183, v61, v133 row_shr:1 row_mask:0xf bank_mask:0xf
	v_fmac_f32_dpp v184, v178, v130 row_shl:15 row_mask:0xf bank_mask:0xf
	v_fmac_f32_dpp v185, v179, v131 row_shl:15 row_mask:0xf bank_mask:0xf
	v_fmac_f32_dpp v182, v180, v132 row_shl:15 row_mask:0xf bank_mask:0xf
	v_fmac_f32_dpp v183, v181, v133 row_shl:15 row_mask:0xf bank_mask:0xf
	v_fmac_f32_dpp v184, v58, v134 row_shl:1 row_mask:0xf bank_mask:0xf
	v_fmac_f32_dpp v185, v59, v135 row_shl:1 row_mask:0xf bank_mask:0xf
	v_fmac_f32_dpp v182, v60, v136 row_shl:1 row_mask:0xf bank_mask:0xf
	v_fmac_f32_dpp v183, v61, v137 row_shl:1 row_mask:0xf bank_mask:0xf
	v_fmac_f32_dpp v184, v42, v134 row_shr:15 row_mask:0xf bank_mask:0xf
	v_fmac_f32_dpp v185, v43, v135 row_shr:15 row_mask:0xf bank_mask:0xf
	v_fmac_f32_dpp v182, v44, v136 row_shr:15 row_mask:0xf bank_mask:0xf
	v_fmac_f32_dpp v183, v45, v137 row_shr:15 row_mask:0xf bank_mask:0xf
	v_fmac_f32_dpp v184, v58, v142 row_shl:2 row_mask:0xf bank_mask:0xf
	v_fmac_f32_dpp v185, v59, v143 row_shl:2 row_mask:0xf bank_mask:0xf
	v_fmac_f32_dpp v182, v60, v144 row_shl:2 row_mask:0xf bank_mask:0xf
	v_fmac_f32_dpp v183, v61, v145 row_shl:2 row_mask:0xf bank_mask:0xf
	v_fmac_f32_dpp v184, v42, v142 row_shr:14 row_mask:0xf bank_mask:0xf
	v_fmac_f32_dpp v185, v43, v143 row_shr:14 row_mask:0xf bank_mask:0xf
	v_fmac_f32_dpp v182, v44, v144 row_shr:14 row_mask:0xf bank_mask:0xf
	v_fmac_f32_dpp v183, v45, v145 row_shr:14 row_mask:0xf bank_mask:0xf
	v_cvt_pk_bf16_f32 v178, v230, v220
	v_cvt_pk_bf16_f32 v179, v226, v224
	s_mov_b64 s[2:3], 0x2200
	v_cvt_pk_bf16_f32 v180, v184, v185
	v_cvt_pk_bf16_f32 v181, v182, v183
	v_ashrrev_i32_e32 v182, 2, v223
	v_lshlrev_b32_e32 v183, 6, v223
	v_lshlrev_b32_e32 v184, 2, v223
	v_and_b32_e32 v220, 0xffffffe0, v182
	v_and_or_b32 v183, v183, s96, v228
	v_and_b32_e32 v184, 32, v184
	v_add_u32_e32 v182, v229, v220
	v_bitop3_b32 v224, v183, v221, v184 bitop3:0xde
	v_lshl_or_b32 v182, v182, 14, v224
	global_store_dwordx4 v182, v[178:181], s[36:37] sc1
	v_pk_fma_f32 v[182:183], v[44:45], v[152:153], v[140:141]
	v_pk_fma_f32 v[184:185], v[42:43], v[150:151], v[138:139]
	v_pk_fma_f32 v[180:181], v[48:49], v[168:169], v[160:161]
	v_pk_fma_f32 v[178:179], v[46:47], v[166:167], v[158:159]
	s_nop 0
	s_nop 1
	v_fmac_f32_dpp v178, v46, v146 row_shr:1 row_mask:0xf bank_mask:0xf
	v_fmac_f32_dpp v179, v47, v147 row_shr:1 row_mask:0xf bank_mask:0xf
	v_fmac_f32_dpp v180, v48, v148 row_shr:1 row_mask:0xf bank_mask:0xf
	v_fmac_f32_dpp v181, v49, v149 row_shr:1 row_mask:0xf bank_mask:0xf
	v_fmac_f32_dpp v178, v62, v146 row_shl:15 row_mask:0xf bank_mask:0xf
	v_fmac_f32_dpp v179, v63, v147 row_shl:15 row_mask:0xf bank_mask:0xf
	v_fmac_f32_dpp v180, v64, v148 row_shl:15 row_mask:0xf bank_mask:0xf
	v_fmac_f32_dpp v181, v65, v149 row_shl:15 row_mask:0xf bank_mask:0xf
	v_fmac_f32_dpp v178, v46, v154 row_shl:1 row_mask:0xf bank_mask:0xf
	v_fmac_f32_dpp v179, v47, v155 row_shl:1 row_mask:0xf bank_mask:0xf
	v_fmac_f32_dpp v180, v48, v156 row_shl:1 row_mask:0xf bank_mask:0xf
	v_fmac_f32_dpp v181, v49, v157 row_shl:1 row_mask:0xf bank_mask:0xf
	v_fmac_f32_dpp v178, v30, v154 row_shr:15 row_mask:0xf bank_mask:0xf
	v_fmac_f32_dpp v179, v31, v155 row_shr:15 row_mask:0xf bank_mask:0xf
	v_fmac_f32_dpp v180, v32, v156 row_shr:15 row_mask:0xf bank_mask:0xf
	v_fmac_f32_dpp v181, v33, v157 row_shr:15 row_mask:0xf bank_mask:0xf
	v_fmac_f32_dpp v178, v46, v162 row_shl:2 row_mask:0xf bank_mask:0xf
	v_fmac_f32_dpp v179, v47, v163 row_shl:2 row_mask:0xf bank_mask:0xf
	v_fmac_f32_dpp v180, v48, v164 row_shl:2 row_mask:0xf bank_mask:0xf
	v_fmac_f32_dpp v181, v49, v165 row_shl:2 row_mask:0xf bank_mask:0xf
	v_fmac_f32_dpp v178, v30, v162 row_shr:14 row_mask:0xf bank_mask:0xf
	v_fmac_f32_dpp v179, v31, v163 row_shr:14 row_mask:0xf bank_mask:0xf
	v_fmac_f32_dpp v180, v32, v164 row_shr:14 row_mask:0xf bank_mask:0xf
	v_fmac_f32_dpp v181, v33, v165 row_shr:14 row_mask:0xf bank_mask:0xf
	s_nop 1
	v_fmac_f32_dpp v184, v42, v130 row_shr:1 row_mask:0xf bank_mask:0xf
	v_fmac_f32_dpp v185, v43, v131 row_shr:1 row_mask:0xf bank_mask:0xf
	v_fmac_f32_dpp v182, v44, v132 row_shr:1 row_mask:0xf bank_mask:0xf
	v_fmac_f32_dpp v183, v45, v133 row_shr:1 row_mask:0xf bank_mask:0xf
	v_fmac_f32_dpp v184, v58, v130 row_shl:15 row_mask:0xf bank_mask:0xf
	v_fmac_f32_dpp v185, v59, v131 row_shl:15 row_mask:0xf bank_mask:0xf
	v_fmac_f32_dpp v182, v60, v132 row_shl:15 row_mask:0xf bank_mask:0xf
	v_fmac_f32_dpp v183, v61, v133 row_shl:15 row_mask:0xf bank_mask:0xf
	v_fmac_f32_dpp v184, v42, v134 row_shl:1 row_mask:0xf bank_mask:0xf
	v_fmac_f32_dpp v185, v43, v135 row_shl:1 row_mask:0xf bank_mask:0xf
	v_fmac_f32_dpp v182, v44, v136 row_shl:1 row_mask:0xf bank_mask:0xf
	v_fmac_f32_dpp v183, v45, v137 row_shl:1 row_mask:0xf bank_mask:0xf
	v_fmac_f32_dpp v184, v26, v134 row_shr:15 row_mask:0xf bank_mask:0xf
	v_fmac_f32_dpp v185, v27, v135 row_shr:15 row_mask:0xf bank_mask:0xf
	v_fmac_f32_dpp v182, v28, v136 row_shr:15 row_mask:0xf bank_mask:0xf
	v_fmac_f32_dpp v183, v29, v137 row_shr:15 row_mask:0xf bank_mask:0xf
	v_fmac_f32_dpp v184, v42, v142 row_shl:2 row_mask:0xf bank_mask:0xf
	v_fmac_f32_dpp v185, v43, v143 row_shl:2 row_mask:0xf bank_mask:0xf
	v_fmac_f32_dpp v182, v44, v144 row_shl:2 row_mask:0xf bank_mask:0xf
	v_fmac_f32_dpp v183, v45, v145 row_shl:2 row_mask:0xf bank_mask:0xf
	v_fmac_f32_dpp v184, v26, v142 row_shr:14 row_mask:0xf bank_mask:0xf
	v_fmac_f32_dpp v185, v27, v143 row_shr:14 row_mask:0xf bank_mask:0xf
	v_fmac_f32_dpp v182, v28, v144 row_shr:14 row_mask:0xf bank_mask:0xf
	v_fmac_f32_dpp v183, v29, v145 row_shr:14 row_mask:0xf bank_mask:0xf
	s_nop 0
	v_cvt_pk_bf16_f32 v178, v178, v179
	v_cvt_pk_bf16_f32 v179, v180, v181
	v_cvt_pk_bf16_f32 v180, v184, v185
	v_cvt_pk_bf16_f32 v181, v182, v183
	v_add_u32_e32 v182, 0x84, v219
	v_lshrrev_b32_e32 v184, 3, v182
	v_ashrrev_i32_e32 v183, 2, v182
	v_and_or_b32 v184, v184, 14, v225
	v_lshlrev_b32_e32 v185, 6, v182
	v_lshlrev_b32_e32 v182, 2, v182
	v_and_b32_e32 v221, 0xffffffe0, v183
	v_and_or_b32 v185, v185, s96, v228
	v_lshlrev_b32_e32 v184, 10, v184
	v_and_b32_e32 v182, 32, v182
	v_add_u32_e32 v183, v229, v221
	v_bitop3_b32 v226, v185, v184, v182 bitop3:0xde
	v_lshl_or_b32 v182, v183, 14, v226
	global_store_dwordx4 v182, v[178:181], s[36:37] sc1
	v_pk_fma_f32 v[182:183], v[28:29], v[152:153], v[140:141]
	v_pk_fma_f32 v[184:185], v[26:27], v[150:151], v[138:139]
	v_pk_fma_f32 v[180:181], v[32:33], v[168:169], v[160:161]
	v_pk_fma_f32 v[178:179], v[30:31], v[166:167], v[158:159]
	v_pk_fma_f32 v[160:161], v[16:17], v[168:169], v[160:161]
	s_nop 1
	v_fmac_f32_dpp v178, v30, v146 row_shr:1 row_mask:0xf bank_mask:0xf
	v_fmac_f32_dpp v179, v31, v147 row_shr:1 row_mask:0xf bank_mask:0xf
	v_fmac_f32_dpp v180, v32, v148 row_shr:1 row_mask:0xf bank_mask:0xf
	v_fmac_f32_dpp v181, v33, v149 row_shr:1 row_mask:0xf bank_mask:0xf
	v_fmac_f32_dpp v178, v46, v146 row_shl:15 row_mask:0xf bank_mask:0xf
	v_fmac_f32_dpp v179, v47, v147 row_shl:15 row_mask:0xf bank_mask:0xf
	v_fmac_f32_dpp v180, v48, v148 row_shl:15 row_mask:0xf bank_mask:0xf
	v_fmac_f32_dpp v181, v49, v149 row_shl:15 row_mask:0xf bank_mask:0xf
	v_fmac_f32_dpp v178, v30, v154 row_shl:1 row_mask:0xf bank_mask:0xf
	v_fmac_f32_dpp v179, v31, v155 row_shl:1 row_mask:0xf bank_mask:0xf
	v_fmac_f32_dpp v180, v32, v156 row_shl:1 row_mask:0xf bank_mask:0xf
	v_fmac_f32_dpp v181, v33, v157 row_shl:1 row_mask:0xf bank_mask:0xf
	v_fmac_f32_dpp v178, v14, v154 row_shr:15 row_mask:0xf bank_mask:0xf
	v_fmac_f32_dpp v179, v15, v155 row_shr:15 row_mask:0xf bank_mask:0xf
	v_fmac_f32_dpp v180, v16, v156 row_shr:15 row_mask:0xf bank_mask:0xf
	v_fmac_f32_dpp v181, v17, v157 row_shr:15 row_mask:0xf bank_mask:0xf
	v_fmac_f32_dpp v178, v30, v162 row_shl:2 row_mask:0xf bank_mask:0xf
	v_fmac_f32_dpp v179, v31, v163 row_shl:2 row_mask:0xf bank_mask:0xf
	v_fmac_f32_dpp v180, v32, v164 row_shl:2 row_mask:0xf bank_mask:0xf
	v_fmac_f32_dpp v181, v33, v165 row_shl:2 row_mask:0xf bank_mask:0xf
	v_fmac_f32_dpp v178, v14, v162 row_shr:14 row_mask:0xf bank_mask:0xf
	v_fmac_f32_dpp v179, v15, v163 row_shr:14 row_mask:0xf bank_mask:0xf
	v_fmac_f32_dpp v180, v16, v164 row_shr:14 row_mask:0xf bank_mask:0xf
	v_fmac_f32_dpp v181, v17, v165 row_shr:14 row_mask:0xf bank_mask:0xf
	s_nop 1
	v_fmac_f32_dpp v184, v26, v130 row_shr:1 row_mask:0xf bank_mask:0xf
	v_fmac_f32_dpp v185, v27, v131 row_shr:1 row_mask:0xf bank_mask:0xf
	v_fmac_f32_dpp v182, v28, v132 row_shr:1 row_mask:0xf bank_mask:0xf
	v_fmac_f32_dpp v183, v29, v133 row_shr:1 row_mask:0xf bank_mask:0xf
	v_fmac_f32_dpp v184, v42, v130 row_shl:15 row_mask:0xf bank_mask:0xf
	v_fmac_f32_dpp v185, v43, v131 row_shl:15 row_mask:0xf bank_mask:0xf
	v_fmac_f32_dpp v182, v44, v132 row_shl:15 row_mask:0xf bank_mask:0xf
	v_fmac_f32_dpp v183, v45, v133 row_shl:15 row_mask:0xf bank_mask:0xf
	v_fmac_f32_dpp v184, v26, v134 row_shl:1 row_mask:0xf bank_mask:0xf
	v_fmac_f32_dpp v185, v27, v135 row_shl:1 row_mask:0xf bank_mask:0xf
	v_fmac_f32_dpp v182, v28, v136 row_shl:1 row_mask:0xf bank_mask:0xf
	v_fmac_f32_dpp v183, v29, v137 row_shl:1 row_mask:0xf bank_mask:0xf
	v_fmac_f32_dpp v184, v10, v134 row_shr:15 row_mask:0xf bank_mask:0xf
	v_fmac_f32_dpp v185, v11, v135 row_shr:15 row_mask:0xf bank_mask:0xf
	v_fmac_f32_dpp v182, v12, v136 row_shr:15 row_mask:0xf bank_mask:0xf
	v_fmac_f32_dpp v183, v13, v137 row_shr:15 row_mask:0xf bank_mask:0xf
	v_fmac_f32_dpp v184, v26, v142 row_shl:2 row_mask:0xf bank_mask:0xf
	v_fmac_f32_dpp v185, v27, v143 row_shl:2 row_mask:0xf bank_mask:0xf
	v_fmac_f32_dpp v182, v28, v144 row_shl:2 row_mask:0xf bank_mask:0xf
	v_fmac_f32_dpp v183, v29, v145 row_shl:2 row_mask:0xf bank_mask:0xf
	v_fmac_f32_dpp v184, v10, v142 row_shr:14 row_mask:0xf bank_mask:0xf
	v_fmac_f32_dpp v185, v11, v143 row_shr:14 row_mask:0xf bank_mask:0xf
	v_fmac_f32_dpp v182, v12, v144 row_shr:14 row_mask:0xf bank_mask:0xf
	v_fmac_f32_dpp v183, v13, v145 row_shr:14 row_mask:0xf bank_mask:0xf
	v_pk_fma_f32 v[158:159], v[14:15], v[166:167], v[158:159]
	v_cvt_pk_bf16_f32 v178, v178, v179
	v_cvt_pk_bf16_f32 v179, v180, v181
	v_cvt_pk_bf16_f32 v180, v184, v185
	v_cvt_pk_bf16_f32 v181, v182, v183
	v_add_u32_e32 v182, 0x88, v219
	v_lshrrev_b32_e32 v184, 3, v182
	v_ashrrev_i32_e32 v183, 2, v182
	v_and_or_b32 v184, v184, 14, v225
	v_lshlrev_b32_e32 v185, 6, v182
	v_lshlrev_b32_e32 v182, 2, v182
	v_and_b32_e32 v223, 0xffffffe0, v183
	v_and_or_b32 v185, v185, s96, v228
	v_lshlrev_b32_e32 v184, 10, v184
	v_and_b32_e32 v182, 32, v182
	v_add_u32_e32 v183, v229, v223
	v_bitop3_b32 v227, v185, v184, v182 bitop3:0xde
	v_lshl_or_b32 v182, v183, 14, v227
	v_pk_fma_f32 v[140:141], v[12:13], v[152:153], v[140:141]
	v_pk_fma_f32 v[138:139], v[10:11], v[150:151], v[138:139]
	global_store_dwordx4 v182, v[178:181], s[36:37] sc1
	s_nop 1
	v_fmac_f32_dpp v158, v14, v146 row_shr:1 row_mask:0xf bank_mask:0xf
	v_fmac_f32_dpp v159, v15, v147 row_shr:1 row_mask:0xf bank_mask:0xf
	v_fmac_f32_dpp v160, v16, v148 row_shr:1 row_mask:0xf bank_mask:0xf
	v_fmac_f32_dpp v161, v17, v149 row_shr:1 row_mask:0xf bank_mask:0xf
	v_fmac_f32_dpp v158, v30, v146 row_shl:15 row_mask:0xf bank_mask:0xf
	v_fmac_f32_dpp v159, v31, v147 row_shl:15 row_mask:0xf bank_mask:0xf
	v_fmac_f32_dpp v160, v32, v148 row_shl:15 row_mask:0xf bank_mask:0xf
	v_fmac_f32_dpp v161, v33, v149 row_shl:15 row_mask:0xf bank_mask:0xf
	v_fmac_f32_dpp v158, v14, v154 row_shl:1 row_mask:0xf bank_mask:0xf
	v_fmac_f32_dpp v159, v15, v155 row_shl:1 row_mask:0xf bank_mask:0xf
	v_fmac_f32_dpp v160, v16, v156 row_shl:1 row_mask:0xf bank_mask:0xf
	v_fmac_f32_dpp v161, v17, v157 row_shl:1 row_mask:0xf bank_mask:0xf
	v_fmac_f32_dpp v158, v174, v154 row_shr:15 row_mask:0xf bank_mask:0xf
	v_fmac_f32_dpp v159, v175, v155 row_shr:15 row_mask:0xf bank_mask:0xf
	v_fmac_f32_dpp v160, v176, v156 row_shr:15 row_mask:0xf bank_mask:0xf
	v_fmac_f32_dpp v161, v177, v157 row_shr:15 row_mask:0xf bank_mask:0xf
	v_fmac_f32_dpp v158, v14, v162 row_shl:2 row_mask:0xf bank_mask:0xf
	v_fmac_f32_dpp v159, v15, v163 row_shl:2 row_mask:0xf bank_mask:0xf
	v_fmac_f32_dpp v160, v16, v164 row_shl:2 row_mask:0xf bank_mask:0xf
	v_fmac_f32_dpp v161, v17, v165 row_shl:2 row_mask:0xf bank_mask:0xf
	v_fmac_f32_dpp v158, v174, v162 row_shr:14 row_mask:0xf bank_mask:0xf
	v_fmac_f32_dpp v159, v175, v163 row_shr:14 row_mask:0xf bank_mask:0xf
	v_fmac_f32_dpp v160, v176, v164 row_shr:14 row_mask:0xf bank_mask:0xf
	v_fmac_f32_dpp v161, v177, v165 row_shr:14 row_mask:0xf bank_mask:0xf
	s_nop 1
	v_fmac_f32_dpp v138, v10, v130 row_shr:1 row_mask:0xf bank_mask:0xf
	v_fmac_f32_dpp v139, v11, v131 row_shr:1 row_mask:0xf bank_mask:0xf
	v_fmac_f32_dpp v140, v12, v132 row_shr:1 row_mask:0xf bank_mask:0xf
	v_fmac_f32_dpp v141, v13, v133 row_shr:1 row_mask:0xf bank_mask:0xf
	v_fmac_f32_dpp v138, v26, v130 row_shl:15 row_mask:0xf bank_mask:0xf
	v_fmac_f32_dpp v139, v27, v131 row_shl:15 row_mask:0xf bank_mask:0xf
	v_fmac_f32_dpp v140, v28, v132 row_shl:15 row_mask:0xf bank_mask:0xf
	v_fmac_f32_dpp v141, v29, v133 row_shl:15 row_mask:0xf bank_mask:0xf
	v_fmac_f32_dpp v138, v10, v134 row_shl:1 row_mask:0xf bank_mask:0xf
	v_fmac_f32_dpp v139, v11, v135 row_shl:1 row_mask:0xf bank_mask:0xf
	v_fmac_f32_dpp v140, v12, v136 row_shl:1 row_mask:0xf bank_mask:0xf
	v_fmac_f32_dpp v141, v13, v137 row_shl:1 row_mask:0xf bank_mask:0xf
	v_fmac_f32_dpp v138, v170, v134 row_shr:15 row_mask:0xf bank_mask:0xf
	v_fmac_f32_dpp v139, v171, v135 row_shr:15 row_mask:0xf bank_mask:0xf
	v_fmac_f32_dpp v140, v172, v136 row_shr:15 row_mask:0xf bank_mask:0xf
	v_fmac_f32_dpp v141, v173, v137 row_shr:15 row_mask:0xf bank_mask:0xf
	v_fmac_f32_dpp v138, v10, v142 row_shl:2 row_mask:0xf bank_mask:0xf
	v_fmac_f32_dpp v139, v11, v143 row_shl:2 row_mask:0xf bank_mask:0xf
	v_fmac_f32_dpp v140, v12, v144 row_shl:2 row_mask:0xf bank_mask:0xf
	v_fmac_f32_dpp v141, v13, v145 row_shl:2 row_mask:0xf bank_mask:0xf
	v_fmac_f32_dpp v138, v170, v142 row_shr:14 row_mask:0xf bank_mask:0xf
	v_fmac_f32_dpp v139, v171, v143 row_shr:14 row_mask:0xf bank_mask:0xf
	v_fmac_f32_dpp v140, v172, v144 row_shr:14 row_mask:0xf bank_mask:0xf
	v_fmac_f32_dpp v141, v173, v145 row_shr:14 row_mask:0xf bank_mask:0xf
	v_add_u32_e32 v134, 0x8c, v219
	v_lshrrev_b32_e32 v136, 3, v134
	v_ashrrev_i32_e32 v135, 2, v134
	v_and_or_b32 v136, v136, 14, v225
	v_lshlrev_b32_e32 v137, 6, v134
	v_lshlrev_b32_e32 v134, 2, v134
	v_and_b32_e32 v219, 0xffffffe0, v135
	v_and_or_b32 v137, v137, s96, v228
	v_lshlrev_b32_e32 v136, 10, v136
	v_and_b32_e32 v134, 32, v134
	v_add_u32_e32 v135, v229, v219
	v_bitop3_b32 v225, v137, v136, v134 bitop3:0xde
	v_lshl_or_b32 v134, v135, 14, v225
	v_add_co_u32_e32 v136, vcc, 0x4000, v194
	v_cvt_pk_bf16_f32 v130, v158, v159
	v_cvt_pk_bf16_f32 v131, v160, v161
	v_cvt_pk_bf16_f32 v132, v138, v139
	v_cvt_pk_bf16_f32 v133, v140, v141
	global_store_dwordx4 v134, v[130:133], s[36:37] sc1
	v_lshl_add_u64 v[134:135], v[194:195], 0, s[2:3]
	s_mov_b64 s[2:3], 0x4200
	v_addc_co_u32_e32 v137, vcc, 0, v195, vcc
	global_load_dwordx4 v[138:141], v[196:197], off offset:528
	global_load_dwordx4 v[162:165], v[196:197], off offset:512
	global_load_dwordx4 v[130:133], v[194:195], off offset:528
	global_load_dwordx4 v[146:149], v[194:195], off offset:512
	global_load_dwordx4 v[166:169], v[198:199], off offset:512
	global_load_dwordx4 v[150:153], v[134:135], off offset:16
	v_lshl_add_u64 v[134:135], v[194:195], 0, s[2:3]
	s_mov_b64 s[2:3], 0x6200
	v_add_co_u32_e32 v144, vcc, 0x6000, v194
	v_lshl_add_u64 v[142:143], v[194:195], 0, s[2:3]
	s_nop 0
	v_addc_co_u32_e32 v145, vcc, 0, v195, vcc
	global_load_dwordx4 v[154:157], v[136:137], off offset:512
	s_nop 0
	global_load_dwordx4 v[134:137], v[134:135], off offset:16
	s_nop 0
	global_load_dwordx4 v[158:161], v[144:145], off offset:512
	s_nop 0
	global_load_dwordx4 v[142:145], v[142:143], off offset:16
	v_lshl_add_u32 v175, v188, 2, s69
	v_mov_b32_e32 v170, 0
	s_and_b64 vcc, exec, s[6:7]
	v_mov_b32_e32 v178, 0
	v_mov_b32_e32 v179, 0
	v_mov_b32_e32 v180, 0
	v_mov_b32_e32 v181, 0
	s_cbranch_vccnz .LBB0_765
	ds_read_b128 v[178:181], v175

.LBB0_771:
	s_waitcnt vmcnt(5)
	v_pk_fma_f32 v[196:197], v[118:119], v[166:167], v[162:163]
	v_add_u32_e32 v192, 0x80, v192
	v_pk_fma_f32 v[194:195], v[120:121], v[168:169], v[164:165]
	v_mov_b32_e32 v193, v196
	s_waitcnt vmcnt(4)
	v_pk_fma_f32 v[198:199], v[116:117], v[152:153], v[140:141]
	v_ashrrev_i32_e32 v192, 6, v192
	s_waitcnt vmcnt(1) lgkmcnt(0)
	s_nop 1
	v_fmac_f32_dpp v193, v118, v146 row_shr:1 row_mask:0xf bank_mask:0xf
	v_fmac_f32_dpp v197, v119, v147 row_shr:1 row_mask:0xf bank_mask:0xf
	v_fmac_f32_dpp v194, v120, v148 row_shr:1 row_mask:0xf bank_mask:0xf
	v_fmac_f32_dpp v195, v121, v149 row_shr:1 row_mask:0xf bank_mask:0xf
	v_fmac_f32_dpp v193, v178, v146 row_shl:15 row_mask:0xf bank_mask:0xf
	v_fmac_f32_dpp v197, v179, v147 row_shl:15 row_mask:0xf bank_mask:0xf
	v_fmac_f32_dpp v194, v180, v148 row_shl:15 row_mask:0xf bank_mask:0xf
	v_fmac_f32_dpp v195, v181, v149 row_shl:15 row_mask:0xf bank_mask:0xf
	v_fmac_f32_dpp v193, v118, v154 row_shl:1 row_mask:0xf bank_mask:0xf
	v_fmac_f32_dpp v197, v119, v155 row_shl:1 row_mask:0xf bank_mask:0xf
	v_fmac_f32_dpp v194, v120, v156 row_shl:1 row_mask:0xf bank_mask:0xf
	v_fmac_f32_dpp v195, v121, v157 row_shl:1 row_mask:0xf bank_mask:0xf
	v_fmac_f32_dpp v193, v102, v154 row_shr:15 row_mask:0xf bank_mask:0xf
	v_fmac_f32_dpp v197, v103, v155 row_shr:15 row_mask:0xf bank_mask:0xf
	v_fmac_f32_dpp v194, v104, v156 row_shr:15 row_mask:0xf bank_mask:0xf
	v_fmac_f32_dpp v195, v105, v157 row_shr:15 row_mask:0xf bank_mask:0xf
	v_fmac_f32_dpp v193, v118, v158 row_shl:2 row_mask:0xf bank_mask:0xf
	v_fmac_f32_dpp v197, v119, v159 row_shl:2 row_mask:0xf bank_mask:0xf
	v_fmac_f32_dpp v194, v120, v160 row_shl:2 row_mask:0xf bank_mask:0xf
	v_fmac_f32_dpp v195, v121, v161 row_shl:2 row_mask:0xf bank_mask:0xf
	v_fmac_f32_dpp v193, v102, v158 row_shr:14 row_mask:0xf bank_mask:0xf
	v_fmac_f32_dpp v197, v103, v159 row_shr:14 row_mask:0xf bank_mask:0xf
	v_fmac_f32_dpp v194, v104, v160 row_shr:14 row_mask:0xf bank_mask:0xf
	v_fmac_f32_dpp v195, v105, v161 row_shr:14 row_mask:0xf bank_mask:0xf
	v_pk_fma_f32 v[180:181], v[114:115], v[150:151], v[138:139]
	v_mov_b32_e32 v196, v199
	s_waitcnt vmcnt(0)
	s_nop 1
	v_fmac_f32_dpp v180, v114, v130 row_shr:1 row_mask:0xf bank_mask:0xf
	v_fmac_f32_dpp v181, v115, v131 row_shr:1 row_mask:0xf bank_mask:0xf
	v_fmac_f32_dpp v198, v116, v132 row_shr:1 row_mask:0xf bank_mask:0xf
	v_fmac_f32_dpp v196, v117, v133 row_shr:1 row_mask:0xf bank_mask:0xf
	v_fmac_f32_dpp v180, v182, v130 row_shl:15 row_mask:0xf bank_mask:0xf
	v_fmac_f32_dpp v181, v183, v131 row_shl:15 row_mask:0xf bank_mask:0xf
	v_fmac_f32_dpp v198, v184, v132 row_shl:15 row_mask:0xf bank_mask:0xf
	v_fmac_f32_dpp v196, v185, v133 row_shl:15 row_mask:0xf bank_mask:0xf
	v_fmac_f32_dpp v180, v114, v134 row_shl:1 row_mask:0xf bank_mask:0xf
	v_fmac_f32_dpp v181, v115, v135 row_shl:1 row_mask:0xf bank_mask:0xf
	v_fmac_f32_dpp v198, v116, v136 row_shl:1 row_mask:0xf bank_mask:0xf
	v_fmac_f32_dpp v196, v117, v137 row_shl:1 row_mask:0xf bank_mask:0xf
	v_fmac_f32_dpp v180, v98, v134 row_shr:15 row_mask:0xf bank_mask:0xf
	v_fmac_f32_dpp v181, v99, v135 row_shr:15 row_mask:0xf bank_mask:0xf
	v_fmac_f32_dpp v198, v100, v136 row_shr:15 row_mask:0xf bank_mask:0xf
	v_fmac_f32_dpp v196, v101, v137 row_shr:15 row_mask:0xf bank_mask:0xf
	v_fmac_f32_dpp v180, v114, v142 row_shl:2 row_mask:0xf bank_mask:0xf
	v_fmac_f32_dpp v181, v115, v143 row_shl:2 row_mask:0xf bank_mask:0xf
	v_fmac_f32_dpp v198, v116, v144 row_shl:2 row_mask:0xf bank_mask:0xf
	v_fmac_f32_dpp v196, v117, v145 row_shl:2 row_mask:0xf bank_mask:0xf
	v_fmac_f32_dpp v180, v98, v142 row_shr:14 row_mask:0xf bank_mask:0xf
	v_fmac_f32_dpp v181, v99, v143 row_shr:14 row_mask:0xf bank_mask:0xf
	v_fmac_f32_dpp v198, v100, v144 row_shr:14 row_mask:0xf bank_mask:0xf
	v_fmac_f32_dpp v196, v101, v145 row_shr:14 row_mask:0xf bank_mask:0xf
	v_add_u32_e32 v182, v192, v211
	v_cvt_pk_bf16_f32 v178, v193, v197
	v_cvt_pk_bf16_f32 v179, v194, v195
	v_lshl_or_b32 v182, v182, 14, v212
	v_cvt_pk_bf16_f32 v180, v180, v181
	v_cvt_pk_bf16_f32 v181, v198, v196
	global_store_dwordx4 v182, v[178:181], s[36:37] sc1
	v_pk_fma_f32 v[182:183], v[100:101], v[152:153], v[140:141]
	v_pk_fma_f32 v[184:185], v[98:99], v[150:151], v[138:139]
	v_pk_fma_f32 v[178:179], v[104:105], v[168:169], v[164:165]
	v_pk_fma_f32 v[180:181], v[102:103], v[166:167], v[162:163]
	v_mov_b32_e32 v193, v178
	s_nop 1
	v_fmac_f32_dpp v180, v102, v146 row_shr:1 row_mask:0xf bank_mask:0xf
	v_fmac_f32_dpp v181, v103, v147 row_shr:1 row_mask:0xf bank_mask:0xf
	v_fmac_f32_dpp v193, v104, v148 row_shr:1 row_mask:0xf bank_mask:0xf
	v_fmac_f32_dpp v179, v105, v149 row_shr:1 row_mask:0xf bank_mask:0xf
	v_fmac_f32_dpp v180, v118, v146 row_shl:15 row_mask:0xf bank_mask:0xf
	v_fmac_f32_dpp v181, v119, v147 row_shl:15 row_mask:0xf bank_mask:0xf
	v_fmac_f32_dpp v193, v120, v148 row_shl:15 row_mask:0xf bank_mask:0xf
	v_fmac_f32_dpp v179, v121, v149 row_shl:15 row_mask:0xf bank_mask:0xf
	v_fmac_f32_dpp v180, v102, v154 row_shl:1 row_mask:0xf bank_mask:0xf
	v_fmac_f32_dpp v181, v103, v155 row_shl:1 row_mask:0xf bank_mask:0xf
	v_fmac_f32_dpp v193, v104, v156 row_shl:1 row_mask:0xf bank_mask:0xf
	v_fmac_f32_dpp v179, v105, v157 row_shl:1 row_mask:0xf bank_mask:0xf
	v_fmac_f32_dpp v180, v86, v154 row_shr:15 row_mask:0xf bank_mask:0xf
	v_fmac_f32_dpp v181, v87, v155 row_shr:15 row_mask:0xf bank_mask:0xf
	v_fmac_f32_dpp v193, v88, v156 row_shr:15 row_mask:0xf bank_mask:0xf
	v_fmac_f32_dpp v179, v89, v157 row_shr:15 row_mask:0xf bank_mask:0xf
	v_fmac_f32_dpp v180, v102, v158 row_shl:2 row_mask:0xf bank_mask:0xf
	v_fmac_f32_dpp v181, v103, v159 row_shl:2 row_mask:0xf bank_mask:0xf
	v_fmac_f32_dpp v193, v104, v160 row_shl:2 row_mask:0xf bank_mask:0xf
	v_fmac_f32_dpp v179, v105, v161 row_shl:2 row_mask:0xf bank_mask:0xf
	v_fmac_f32_dpp v180, v86, v158 row_shr:14 row_mask:0xf bank_mask:0xf
	v_fmac_f32_dpp v181, v87, v159 row_shr:14 row_mask:0xf bank_mask:0xf
	v_fmac_f32_dpp v193, v88, v160 row_shr:14 row_mask:0xf bank_mask:0xf
	v_fmac_f32_dpp v179, v89, v161 row_shr:14 row_mask:0xf bank_mask:0xf
	s_nop 1
	v_fmac_f32_dpp v184, v98, v130 row_shr:1 row_mask:0xf bank_mask:0xf
	v_fmac_f32_dpp v185, v99, v131 row_shr:1 row_mask:0xf bank_mask:0xf
	v_fmac_f32_dpp v182, v100, v132 row_shr:1 row_mask:0xf bank_mask:0xf
	v_fmac_f32_dpp v183, v101, v133 row_shr:1 row_mask:0xf bank_mask:0xf
	v_fmac_f32_dpp v184, v114, v130 row_shl:15 row_mask:0xf bank_mask:0xf
	v_fmac_f32_dpp v185, v115, v131 row_shl:15 row_mask:0xf bank_mask:0xf
	v_fmac_f32_dpp v182, v116, v132 row_shl:15 row_mask:0xf bank_mask:0xf
	v_fmac_f32_dpp v183, v117, v133 row_shl:15 row_mask:0xf bank_mask:0xf
	v_fmac_f32_dpp v184, v98, v134 row_shl:1 row_mask:0xf bank_mask:0xf
	v_fmac_f32_dpp v185, v99, v135 row_shl:1 row_mask:0xf bank_mask:0xf
	v_fmac_f32_dpp v182, v100, v136 row_shl:1 row_mask:0xf bank_mask:0xf
	v_fmac_f32_dpp v183, v101, v137 row_shl:1 row_mask:0xf bank_mask:0xf
	v_fmac_f32_dpp v184, v82, v134 row_shr:15 row_mask:0xf bank_mask:0xf
	v_fmac_f32_dpp v185, v83, v135 row_shr:15 row_mask:0xf bank_mask:0xf
	v_fmac_f32_dpp v182, v84, v136 row_shr:15 row_mask:0xf bank_mask:0xf
	v_fmac_f32_dpp v183, v85, v137 row_shr:15 row_mask:0xf bank_mask:0xf
	v_fmac_f32_dpp v184, v98, v142 row_shl:2 row_mask:0xf bank_mask:0xf
	v_fmac_f32_dpp v185, v99, v143 row_shl:2 row_mask:0xf bank_mask:0xf
	v_fmac_f32_dpp v182, v100, v144 row_shl:2 row_mask:0xf bank_mask:0xf
	v_fmac_f32_dpp v183, v101, v145 row_shl:2 row_mask:0xf bank_mask:0xf
	v_fmac_f32_dpp v184, v82, v142 row_shr:14 row_mask:0xf bank_mask:0xf
	v_fmac_f32_dpp v185, v83, v143 row_shr:14 row_mask:0xf bank_mask:0xf
	v_fmac_f32_dpp v182, v84, v144 row_shr:14 row_mask:0xf bank_mask:0xf
	v_fmac_f32_dpp v183, v85, v145 row_shr:14 row_mask:0xf bank_mask:0xf
	s_and_b64 vcc, exec, s[10:11]
	v_cvt_pk_bf16_f32 v178, v180, v181
	v_cvt_pk_bf16_f32 v179, v193, v179
	v_cvt_pk_bf16_f32 v180, v184, v185
	v_cvt_pk_bf16_f32 v181, v182, v183
	v_add_u32_e32 v182, v192, v214
	v_lshl_or_b32 v182, v182, 14, v215
	global_store_dwordx4 v182, v[178:181], s[36:37] sc1
	v_pk_fma_f32 v[182:183], v[84:85], v[152:153], v[140:141]
	v_pk_fma_f32 v[184:185], v[82:83], v[150:151], v[138:139]
	v_pk_fma_f32 v[178:179], v[88:89], v[168:169], v[164:165]
	v_pk_fma_f32 v[180:181], v[86:87], v[166:167], v[162:163]
	v_mov_b32_e32 v193, v178
	s_nop 1
	v_fmac_f32_dpp v180, v86, v146 row_shr:1 row_mask:0xf bank_mask:0xf
	v_fmac_f32_dpp v181, v87, v147 row_shr:1 row_mask:0xf bank_mask:0xf
	v_fmac_f32_dpp v193, v88, v148 row_shr:1 row_mask:0xf bank_mask:0xf
	v_fmac_f32_dpp v179, v89, v149 row_shr:1 row_mask:0xf bank_mask:0xf
	v_fmac_f32_dpp v180, v102, v146 row_shl:15 row_mask:0xf bank_mask:0xf
	v_fmac_f32_dpp v181, v103, v147 row_shl:15 row_mask:0xf bank_mask:0xf
	v_fmac_f32_dpp v193, v104, v148 row_shl:15 row_mask:0xf bank_mask:0xf
	v_fmac_f32_dpp v179, v105, v149 row_shl:15 row_mask:0xf bank_mask:0xf
	v_fmac_f32_dpp v180, v86, v154 row_shl:1 row_mask:0xf bank_mask:0xf
	v_fmac_f32_dpp v181, v87, v155 row_shl:1 row_mask:0xf bank_mask:0xf
	v_fmac_f32_dpp v193, v88, v156 row_shl:1 row_mask:0xf bank_mask:0xf
	v_fmac_f32_dpp v179, v89, v157 row_shl:1 row_mask:0xf bank_mask:0xf
	v_fmac_f32_dpp v180, v70, v154 row_shr:15 row_mask:0xf bank_mask:0xf
	v_fmac_f32_dpp v181, v71, v155 row_shr:15 row_mask:0xf bank_mask:0xf
	v_fmac_f32_dpp v193, v72, v156 row_shr:15 row_mask:0xf bank_mask:0xf
	v_fmac_f32_dpp v179, v73, v157 row_shr:15 row_mask:0xf bank_mask:0xf
	v_fmac_f32_dpp v180, v86, v158 row_shl:2 row_mask:0xf bank_mask:0xf
	v_fmac_f32_dpp v181, v87, v159 row_shl:2 row_mask:0xf bank_mask:0xf
	v_fmac_f32_dpp v193, v88, v160 row_shl:2 row_mask:0xf bank_mask:0xf
	v_fmac_f32_dpp v179, v89, v161 row_shl:2 row_mask:0xf bank_mask:0xf
	v_fmac_f32_dpp v180, v70, v158 row_shr:14 row_mask:0xf bank_mask:0xf
	v_fmac_f32_dpp v181, v71, v159 row_shr:14 row_mask:0xf bank_mask:0xf
	v_fmac_f32_dpp v193, v72, v160 row_shr:14 row_mask:0xf bank_mask:0xf
	v_fmac_f32_dpp v179, v73, v161 row_shr:14 row_mask:0xf bank_mask:0xf
	s_nop 1
	v_fmac_f32_dpp v184, v82, v130 row_shr:1 row_mask:0xf bank_mask:0xf
	v_fmac_f32_dpp v185, v83, v131 row_shr:1 row_mask:0xf bank_mask:0xf
	v_fmac_f32_dpp v182, v84, v132 row_shr:1 row_mask:0xf bank_mask:0xf
	v_fmac_f32_dpp v183, v85, v133 row_shr:1 row_mask:0xf bank_mask:0xf
	v_fmac_f32_dpp v184, v98, v130 row_shl:15 row_mask:0xf bank_mask:0xf
	v_fmac_f32_dpp v185, v99, v131 row_shl:15 row_mask:0xf bank_mask:0xf
	v_fmac_f32_dpp v182, v100, v132 row_shl:15 row_mask:0xf bank_mask:0xf
	v_fmac_f32_dpp v183, v101, v133 row_shl:15 row_mask:0xf bank_mask:0xf
	v_fmac_f32_dpp v184, v82, v134 row_shl:1 row_mask:0xf bank_mask:0xf
	v_fmac_f32_dpp v185, v83, v135 row_shl:1 row_mask:0xf bank_mask:0xf
	v_fmac_f32_dpp v182, v84, v136 row_shl:1 row_mask:0xf bank_mask:0xf
	v_fmac_f32_dpp v183, v85, v137 row_shl:1 row_mask:0xf bank_mask:0xf
	v_fmac_f32_dpp v184, v66, v134 row_shr:15 row_mask:0xf bank_mask:0xf
	v_fmac_f32_dpp v185, v67, v135 row_shr:15 row_mask:0xf bank_mask:0xf
	v_fmac_f32_dpp v182, v68, v136 row_shr:15 row_mask:0xf bank_mask:0xf
	v_fmac_f32_dpp v183, v69, v137 row_shr:15 row_mask:0xf bank_mask:0xf
	v_fmac_f32_dpp v184, v82, v142 row_shl:2 row_mask:0xf bank_mask:0xf
	v_fmac_f32_dpp v185, v83, v143 row_shl:2 row_mask:0xf bank_mask:0xf
	v_fmac_f32_dpp v182, v84, v144 row_shl:2 row_mask:0xf bank_mask:0xf
	v_fmac_f32_dpp v183, v85, v145 row_shl:2 row_mask:0xf bank_mask:0xf
	v_fmac_f32_dpp v184, v66, v142 row_shr:14 row_mask:0xf bank_mask:0xf
	v_fmac_f32_dpp v185, v67, v143 row_shr:14 row_mask:0xf bank_mask:0xf
	v_fmac_f32_dpp v182, v68, v144 row_shr:14 row_mask:0xf bank_mask:0xf
	v_fmac_f32_dpp v183, v69, v145 row_shr:14 row_mask:0xf bank_mask:0xf
	s_nop 0
	v_cvt_pk_bf16_f32 v178, v180, v181
	v_cvt_pk_bf16_f32 v179, v193, v179
	v_cvt_pk_bf16_f32 v180, v184, v185
	v_cvt_pk_bf16_f32 v181, v182, v183
	v_add_u32_e32 v182, v192, v216
	v_lshl_or_b32 v182, v182, 14, v217
	global_store_dwordx4 v182, v[178:181], s[36:37] sc1
	v_pk_fma_f32 v[182:183], v[68:69], v[152:153], v[140:141]
	s_nop 0
	v_pk_fma_f32 v[178:179], v[72:73], v[168:169], v[164:165]
	v_pk_fma_f32 v[180:181], v[70:71], v[166:167], v[162:163]
	s_nop 0
	s_nop 1
	v_fmac_f32_dpp v180, v70, v146 row_shr:1 row_mask:0xf bank_mask:0xf
	v_fmac_f32_dpp v181, v71, v147 row_shr:1 row_mask:0xf bank_mask:0xf
	v_fmac_f32_dpp v178, v72, v148 row_shr:1 row_mask:0xf bank_mask:0xf
	v_fmac_f32_dpp v179, v73, v149 row_shr:1 row_mask:0xf bank_mask:0xf
	v_fmac_f32_dpp v180, v86, v146 row_shl:15 row_mask:0xf bank_mask:0xf
	v_fmac_f32_dpp v181, v87, v147 row_shl:15 row_mask:0xf bank_mask:0xf
	v_fmac_f32_dpp v178, v88, v148 row_shl:15 row_mask:0xf bank_mask:0xf
	v_fmac_f32_dpp v179, v89, v149 row_shl:15 row_mask:0xf bank_mask:0xf
	v_fmac_f32_dpp v180, v70, v154 row_shl:1 row_mask:0xf bank_mask:0xf
	v_fmac_f32_dpp v181, v71, v155 row_shl:1 row_mask:0xf bank_mask:0xf
	v_fmac_f32_dpp v178, v72, v156 row_shl:1 row_mask:0xf bank_mask:0xf
	v_fmac_f32_dpp v179, v73, v157 row_shl:1 row_mask:0xf bank_mask:0xf
	v_fmac_f32_dpp v180, v170, v154 row_shr:15 row_mask:0xf bank_mask:0xf
	v_fmac_f32_dpp v181, v171, v155 row_shr:15 row_mask:0xf bank_mask:0xf
	v_fmac_f32_dpp v178, v172, v156 row_shr:15 row_mask:0xf bank_mask:0xf
	v_fmac_f32_dpp v179, v173, v157 row_shr:15 row_mask:0xf bank_mask:0xf
	v_fmac_f32_dpp v180, v70, v158 row_shl:2 row_mask:0xf bank_mask:0xf
	v_fmac_f32_dpp v181, v71, v159 row_shl:2 row_mask:0xf bank_mask:0xf
	v_fmac_f32_dpp v178, v72, v160 row_shl:2 row_mask:0xf bank_mask:0xf
	v_fmac_f32_dpp v179, v73, v161 row_shl:2 row_mask:0xf bank_mask:0xf
	v_fmac_f32_dpp v180, v170, v158 row_shr:14 row_mask:0xf bank_mask:0xf
	v_fmac_f32_dpp v181, v171, v159 row_shr:14 row_mask:0xf bank_mask:0xf
	v_fmac_f32_dpp v178, v172, v160 row_shr:14 row_mask:0xf bank_mask:0xf
	v_fmac_f32_dpp v179, v173, v161 row_shr:14 row_mask:0xf bank_mask:0xf
	v_pk_fma_f32 v[172:173], v[66:67], v[150:151], v[138:139]
	s_nop 0
	s_nop 1
	v_fmac_f32_dpp v172, v66, v130 row_shr:1 row_mask:0xf bank_mask:0xf
	v_fmac_f32_dpp v173, v67, v131 row_shr:1 row_mask:0xf bank_mask:0xf
	v_fmac_f32_dpp v182, v68, v132 row_shr:1 row_mask:0xf bank_mask:0xf
	v_fmac_f32_dpp v183, v69, v133 row_shr:1 row_mask:0xf bank_mask:0xf
	v_fmac_f32_dpp v172, v82, v130 row_shl:15 row_mask:0xf bank_mask:0xf
	v_fmac_f32_dpp v173, v83, v131 row_shl:15 row_mask:0xf bank_mask:0xf
	v_fmac_f32_dpp v182, v84, v132 row_shl:15 row_mask:0xf bank_mask:0xf
	v_fmac_f32_dpp v183, v85, v133 row_shl:15 row_mask:0xf bank_mask:0xf
	v_fmac_f32_dpp v172, v66, v134 row_shl:1 row_mask:0xf bank_mask:0xf
	v_fmac_f32_dpp v173, v67, v135 row_shl:1 row_mask:0xf bank_mask:0xf
	v_fmac_f32_dpp v182, v68, v136 row_shl:1 row_mask:0xf bank_mask:0xf
	v_fmac_f32_dpp v183, v69, v137 row_shl:1 row_mask:0xf bank_mask:0xf
	v_fmac_f32_dpp v172, v174, v134 row_shr:15 row_mask:0xf bank_mask:0xf
	v_fmac_f32_dpp v173, v175, v135 row_shr:15 row_mask:0xf bank_mask:0xf
	v_fmac_f32_dpp v182, v176, v136 row_shr:15 row_mask:0xf bank_mask:0xf
	v_fmac_f32_dpp v183, v177, v137 row_shr:15 row_mask:0xf bank_mask:0xf
	v_fmac_f32_dpp v172, v66, v142 row_shl:2 row_mask:0xf bank_mask:0xf
	v_fmac_f32_dpp v173, v67, v143 row_shl:2 row_mask:0xf bank_mask:0xf
	v_fmac_f32_dpp v182, v68, v144 row_shl:2 row_mask:0xf bank_mask:0xf
	v_fmac_f32_dpp v183, v69, v145 row_shl:2 row_mask:0xf bank_mask:0xf
	v_fmac_f32_dpp v172, v174, v142 row_shr:14 row_mask:0xf bank_mask:0xf
	v_fmac_f32_dpp v173, v175, v143 row_shr:14 row_mask:0xf bank_mask:0xf
	v_fmac_f32_dpp v182, v176, v144 row_shr:14 row_mask:0xf bank_mask:0xf
	v_fmac_f32_dpp v183, v177, v145 row_shr:14 row_mask:0xf bank_mask:0xf
	v_add_u32_e32 v174, v192, v218
	v_cvt_pk_bf16_f32 v170, v180, v181
	v_cvt_pk_bf16_f32 v171, v178, v179
	v_lshl_or_b32 v174, v174, 14, v222
	v_cvt_pk_bf16_f32 v172, v172, v173
	v_cvt_pk_bf16_f32 v173, v182, v183
	global_store_dwordx4 v174, v[170:173], s[36:37] sc1
	v_mov_b32_e32 v174, 0
	v_mov_b32_e32 v175, 0
	v_lshl_add_u32 v171, v188, 2, s24
	ds_read_b128 v[182:185], v171
	v_mov_b32_e32 v170, 0
	v_mov_b32_e32 v176, 0
	v_mov_b32_e32 v177, 0
	s_cbranch_vccnz .LBB0_773
	ds_read_b128 v[174:177], v213 offset:512

.LBB0_775:
	v_pk_fma_f32 v[194:195], v[56:57], v[168:169], v[164:165]
	v_pk_fma_f32 v[196:197], v[54:55], v[166:167], v[162:163]
	s_waitcnt lgkmcnt(1)
	s_nop 1
	v_fmac_f32_dpp v196, v54, v146 row_shr:1 row_mask:0xf bank_mask:0xf
	v_fmac_f32_dpp v197, v55, v147 row_shr:1 row_mask:0xf bank_mask:0xf
	v_fmac_f32_dpp v194, v56, v148 row_shr:1 row_mask:0xf bank_mask:0xf
	v_fmac_f32_dpp v195, v57, v149 row_shr:1 row_mask:0xf bank_mask:0xf
	v_fmac_f32_dpp v196, v182, v146 row_shl:15 row_mask:0xf bank_mask:0xf
	v_fmac_f32_dpp v197, v183, v147 row_shl:15 row_mask:0xf bank_mask:0xf
	v_fmac_f32_dpp v194, v184, v148 row_shl:15 row_mask:0xf bank_mask:0xf
	v_fmac_f32_dpp v195, v185, v149 row_shl:15 row_mask:0xf bank_mask:0xf
	v_fmac_f32_dpp v196, v54, v154 row_shl:1 row_mask:0xf bank_mask:0xf
	v_fmac_f32_dpp v197, v55, v155 row_shl:1 row_mask:0xf bank_mask:0xf
	v_fmac_f32_dpp v194, v56, v156 row_shl:1 row_mask:0xf bank_mask:0xf
	v_fmac_f32_dpp v195, v57, v157 row_shl:1 row_mask:0xf bank_mask:0xf
	v_fmac_f32_dpp v196, v38, v154 row_shr:15 row_mask:0xf bank_mask:0xf
	v_fmac_f32_dpp v197, v39, v155 row_shr:15 row_mask:0xf bank_mask:0xf
	v_fmac_f32_dpp v194, v40, v156 row_shr:15 row_mask:0xf bank_mask:0xf
	v_fmac_f32_dpp v195, v41, v157 row_shr:15 row_mask:0xf bank_mask:0xf
	v_fmac_f32_dpp v196, v54, v158 row_shl:2 row_mask:0xf bank_mask:0xf
	v_fmac_f32_dpp v197, v55, v159 row_shl:2 row_mask:0xf bank_mask:0xf
	v_fmac_f32_dpp v194, v56, v160 row_shl:2 row_mask:0xf bank_mask:0xf
	v_fmac_f32_dpp v195, v57, v161 row_shl:2 row_mask:0xf bank_mask:0xf
	v_fmac_f32_dpp v196, v38, v158 row_shr:14 row_mask:0xf bank_mask:0xf
	v_fmac_f32_dpp v197, v39, v159 row_shr:14 row_mask:0xf bank_mask:0xf
	v_fmac_f32_dpp v194, v40, v160 row_shr:14 row_mask:0xf bank_mask:0xf
	v_fmac_f32_dpp v195, v41, v161 row_shr:14 row_mask:0xf bank_mask:0xf
	v_pk_fma_f32 v[182:183], v[52:53], v[152:153], v[140:141]
	v_pk_fma_f32 v[184:185], v[50:51], v[150:151], v[138:139]
	s_waitcnt lgkmcnt(0)
	s_nop 1
	v_fmac_f32_dpp v184, v50, v130 row_shr:1 row_mask:0xf bank_mask:0xf
	v_fmac_f32_dpp v185, v51, v131 row_shr:1 row_mask:0xf bank_mask:0xf
	v_fmac_f32_dpp v182, v52, v132 row_shr:1 row_mask:0xf bank_mask:0xf
	v_fmac_f32_dpp v183, v53, v133 row_shr:1 row_mask:0xf bank_mask:0xf
	v_fmac_f32_dpp v184, v178, v130 row_shl:15 row_mask:0xf bank_mask:0xf
	v_fmac_f32_dpp v185, v179, v131 row_shl:15 row_mask:0xf bank_mask:0xf
	v_fmac_f32_dpp v182, v180, v132 row_shl:15 row_mask:0xf bank_mask:0xf
	v_fmac_f32_dpp v183, v181, v133 row_shl:15 row_mask:0xf bank_mask:0xf
	v_fmac_f32_dpp v184, v50, v134 row_shl:1 row_mask:0xf bank_mask:0xf
	v_fmac_f32_dpp v185, v51, v135 row_shl:1 row_mask:0xf bank_mask:0xf
	v_fmac_f32_dpp v182, v52, v136 row_shl:1 row_mask:0xf bank_mask:0xf
	v_fmac_f32_dpp v183, v53, v137 row_shl:1 row_mask:0xf bank_mask:0xf
	v_fmac_f32_dpp v184, v34, v134 row_shr:15 row_mask:0xf bank_mask:0xf
	v_fmac_f32_dpp v185, v35, v135 row_shr:15 row_mask:0xf bank_mask:0xf
	v_fmac_f32_dpp v182, v36, v136 row_shr:15 row_mask:0xf bank_mask:0xf
	v_fmac_f32_dpp v183, v37, v137 row_shr:15 row_mask:0xf bank_mask:0xf
	v_fmac_f32_dpp v184, v50, v142 row_shl:2 row_mask:0xf bank_mask:0xf
	v_fmac_f32_dpp v185, v51, v143 row_shl:2 row_mask:0xf bank_mask:0xf
	v_fmac_f32_dpp v182, v52, v144 row_shl:2 row_mask:0xf bank_mask:0xf
	v_fmac_f32_dpp v183, v53, v145 row_shl:2 row_mask:0xf bank_mask:0xf
	v_fmac_f32_dpp v184, v34, v142 row_shr:14 row_mask:0xf bank_mask:0xf
	v_fmac_f32_dpp v185, v35, v143 row_shr:14 row_mask:0xf bank_mask:0xf
	v_fmac_f32_dpp v182, v36, v144 row_shr:14 row_mask:0xf bank_mask:0xf
	v_fmac_f32_dpp v183, v37, v145 row_shr:14 row_mask:0xf bank_mask:0xf
	v_cvt_pk_bf16_f32 v178, v196, v197
	v_cvt_pk_bf16_f32 v179, v194, v195
	s_nop 0
	v_cvt_pk_bf16_f32 v180, v184, v185
	v_cvt_pk_bf16_f32 v181, v182, v183
	v_add_u32_e32 v182, v192, v220
	v_lshl_or_b32 v182, v182, 14, v224
	global_store_dwordx4 v182, v[178:181], s[36:37] sc1
	v_pk_fma_f32 v[182:183], v[36:37], v[152:153], v[140:141]
	v_pk_fma_f32 v[184:185], v[34:35], v[150:151], v[138:139]
	v_pk_fma_f32 v[180:181], v[40:41], v[168:169], v[164:165]
	v_pk_fma_f32 v[178:179], v[38:39], v[166:167], v[162:163]
	s_nop 0
	s_nop 1
	v_fmac_f32_dpp v178, v38, v146 row_shr:1 row_mask:0xf bank_mask:0xf
	v_fmac_f32_dpp v179, v39, v147 row_shr:1 row_mask:0xf bank_mask:0xf
	v_fmac_f32_dpp v180, v40, v148 row_shr:1 row_mask:0xf bank_mask:0xf
	v_fmac_f32_dpp v181, v41, v149 row_shr:1 row_mask:0xf bank_mask:0xf
	v_fmac_f32_dpp v178, v54, v146 row_shl:15 row_mask:0xf bank_mask:0xf
	v_fmac_f32_dpp v179, v55, v147 row_shl:15 row_mask:0xf bank_mask:0xf
	v_fmac_f32_dpp v180, v56, v148 row_shl:15 row_mask:0xf bank_mask:0xf
	v_fmac_f32_dpp v181, v57, v149 row_shl:15 row_mask:0xf bank_mask:0xf
	v_fmac_f32_dpp v178, v38, v154 row_shl:1 row_mask:0xf bank_mask:0xf
	v_fmac_f32_dpp v179, v39, v155 row_shl:1 row_mask:0xf bank_mask:0xf
	v_fmac_f32_dpp v180, v40, v156 row_shl:1 row_mask:0xf bank_mask:0xf
	v_fmac_f32_dpp v181, v41, v157 row_shl:1 row_mask:0xf bank_mask:0xf
	v_fmac_f32_dpp v178, v22, v154 row_shr:15 row_mask:0xf bank_mask:0xf
	v_fmac_f32_dpp v179, v23, v155 row_shr:15 row_mask:0xf bank_mask:0xf
	v_fmac_f32_dpp v180, v24, v156 row_shr:15 row_mask:0xf bank_mask:0xf
	v_fmac_f32_dpp v181, v25, v157 row_shr:15 row_mask:0xf bank_mask:0xf
	v_fmac_f32_dpp v178, v38, v158 row_shl:2 row_mask:0xf bank_mask:0xf
	v_fmac_f32_dpp v179, v39, v159 row_shl:2 row_mask:0xf bank_mask:0xf
	v_fmac_f32_dpp v180, v40, v160 row_shl:2 row_mask:0xf bank_mask:0xf
	v_fmac_f32_dpp v181, v41, v161 row_shl:2 row_mask:0xf bank_mask:0xf
	v_fmac_f32_dpp v178, v22, v158 row_shr:14 row_mask:0xf bank_mask:0xf
	v_fmac_f32_dpp v179, v23, v159 row_shr:14 row_mask:0xf bank_mask:0xf
	v_fmac_f32_dpp v180, v24, v160 row_shr:14 row_mask:0xf bank_mask:0xf
	v_fmac_f32_dpp v181, v25, v161 row_shr:14 row_mask:0xf bank_mask:0xf
	s_nop 1
	v_fmac_f32_dpp v184, v34, v130 row_shr:1 row_mask:0xf bank_mask:0xf
	v_fmac_f32_dpp v185, v35, v131 row_shr:1 row_mask:0xf bank_mask:0xf
	v_fmac_f32_dpp v182, v36, v132 row_shr:1 row_mask:0xf bank_mask:0xf
	v_fmac_f32_dpp v183, v37, v133 row_shr:1 row_mask:0xf bank_mask:0xf
	v_fmac_f32_dpp v184, v50, v130 row_shl:15 row_mask:0xf bank_mask:0xf
	v_fmac_f32_dpp v185, v51, v131 row_shl:15 row_mask:0xf bank_mask:0xf
	v_fmac_f32_dpp v182, v52, v132 row_shl:15 row_mask:0xf bank_mask:0xf
	v_fmac_f32_dpp v183, v53, v133 row_shl:15 row_mask:0xf bank_mask:0xf
	v_fmac_f32_dpp v184, v34, v134 row_shl:1 row_mask:0xf bank_mask:0xf
	v_fmac_f32_dpp v185, v35, v135 row_shl:1 row_mask:0xf bank_mask:0xf
	v_fmac_f32_dpp v182, v36, v136 row_shl:1 row_mask:0xf bank_mask:0xf
	v_fmac_f32_dpp v183, v37, v137 row_shl:1 row_mask:0xf bank_mask:0xf
	v_fmac_f32_dpp v184, v18, v134 row_shr:15 row_mask:0xf bank_mask:0xf
	v_fmac_f32_dpp v185, v19, v135 row_shr:15 row_mask:0xf bank_mask:0xf
	v_fmac_f32_dpp v182, v20, v136 row_shr:15 row_mask:0xf bank_mask:0xf
	v_fmac_f32_dpp v183, v21, v137 row_shr:15 row_mask:0xf bank_mask:0xf
	v_fmac_f32_dpp v184, v34, v142 row_shl:2 row_mask:0xf bank_mask:0xf
	v_fmac_f32_dpp v185, v35, v143 row_shl:2 row_mask:0xf bank_mask:0xf
	v_fmac_f32_dpp v182, v36, v144 row_shl:2 row_mask:0xf bank_mask:0xf
	v_fmac_f32_dpp v183, v37, v145 row_shl:2 row_mask:0xf bank_mask:0xf
	v_fmac_f32_dpp v184, v18, v142 row_shr:14 row_mask:0xf bank_mask:0xf
	v_fmac_f32_dpp v185, v19, v143 row_shr:14 row_mask:0xf bank_mask:0xf
	v_fmac_f32_dpp v182, v20, v144 row_shr:14 row_mask:0xf bank_mask:0xf
	v_fmac_f32_dpp v183, v21, v145 row_shr:14 row_mask:0xf bank_mask:0xf
	s_nop 0
	v_cvt_pk_bf16_f32 v178, v178, v179
	v_cvt_pk_bf16_f32 v179, v180, v181
	v_cvt_pk_bf16_f32 v180, v184, v185
	v_cvt_pk_bf16_f32 v181, v182, v183
	v_add_u32_e32 v182, v192, v221
	v_lshl_or_b32 v182, v182, 14, v226
	global_store_dwordx4 v182, v[178:181], s[36:37] sc1
	v_pk_fma_f32 v[182:183], v[20:21], v[152:153], v[140:141]
	v_pk_fma_f32 v[184:185], v[18:19], v[150:151], v[138:139]
	v_pk_fma_f32 v[180:181], v[24:25], v[168:169], v[164:165]
	v_pk_fma_f32 v[178:179], v[22:23], v[166:167], v[162:163]
	v_pk_fma_f32 v[164:165], v[8:9], v[168:169], v[164:165]
	s_nop 1
	v_fmac_f32_dpp v178, v22, v146 row_shr:1 row_mask:0xf bank_mask:0xf
	v_fmac_f32_dpp v179, v23, v147 row_shr:1 row_mask:0xf bank_mask:0xf
	v_fmac_f32_dpp v180, v24, v148 row_shr:1 row_mask:0xf bank_mask:0xf
	v_fmac_f32_dpp v181, v25, v149 row_shr:1 row_mask:0xf bank_mask:0xf
	v_fmac_f32_dpp v178, v38, v146 row_shl:15 row_mask:0xf bank_mask:0xf
	v_fmac_f32_dpp v179, v39, v147 row_shl:15 row_mask:0xf bank_mask:0xf
	v_fmac_f32_dpp v180, v40, v148 row_shl:15 row_mask:0xf bank_mask:0xf
	v_fmac_f32_dpp v181, v41, v149 row_shl:15 row_mask:0xf bank_mask:0xf
	v_fmac_f32_dpp v178, v22, v154 row_shl:1 row_mask:0xf bank_mask:0xf
	v_fmac_f32_dpp v179, v23, v155 row_shl:1 row_mask:0xf bank_mask:0xf
	v_fmac_f32_dpp v180, v24, v156 row_shl:1 row_mask:0xf bank_mask:0xf
	v_fmac_f32_dpp v181, v25, v157 row_shl:1 row_mask:0xf bank_mask:0xf
	v_fmac_f32_dpp v178, v6, v154 row_shr:15 row_mask:0xf bank_mask:0xf
	v_fmac_f32_dpp v179, v7, v155 row_shr:15 row_mask:0xf bank_mask:0xf
	v_fmac_f32_dpp v180, v8, v156 row_shr:15 row_mask:0xf bank_mask:0xf
	v_fmac_f32_dpp v181, v9, v157 row_shr:15 row_mask:0xf bank_mask:0xf
	v_fmac_f32_dpp v178, v22, v158 row_shl:2 row_mask:0xf bank_mask:0xf
	v_fmac_f32_dpp v179, v23, v159 row_shl:2 row_mask:0xf bank_mask:0xf
	v_fmac_f32_dpp v180, v24, v160 row_shl:2 row_mask:0xf bank_mask:0xf
	v_fmac_f32_dpp v181, v25, v161 row_shl:2 row_mask:0xf bank_mask:0xf
	v_fmac_f32_dpp v178, v6, v158 row_shr:14 row_mask:0xf bank_mask:0xf
	v_fmac_f32_dpp v179, v7, v159 row_shr:14 row_mask:0xf bank_mask:0xf
	v_fmac_f32_dpp v180, v8, v160 row_shr:14 row_mask:0xf bank_mask:0xf
	v_fmac_f32_dpp v181, v9, v161 row_shr:14 row_mask:0xf bank_mask:0xf
	s_nop 1
	v_fmac_f32_dpp v184, v18, v130 row_shr:1 row_mask:0xf bank_mask:0xf
	v_fmac_f32_dpp v185, v19, v131 row_shr:1 row_mask:0xf bank_mask:0xf
	v_fmac_f32_dpp v182, v20, v132 row_shr:1 row_mask:0xf bank_mask:0xf
	v_fmac_f32_dpp v183, v21, v133 row_shr:1 row_mask:0xf bank_mask:0xf
	v_fmac_f32_dpp v184, v34, v130 row_shl:15 row_mask:0xf bank_mask:0xf
	v_fmac_f32_dpp v185, v35, v131 row_shl:15 row_mask:0xf bank_mask:0xf
	v_fmac_f32_dpp v182, v36, v132 row_shl:15 row_mask:0xf bank_mask:0xf
	v_fmac_f32_dpp v183, v37, v133 row_shl:15 row_mask:0xf bank_mask:0xf
	v_fmac_f32_dpp v184, v18, v134 row_shl:1 row_mask:0xf bank_mask:0xf
	v_fmac_f32_dpp v185, v19, v135 row_shl:1 row_mask:0xf bank_mask:0xf
	v_fmac_f32_dpp v182, v20, v136 row_shl:1 row_mask:0xf bank_mask:0xf
	v_fmac_f32_dpp v183, v21, v137 row_shl:1 row_mask:0xf bank_mask:0xf
	v_fmac_f32_dpp v184, v2, v134 row_shr:15 row_mask:0xf bank_mask:0xf
	v_fmac_f32_dpp v185, v3, v135 row_shr:15 row_mask:0xf bank_mask:0xf
	v_fmac_f32_dpp v182, v4, v136 row_shr:15 row_mask:0xf bank_mask:0xf
	v_fmac_f32_dpp v183, v5, v137 row_shr:15 row_mask:0xf bank_mask:0xf
	v_fmac_f32_dpp v184, v18, v142 row_shl:2 row_mask:0xf bank_mask:0xf
	v_fmac_f32_dpp v185, v19, v143 row_shl:2 row_mask:0xf bank_mask:0xf
	v_fmac_f32_dpp v182, v20, v144 row_shl:2 row_mask:0xf bank_mask:0xf
	v_fmac_f32_dpp v183, v21, v145 row_shl:2 row_mask:0xf bank_mask:0xf
	v_fmac_f32_dpp v184, v2, v142 row_shr:14 row_mask:0xf bank_mask:0xf
	v_fmac_f32_dpp v185, v3, v143 row_shr:14 row_mask:0xf bank_mask:0xf
	v_fmac_f32_dpp v182, v4, v144 row_shr:14 row_mask:0xf bank_mask:0xf
	v_fmac_f32_dpp v183, v5, v145 row_shr:14 row_mask:0xf bank_mask:0xf
	v_pk_fma_f32 v[162:163], v[6:7], v[166:167], v[162:163]
	v_cvt_pk_bf16_f32 v178, v178, v179
	v_cvt_pk_bf16_f32 v179, v180, v181
	v_cvt_pk_bf16_f32 v180, v184, v185
	v_cvt_pk_bf16_f32 v181, v182, v183
	v_add_u32_e32 v182, v192, v223
	v_lshl_or_b32 v182, v182, 14, v227
	v_pk_fma_f32 v[140:141], v[4:5], v[152:153], v[140:141]
	v_pk_fma_f32 v[138:139], v[2:3], v[150:151], v[138:139]
	global_store_dwordx4 v182, v[178:181], s[36:37] sc1
	s_nop 1
	v_fmac_f32_dpp v162, v6, v146 row_shr:1 row_mask:0xf bank_mask:0xf
	v_fmac_f32_dpp v163, v7, v147 row_shr:1 row_mask:0xf bank_mask:0xf
	v_fmac_f32_dpp v164, v8, v148 row_shr:1 row_mask:0xf bank_mask:0xf
	v_fmac_f32_dpp v165, v9, v149 row_shr:1 row_mask:0xf bank_mask:0xf
	v_fmac_f32_dpp v162, v22, v146 row_shl:15 row_mask:0xf bank_mask:0xf
	v_fmac_f32_dpp v163, v23, v147 row_shl:15 row_mask:0xf bank_mask:0xf
	v_fmac_f32_dpp v164, v24, v148 row_shl:15 row_mask:0xf bank_mask:0xf
	v_fmac_f32_dpp v165, v25, v149 row_shl:15 row_mask:0xf bank_mask:0xf
	v_fmac_f32_dpp v162, v6, v154 row_shl:1 row_mask:0xf bank_mask:0xf
	v_fmac_f32_dpp v163, v7, v155 row_shl:1 row_mask:0xf bank_mask:0xf
	v_fmac_f32_dpp v164, v8, v156 row_shl:1 row_mask:0xf bank_mask:0xf
	v_fmac_f32_dpp v165, v9, v157 row_shl:1 row_mask:0xf bank_mask:0xf
	v_fmac_f32_dpp v162, v174, v154 row_shr:15 row_mask:0xf bank_mask:0xf
	v_fmac_f32_dpp v163, v175, v155 row_shr:15 row_mask:0xf bank_mask:0xf
	v_fmac_f32_dpp v164, v176, v156 row_shr:15 row_mask:0xf bank_mask:0xf
	v_fmac_f32_dpp v165, v177, v157 row_shr:15 row_mask:0xf bank_mask:0xf
	v_fmac_f32_dpp v162, v6, v158 row_shl:2 row_mask:0xf bank_mask:0xf
	v_fmac_f32_dpp v163, v7, v159 row_shl:2 row_mask:0xf bank_mask:0xf
	v_fmac_f32_dpp v164, v8, v160 row_shl:2 row_mask:0xf bank_mask:0xf
	v_fmac_f32_dpp v165, v9, v161 row_shl:2 row_mask:0xf bank_mask:0xf
	v_fmac_f32_dpp v162, v174, v158 row_shr:14 row_mask:0xf bank_mask:0xf
	v_fmac_f32_dpp v163, v175, v159 row_shr:14 row_mask:0xf bank_mask:0xf
	v_fmac_f32_dpp v164, v176, v160 row_shr:14 row_mask:0xf bank_mask:0xf
	v_fmac_f32_dpp v165, v177, v161 row_shr:14 row_mask:0xf bank_mask:0xf
	s_nop 1
	v_fmac_f32_dpp v138, v2, v130 row_shr:1 row_mask:0xf bank_mask:0xf
	v_fmac_f32_dpp v139, v3, v131 row_shr:1 row_mask:0xf bank_mask:0xf
	v_fmac_f32_dpp v140, v4, v132 row_shr:1 row_mask:0xf bank_mask:0xf
	v_fmac_f32_dpp v141, v5, v133 row_shr:1 row_mask:0xf bank_mask:0xf
	v_fmac_f32_dpp v138, v18, v130 row_shl:15 row_mask:0xf bank_mask:0xf
	v_fmac_f32_dpp v139, v19, v131 row_shl:15 row_mask:0xf bank_mask:0xf
	v_fmac_f32_dpp v140, v20, v132 row_shl:15 row_mask:0xf bank_mask:0xf
	v_fmac_f32_dpp v141, v21, v133 row_shl:15 row_mask:0xf bank_mask:0xf
	v_fmac_f32_dpp v138, v2, v134 row_shl:1 row_mask:0xf bank_mask:0xf
	v_fmac_f32_dpp v139, v3, v135 row_shl:1 row_mask:0xf bank_mask:0xf
	v_fmac_f32_dpp v140, v4, v136 row_shl:1 row_mask:0xf bank_mask:0xf
	v_fmac_f32_dpp v141, v5, v137 row_shl:1 row_mask:0xf bank_mask:0xf
	v_fmac_f32_dpp v138, v170, v134 row_shr:15 row_mask:0xf bank_mask:0xf
	v_fmac_f32_dpp v139, v171, v135 row_shr:15 row_mask:0xf bank_mask:0xf
	v_fmac_f32_dpp v140, v172, v136 row_shr:15 row_mask:0xf bank_mask:0xf
	v_fmac_f32_dpp v141, v173, v137 row_shr:15 row_mask:0xf bank_mask:0xf
	v_fmac_f32_dpp v138, v2, v142 row_shl:2 row_mask:0xf bank_mask:0xf
	v_fmac_f32_dpp v139, v3, v143 row_shl:2 row_mask:0xf bank_mask:0xf
	v_fmac_f32_dpp v140, v4, v144 row_shl:2 row_mask:0xf bank_mask:0xf
	v_fmac_f32_dpp v141, v5, v145 row_shl:2 row_mask:0xf bank_mask:0xf
	v_fmac_f32_dpp v138, v170, v142 row_shr:14 row_mask:0xf bank_mask:0xf
	v_fmac_f32_dpp v139, v171, v143 row_shr:14 row_mask:0xf bank_mask:0xf
	v_fmac_f32_dpp v140, v172, v144 row_shr:14 row_mask:0xf bank_mask:0xf
	v_fmac_f32_dpp v141, v173, v145 row_shr:14 row_mask:0xf bank_mask:0xf
	v_add_u32_e32 v134, v192, v219
	v_lshl_or_b32 v134, v134, 14, v225
	v_cvt_pk_bf16_f32 v130, v162, v163
	v_cvt_pk_bf16_f32 v131, v164, v165
	v_cvt_pk_bf16_f32 v132, v138, v139
	v_cvt_pk_bf16_f32 v133, v140, v141
	global_store_dwordx4 v134, v[130:133], s[36:37] sc1
	s_branch .LBB0_737

.LBB0_787:
	v_cmp_gt_i32_e32 vcc, 32, v210
	s_and_saveexec_b64 s[6:7], vcc
	s_cbranch_execz .LBB0_789
	v_lshlrev_b32_e32 v130, 3, v210
	s_waitcnt lgkmcnt(0)
	s_mul_hi_i32 s9, s3, 0xc00
	s_mulk_i32 s3, 0xc00
	v_lshl_add_u32 v138, s1, 8, v130
	s_add_u32 s8, s60, s3
	v_ashrrev_i32_e32 v139, 31, v138
	s_addc_u32 s9, s61, s9
	v_lshl_add_u64 v[134:135], v[138:139], 2, s[38:39]
	s_lshl_b32 s3, s0, 6
	v_lshrrev_b32_e32 v138, 6, v138
	v_lshlrev_b32_e32 v139, 4, v210
	v_lshlrev_b32_e32 v140, 8, v210
	v_ashrrev_i32_e32 v131, 31, v130
	v_add_lshl_u32 v138, v138, s3, 14
	v_and_b32_e32 v139, 48, v139
	v_and_b32_e32 v140, 0x400, v140
	v_lshl_add_u64 v[132:133], v[130:131], 2, s[8:9]
	v_or3_b32 v150, v139, v140, v138
	global_load_dword v142, v[132:133], off offset:2048 sc1
	global_load_dword v143, v[132:133], off offset:2052 sc1
	global_load_dword v144, v[132:133], off offset:2056 sc1
	global_load_dword v145, v[132:133], off offset:2060 sc1
	global_load_dword v146, v[132:133], off offset:2064 sc1
	global_load_dword v147, v[132:133], off offset:2068 sc1
	global_load_dword v148, v[132:133], off offset:2072 sc1
	global_load_dword v149, v[132:133], off offset:2076 sc1
	s_nop 0
	global_load_dwordx4 v[130:133], v[134:135], off offset:16
	s_nop 0
	global_load_dwordx4 v[134:137], v[134:135], off
	s_nop 0
	global_load_dwordx4 v[138:141], v150, s[36:37]
	s_waitcnt vmcnt(0)
	v_lshlrev_b32_e32 v151, 16, v138
	v_fmac_f32_e32 v151, v134, v142
	v_and_b32_e32 v134, 0xffff0000, v138
	v_fmac_f32_e32 v134, v135, v143
	v_lshlrev_b32_e32 v135, 16, v139
	v_fmac_f32_e32 v135, v136, v144
	v_and_b32_e32 v136, 0xffff0000, v139
	v_fmac_f32_e32 v136, v137, v145
	v_cvt_pk_bf16_f32 v134, v151, v134
	v_cvt_pk_bf16_f32 v135, v135, v136
	v_lshlrev_b32_e32 v136, 16, v140
	v_fmac_f32_e32 v136, v130, v146
	v_and_b32_e32 v130, 0xffff0000, v140
	v_fmac_f32_e32 v130, v131, v147
	v_cvt_pk_bf16_f32 v136, v136, v130
	v_lshlrev_b32_e32 v130, 16, v141
	v_and_b32_e32 v131, 0xffff0000, v141
	v_fmac_f32_e32 v130, v132, v148
	v_fmac_f32_e32 v131, v133, v149
	v_cvt_pk_bf16_f32 v137, v130, v131
	global_store_dwordx4 v150, v[134:137], s[36:37] sc1

.LBB0_803:
	v_lshlrev_b32_e32 v130, 3, v210
	s_mul_hi_i32 s3, s2, 0xc00
	s_mulk_i32 s2, 0xc00
	v_and_b32_e32 v130, 0xf8, v130
	s_add_u32 s2, s60, s2
	s_addc_u32 s3, s61, s3
	v_lshlrev_b32_e32 v131, 2, v130
	global_load_dword v149, v131, s[2:3] sc1
	global_load_dword v150, v131, s[2:3] offset:1024 sc1
	global_load_dword v151, v131, s[2:3] offset:4 sc1
	global_load_dword v152, v131, s[2:3] offset:1028 sc1
	global_load_dword v153, v131, s[2:3] offset:8 sc1
	global_load_dword v154, v131, s[2:3] offset:1032 sc1
	global_load_dword v155, v131, s[2:3] offset:12 sc1
	global_load_dword v156, v131, s[2:3] offset:1036 sc1
	global_load_dword v157, v131, s[2:3] offset:16 sc1
	global_load_dword v158, v131, s[2:3] offset:1040 sc1
	global_load_dword v159, v131, s[2:3] offset:20 sc1
	global_load_dword v160, v131, s[2:3] offset:1044 sc1
	global_load_dword v161, v131, s[2:3] offset:24 sc1
	global_load_dword v162, v131, s[2:3] offset:1048 sc1
	global_load_dword v163, v131, s[2:3] offset:28 sc1
	global_load_dword v164, v131, s[2:3] offset:1052 sc1
	s_lshl_b32 s2, s1, 8
	v_or_b32_e32 v146, s2, v130
	v_cmp_gt_u32_e32 vcc, 32, v210
	v_ashrrev_i32_e32 v147, 31, v146
	v_readlane_b32 s6, v255, 34
	v_cndmask_b32_e32 v188, v206, v207, vcc
	v_lshl_add_u64 v[130:131], s[38:39], 0, v[188:189]
	v_lshlrev_b64 v[138:139], 2, v[146:147]
	v_readlane_b32 s7, v255, 35
	v_lshl_add_u64 v[134:135], v[130:131], 0, v[138:139]
	global_load_dwordx4 v[130:133], v[134:135], off offset:16
	s_nop 0
	global_load_dwordx4 v[134:137], v[134:135], off
	v_lshl_add_u64 v[142:143], s[6:7], 0, v[138:139]
	global_load_dwordx4 v[138:141], v[142:143], off offset:16
	s_nop 0
	global_load_dwordx4 v[142:145], v[142:143], off
	v_ashrrev_i32_e32 v148, 5, v210
	s_lshl_b32 s3, s0, 8
	s_waitcnt vmcnt(0)
	v_mul_f32_e32 v142, v142, v150
	v_cndmask_b32_e64 v142, v142, 0, vcc
	v_fmac_f32_e32 v142, v134, v149
	v_mul_f32_e32 v134, v143, v152
	v_cndmask_b32_e64 v134, v134, 0, vcc
	v_fmac_f32_e32 v134, v135, v151
	v_mul_f32_e32 v135, v144, v154
	v_cndmask_b32_e64 v135, v135, 0, vcc
	v_fmac_f32_e32 v135, v136, v153
	v_mul_f32_e32 v136, v145, v156
	v_cndmask_b32_e64 v136, v136, 0, vcc
	v_fmac_f32_e32 v136, v137, v155
	v_mul_f32_e32 v137, v138, v158
	v_cndmask_b32_e64 v137, v137, 0, vcc
	v_fmac_f32_e32 v137, v130, v157
	v_mul_f32_e32 v130, v139, v160
	v_cndmask_b32_e64 v138, v130, 0, vcc
	v_mul_f32_e32 v130, v140, v162
	v_cndmask_b32_e64 v139, v130, 0, vcc
	v_mul_f32_e32 v130, v141, v164
	v_cndmask_b32_e64 v140, v130, 0, vcc
	v_add_u32_e32 v130, s3, v148
	v_add_u32_e32 v130, 0xfe, v130
	v_fmac_f32_e32 v138, v131, v159
	v_lshlrev_b32_e32 v131, 4, v130
	v_fmac_f32_e32 v139, v132, v161
	v_fmac_f32_e32 v140, v133, v163
	v_and_b32_e32 v132, 48, v131
	v_lshrrev_b32_e32 v133, 2, v130
	v_and_or_b32 v132, v130, 64, v132
	v_and_b32_e32 v133, 0x3ffe0, v133
	v_lshrrev_b32_e32 v141, 6, v146
	v_add_lshl_u32 v133, v133, v141, 14
	v_lshrrev_b32_e32 v132, 3, v132
	v_lshrrev_b32_e32 v141, 2, v210
	v_and_or_b32 v132, v141, 1, v132
	v_lshlrev_b32_e32 v141, 4, v210
	v_and_b32_e32 v131, 0x3c0, v131
	v_and_b32_e32 v141, 48, v141
	v_and_b32_e32 v130, 32, v130
	v_lshlrev_b32_e32 v132, 10, v132
	v_bitop3_b32 v130, v131, v130, v141 bitop3:0x36
	v_or3_b32 v141, v130, v132, v133
	global_load_dwordx4 v[130:133], v141, s[36:37]
	s_waitcnt vmcnt(0)
	v_lshlrev_b32_e32 v143, 16, v130
	v_and_b32_e32 v130, 0xffff0000, v130
	v_add_f32_e32 v130, v134, v130
	v_lshlrev_b32_e32 v134, 16, v131
	v_and_b32_e32 v131, 0xffff0000, v131
	v_add_f32_e32 v134, v135, v134
	v_add_f32_e32 v131, v136, v131
	v_add_f32_e32 v142, v142, v143
	v_cvt_pk_bf16_f32 v130, v142, v130
	v_cvt_pk_bf16_f32 v131, v134, v131
	v_lshlrev_b32_e32 v134, 16, v132
	v_and_b32_e32 v132, 0xffff0000, v132
	v_add_f32_e32 v134, v137, v134
	v_add_f32_e32 v132, v138, v132
	v_cvt_pk_bf16_f32 v132, v134, v132
	v_lshlrev_b32_e32 v134, 16, v133
	v_and_b32_e32 v133, 0xffff0000, v133
	v_add_f32_e32 v133, v140, v133
	v_add_f32_e32 v134, v139, v134
	v_cvt_pk_bf16_f32 v133, v134, v133
	global_store_dwordx4 v141, v[130:133], s[36:37] sc1
.LBB0_804:
	s_add_i32 s0, s3, s16
	s_nop 0
	v_add_u32_e32 v130, s0, v209
	s_add_i32 s0, s2, s17
	v_ashrrev_i32_e32 v131, 31, v130
	v_lshl_add_u32 v132, v208, 3, s0
	v_lshlrev_b64 v[130:131], 12, v[130:131]
	v_ashrrev_i32_e32 v133, 31, v132
	v_lshl_add_u64 v[130:131], s[52:53], 0, v[130:131]
	v_lshl_add_u64 v[130:131], v[132:133], 1, v[130:131]
	v_mul_f32_e32 v132, 0xbfb8aa3b, v126
	v_exp_f32_e32 v132, v132
	s_mov_b64 s[0:1], 0x10000
	v_add_f32_e32 v132, 1.0, v132
	v_rcp_f32_e32 v132, v132
	s_nop 0
	v_mul_f32_e32 v126, v126, v132
	v_mul_f32_e32 v132, 0xbfb8aa3b, v122
	v_exp_f32_e32 v132, v132
	s_nop 0
	v_add_f32_e32 v132, 1.0, v132
	v_rcp_f32_e32 v132, v132
	s_nop 0
	v_mul_f32_e32 v132, v122, v132
	v_mul_f32_e32 v122, 0xbfb8aa3b, v127
	v_exp_f32_e32 v122, v122
	s_nop 0
	v_add_f32_e32 v122, 1.0, v122
	v_rcp_f32_e32 v122, v122
	s_nop 0
	v_mul_f32_e32 v122, v127, v122
	v_mul_f32_e32 v127, 0xbfb8aa3b, v123
	v_exp_f32_e32 v127, v127
	v_cvt_pk_bf16_f32 v122, v126, v122
	s_nop 0
	v_add_f32_e32 v127, 1.0, v127
	v_rcp_f32_e32 v127, v127
	s_nop 0
	v_mul_f32_e32 v127, v123, v127
	v_mul_f32_e32 v123, 0xbfb8aa3b, v128
	v_exp_f32_e32 v123, v123
	s_nop 0
	v_add_f32_e32 v123, 1.0, v123
	v_rcp_f32_e32 v123, v123
	s_nop 0
	v_mul_f32_e32 v123, v128, v123
	v_mul_f32_e32 v128, 0xbfb8aa3b, v124
	v_exp_f32_e32 v128, v128
	s_nop 0
	v_add_f32_e32 v128, 1.0, v128
	v_rcp_f32_e32 v128, v128
	s_nop 0
	v_mul_f32_e32 v128, v124, v128
	v_mul_f32_e32 v124, 0xbfb8aa3b, v129
	v_exp_f32_e32 v124, v124
	s_nop 0
	v_add_f32_e32 v124, 1.0, v124
	v_rcp_f32_e32 v124, v124
	s_nop 0
	v_mul_f32_e32 v124, v129, v124
	v_mul_f32_e32 v129, 0xbfb8aa3b, v125
	v_exp_f32_e32 v129, v129
	v_cvt_pk_bf16_f32 v123, v123, v124
	v_cvt_pk_bf16_f32 v124, v132, v127
	s_nop 0
	v_add_f32_e32 v129, 1.0, v129
	v_rcp_f32_e32 v129, v129
	s_nop 0
	v_mul_f32_e32 v125, v125, v129
	v_cvt_pk_bf16_f32 v125, v128, v125
	global_store_dwordx4 v[130:131], v[122:125], off sc1
	s_nop 1
	v_mul_f32_e32 v122, 0xbfb8aa3b, v118
	v_exp_f32_e32 v122, v122
	s_nop 0
	v_add_f32_e32 v122, 1.0, v122
	v_rcp_f32_e32 v122, v122
	s_nop 0
	v_mul_f32_e32 v118, v118, v122
	v_mul_f32_e32 v122, 0xbfb8aa3b, v114
	v_exp_f32_e32 v122, v122
	s_nop 0
	v_add_f32_e32 v122, 1.0, v122
	v_rcp_f32_e32 v122, v122
	s_nop 0
	v_mul_f32_e32 v122, v114, v122
	v_mul_f32_e32 v114, 0xbfb8aa3b, v119
	v_exp_f32_e32 v114, v114
	s_nop 0
	v_add_f32_e32 v114, 1.0, v114
	v_rcp_f32_e32 v114, v114
	s_nop 0
	v_mul_f32_e32 v114, v119, v114
	v_mul_f32_e32 v119, 0xbfb8aa3b, v115
	v_exp_f32_e32 v119, v119
	v_cvt_pk_bf16_f32 v114, v118, v114
	s_nop 0
	v_add_f32_e32 v119, 1.0, v119
	v_rcp_f32_e32 v119, v119
	s_nop 0
	v_mul_f32_e32 v119, v115, v119
	v_mul_f32_e32 v115, 0xbfb8aa3b, v120
	v_exp_f32_e32 v115, v115
	s_nop 0
	v_add_f32_e32 v115, 1.0, v115
	v_rcp_f32_e32 v115, v115
	s_nop 0
	v_mul_f32_e32 v115, v120, v115
	v_mul_f32_e32 v120, 0xbfb8aa3b, v116
	v_exp_f32_e32 v120, v120
	s_nop 0
	v_add_f32_e32 v120, 1.0, v120
	v_rcp_f32_e32 v120, v120
	s_nop 0
	v_mul_f32_e32 v120, v116, v120
	v_mul_f32_e32 v116, 0xbfb8aa3b, v121
	v_exp_f32_e32 v116, v116
	s_nop 0
	v_add_f32_e32 v116, 1.0, v116
	v_rcp_f32_e32 v116, v116
	s_nop 0
	v_mul_f32_e32 v116, v121, v116
	v_mul_f32_e32 v121, 0xbfb8aa3b, v117
	v_exp_f32_e32 v121, v121
	v_cvt_pk_bf16_f32 v115, v115, v116
	v_cvt_pk_bf16_f32 v116, v122, v119
	s_nop 0
	v_add_f32_e32 v121, 1.0, v121
	v_rcp_f32_e32 v121, v121
	s_nop 0
	v_mul_f32_e32 v117, v117, v121
	v_cvt_pk_bf16_f32 v117, v120, v117
	global_store_dwordx4 v[130:131], v[114:117], off offset:256 sc1
	s_nop 1
	v_mul_f32_e32 v116, 0xbfb8aa3b, v110
	v_exp_f32_e32 v116, v116
	v_lshl_add_u64 v[114:115], v[130:131], 0, s[0:1]
	s_mov_b32 s0, 0x10000
	v_add_f32_e32 v116, 1.0, v116
	v_rcp_f32_e32 v116, v116
	s_nop 0
	v_mul_f32_e32 v110, v110, v116
	v_mul_f32_e32 v116, 0xbfb8aa3b, v106
	v_exp_f32_e32 v116, v116
	s_nop 0
	v_add_f32_e32 v116, 1.0, v116
	v_rcp_f32_e32 v116, v116
	s_nop 0
	v_mul_f32_e32 v116, v106, v116
	v_mul_f32_e32 v106, 0xbfb8aa3b, v111
	v_exp_f32_e32 v106, v106
	s_nop 0
	v_add_f32_e32 v106, 1.0, v106
	v_rcp_f32_e32 v106, v106
	s_nop 0
	v_mul_f32_e32 v106, v111, v106
	v_mul_f32_e32 v111, 0xbfb8aa3b, v107
	v_exp_f32_e32 v111, v111
	v_cvt_pk_bf16_f32 v106, v110, v106
	v_add_co_u32_e32 v110, vcc, s0, v130
	v_add_f32_e32 v111, 1.0, v111
	v_rcp_f32_e32 v111, v111
	s_mov_b64 s[0:1], 0x20000
	v_mul_f32_e32 v111, v107, v111
	v_mul_f32_e32 v107, 0xbfb8aa3b, v112
	v_exp_f32_e32 v107, v107
	s_nop 0
	v_add_f32_e32 v107, 1.0, v107
	v_rcp_f32_e32 v107, v107
	s_nop 0
	v_mul_f32_e32 v107, v112, v107
	v_mul_f32_e32 v112, 0xbfb8aa3b, v108
	v_exp_f32_e32 v112, v112
	s_nop 0
	v_add_f32_e32 v112, 1.0, v112
	v_rcp_f32_e32 v112, v112
	s_nop 0
	v_mul_f32_e32 v112, v108, v112
	v_mul_f32_e32 v108, 0xbfb8aa3b, v113
	v_exp_f32_e32 v108, v108
	s_nop 0
	v_add_f32_e32 v108, 1.0, v108
	v_rcp_f32_e32 v108, v108
	s_nop 0
	v_mul_f32_e32 v108, v113, v108
	v_mul_f32_e32 v113, 0xbfb8aa3b, v109
	v_exp_f32_e32 v113, v113
	v_cvt_pk_bf16_f32 v107, v107, v108
	v_cvt_pk_bf16_f32 v108, v116, v111
	v_addc_co_u32_e32 v111, vcc, 0, v131, vcc
	v_add_f32_e32 v113, 1.0, v113
	v_rcp_f32_e32 v113, v113
	s_nop 0
	v_mul_f32_e32 v109, v109, v113
	v_cvt_pk_bf16_f32 v109, v112, v109
	global_store_dwordx4 v[110:111], v[106:109], off sc1
	s_nop 1
	v_mul_f32_e32 v106, 0xbfb8aa3b, v102
	v_exp_f32_e32 v106, v106
	s_nop 0
	v_add_f32_e32 v106, 1.0, v106
	v_rcp_f32_e32 v106, v106
	s_nop 0
	v_mul_f32_e32 v102, v102, v106
	v_mul_f32_e32 v106, 0xbfb8aa3b, v98
	v_exp_f32_e32 v106, v106
	s_nop 0
	v_add_f32_e32 v106, 1.0, v106
	v_rcp_f32_e32 v106, v106
	s_nop 0
	v_mul_f32_e32 v106, v98, v106
	v_mul_f32_e32 v98, 0xbfb8aa3b, v103
	v_exp_f32_e32 v98, v98
	s_nop 0
	v_add_f32_e32 v98, 1.0, v98
	v_rcp_f32_e32 v98, v98
	s_nop 0
	v_mul_f32_e32 v98, v103, v98
	v_mul_f32_e32 v103, 0xbfb8aa3b, v99
	v_exp_f32_e32 v103, v103
	v_cvt_pk_bf16_f32 v98, v102, v98
	s_nop 0
	v_add_f32_e32 v103, 1.0, v103
	v_rcp_f32_e32 v103, v103
	s_nop 0
	v_mul_f32_e32 v103, v99, v103
	v_mul_f32_e32 v99, 0xbfb8aa3b, v104
	v_exp_f32_e32 v99, v99
	s_nop 0
	v_add_f32_e32 v99, 1.0, v99
	v_rcp_f32_e32 v99, v99
	s_nop 0
	v_mul_f32_e32 v99, v104, v99
	v_mul_f32_e32 v104, 0xbfb8aa3b, v100
	v_exp_f32_e32 v104, v104
	s_nop 0
	v_add_f32_e32 v104, 1.0, v104
	v_rcp_f32_e32 v104, v104
	s_nop 0
	v_mul_f32_e32 v104, v100, v104
	v_mul_f32_e32 v100, 0xbfb8aa3b, v105
	v_exp_f32_e32 v100, v100
	s_nop 0
	v_add_f32_e32 v100, 1.0, v100
	v_rcp_f32_e32 v100, v100
	s_nop 0
	v_mul_f32_e32 v100, v105, v100
	v_mul_f32_e32 v105, 0xbfb8aa3b, v101
	v_exp_f32_e32 v105, v105
	v_cvt_pk_bf16_f32 v99, v99, v100
	v_cvt_pk_bf16_f32 v100, v106, v103
	s_nop 0
	v_add_f32_e32 v105, 1.0, v105
	v_rcp_f32_e32 v105, v105
	s_nop 0
	v_mul_f32_e32 v101, v101, v105
	v_cvt_pk_bf16_f32 v101, v104, v101
	global_store_dwordx4 v[114:115], v[98:101], off offset:256 sc1
	s_nop 1
	v_mul_f32_e32 v100, 0xbfb8aa3b, v94
	v_exp_f32_e32 v100, v100
	v_lshl_add_u64 v[98:99], v[130:131], 0, s[0:1]
	s_mov_b32 s0, 0x20000
	v_add_f32_e32 v100, 1.0, v100
	v_rcp_f32_e32 v100, v100
	s_nop 0
	v_mul_f32_e32 v94, v94, v100
	v_mul_f32_e32 v100, 0xbfb8aa3b, v90
	v_exp_f32_e32 v100, v100
	s_nop 0
	v_add_f32_e32 v100, 1.0, v100
	v_rcp_f32_e32 v100, v100
	s_nop 0
	v_mul_f32_e32 v100, v90, v100
	v_mul_f32_e32 v90, 0xbfb8aa3b, v95
	v_exp_f32_e32 v90, v90
	s_nop 0
	v_add_f32_e32 v90, 1.0, v90
	v_rcp_f32_e32 v90, v90
	s_nop 0
	v_mul_f32_e32 v90, v95, v90
	v_mul_f32_e32 v95, 0xbfb8aa3b, v91
	v_exp_f32_e32 v95, v95
	v_cvt_pk_bf16_f32 v90, v94, v90
	v_add_co_u32_e32 v94, vcc, s0, v130
	v_add_f32_e32 v95, 1.0, v95
	v_rcp_f32_e32 v95, v95
	s_mov_b64 s[0:1], 0x30000
	v_mul_f32_e32 v95, v91, v95
	v_mul_f32_e32 v91, 0xbfb8aa3b, v96
	v_exp_f32_e32 v91, v91
	s_nop 0
	v_add_f32_e32 v91, 1.0, v91
	v_rcp_f32_e32 v91, v91
	s_nop 0
	v_mul_f32_e32 v91, v96, v91
	v_mul_f32_e32 v96, 0xbfb8aa3b, v92
	v_exp_f32_e32 v96, v96
	s_nop 0
	v_add_f32_e32 v96, 1.0, v96
	v_rcp_f32_e32 v96, v96
	s_nop 0
	v_mul_f32_e32 v96, v92, v96
	v_mul_f32_e32 v92, 0xbfb8aa3b, v97
	v_exp_f32_e32 v92, v92
	s_nop 0
	v_add_f32_e32 v92, 1.0, v92
	v_rcp_f32_e32 v92, v92
	s_nop 0
	v_mul_f32_e32 v92, v97, v92
	v_mul_f32_e32 v97, 0xbfb8aa3b, v93
	v_exp_f32_e32 v97, v97
	v_cvt_pk_bf16_f32 v91, v91, v92
	v_cvt_pk_bf16_f32 v92, v100, v95
	v_addc_co_u32_e32 v95, vcc, 0, v131, vcc
	v_add_f32_e32 v97, 1.0, v97
	v_rcp_f32_e32 v97, v97
	s_nop 0
	v_mul_f32_e32 v93, v93, v97
	v_cvt_pk_bf16_f32 v93, v96, v93
	global_store_dwordx4 v[94:95], v[90:93], off sc1
	s_nop 1
	v_mul_f32_e32 v90, 0xbfb8aa3b, v86
	v_exp_f32_e32 v90, v90
	s_nop 0
	v_add_f32_e32 v90, 1.0, v90
	v_rcp_f32_e32 v90, v90
	s_nop 0
	v_mul_f32_e32 v86, v86, v90
	v_mul_f32_e32 v90, 0xbfb8aa3b, v82
	v_exp_f32_e32 v90, v90
	s_nop 0
	v_add_f32_e32 v90, 1.0, v90
	v_rcp_f32_e32 v90, v90
	s_nop 0
	v_mul_f32_e32 v90, v82, v90
	v_mul_f32_e32 v82, 0xbfb8aa3b, v87
	v_exp_f32_e32 v82, v82
	s_nop 0
	v_add_f32_e32 v82, 1.0, v82
	v_rcp_f32_e32 v82, v82
	s_nop 0
	v_mul_f32_e32 v82, v87, v82
	v_mul_f32_e32 v87, 0xbfb8aa3b, v83
	v_exp_f32_e32 v87, v87
	v_cvt_pk_bf16_f32 v82, v86, v82
	s_nop 0
	v_add_f32_e32 v87, 1.0, v87
	v_rcp_f32_e32 v87, v87
	s_nop 0
	v_mul_f32_e32 v87, v83, v87
	v_mul_f32_e32 v83, 0xbfb8aa3b, v88
	v_exp_f32_e32 v83, v83
	s_nop 0
	v_add_f32_e32 v83, 1.0, v83
	v_rcp_f32_e32 v83, v83
	s_nop 0
	v_mul_f32_e32 v83, v88, v83
	v_mul_f32_e32 v88, 0xbfb8aa3b, v84
	v_exp_f32_e32 v88, v88
	s_nop 0
	v_add_f32_e32 v88, 1.0, v88
	v_rcp_f32_e32 v88, v88
	s_nop 0
	v_mul_f32_e32 v88, v84, v88
	v_mul_f32_e32 v84, 0xbfb8aa3b, v89
	v_exp_f32_e32 v84, v84
	s_nop 0
	v_add_f32_e32 v84, 1.0, v84
	v_rcp_f32_e32 v84, v84
	s_nop 0
	v_mul_f32_e32 v84, v89, v84
	v_mul_f32_e32 v89, 0xbfb8aa3b, v85
	v_exp_f32_e32 v89, v89
	v_cvt_pk_bf16_f32 v83, v83, v84
	v_cvt_pk_bf16_f32 v84, v90, v87
	s_nop 0
	v_add_f32_e32 v89, 1.0, v89
	v_rcp_f32_e32 v89, v89
	s_nop 0
	v_mul_f32_e32 v85, v85, v89
	v_cvt_pk_bf16_f32 v85, v88, v85
	global_store_dwordx4 v[98:99], v[82:85], off offset:256 sc1
	s_nop 1
	v_mul_f32_e32 v84, 0xbfb8aa3b, v78
	v_exp_f32_e32 v84, v84
	v_lshl_add_u64 v[82:83], v[130:131], 0, s[0:1]
	s_mov_b32 s0, 0x30000
	v_add_f32_e32 v84, 1.0, v84
	v_rcp_f32_e32 v84, v84
	s_nop 0
	v_mul_f32_e32 v78, v78, v84
	v_mul_f32_e32 v84, 0xbfb8aa3b, v74
	v_exp_f32_e32 v84, v84
	s_nop 0
	v_add_f32_e32 v84, 1.0, v84
	v_rcp_f32_e32 v84, v84
	s_nop 0
	v_mul_f32_e32 v84, v74, v84
	v_mul_f32_e32 v74, 0xbfb8aa3b, v79
	v_exp_f32_e32 v74, v74
	s_nop 0
	v_add_f32_e32 v74, 1.0, v74
	v_rcp_f32_e32 v74, v74
	s_nop 0
	v_mul_f32_e32 v74, v79, v74
	v_mul_f32_e32 v79, 0xbfb8aa3b, v75
	v_exp_f32_e32 v79, v79
	v_cvt_pk_bf16_f32 v74, v78, v74
	v_add_co_u32_e32 v78, vcc, s0, v130
	v_add_f32_e32 v79, 1.0, v79
	v_rcp_f32_e32 v79, v79
	s_mov_b64 s[0:1], 0x80000
	v_mul_f32_e32 v79, v75, v79
	v_mul_f32_e32 v75, 0xbfb8aa3b, v80
	v_exp_f32_e32 v75, v75
	s_nop 0
	v_add_f32_e32 v75, 1.0, v75
	v_rcp_f32_e32 v75, v75
	s_nop 0
	v_mul_f32_e32 v75, v80, v75
	v_mul_f32_e32 v80, 0xbfb8aa3b, v76
	v_exp_f32_e32 v80, v80
	s_nop 0
	v_add_f32_e32 v80, 1.0, v80
	v_rcp_f32_e32 v80, v80
	s_nop 0
	v_mul_f32_e32 v80, v76, v80
	v_mul_f32_e32 v76, 0xbfb8aa3b, v81
	v_exp_f32_e32 v76, v76
	s_nop 0
	v_add_f32_e32 v76, 1.0, v76
	v_rcp_f32_e32 v76, v76
	s_nop 0
	v_mul_f32_e32 v76, v81, v76
	v_mul_f32_e32 v81, 0xbfb8aa3b, v77
	v_exp_f32_e32 v81, v81
	v_cvt_pk_bf16_f32 v75, v75, v76
	v_cvt_pk_bf16_f32 v76, v84, v79
	v_addc_co_u32_e32 v79, vcc, 0, v131, vcc
	v_add_f32_e32 v81, 1.0, v81
	v_rcp_f32_e32 v81, v81
	s_nop 0
	v_mul_f32_e32 v77, v77, v81
	v_cvt_pk_bf16_f32 v77, v80, v77
	global_store_dwordx4 v[78:79], v[74:77], off sc1
	s_nop 1
	v_mul_f32_e32 v74, 0xbfb8aa3b, v70
	v_exp_f32_e32 v74, v74
	s_nop 0
	v_add_f32_e32 v74, 1.0, v74
	v_rcp_f32_e32 v74, v74
	s_nop 0
	v_mul_f32_e32 v70, v70, v74
	v_mul_f32_e32 v74, 0xbfb8aa3b, v66
	v_exp_f32_e32 v74, v74
	s_nop 0
	v_add_f32_e32 v74, 1.0, v74
	v_rcp_f32_e32 v74, v74
	s_nop 0
	v_mul_f32_e32 v74, v66, v74
	v_mul_f32_e32 v66, 0xbfb8aa3b, v71
	v_exp_f32_e32 v66, v66
	s_nop 0
	v_add_f32_e32 v66, 1.0, v66
	v_rcp_f32_e32 v66, v66
	s_nop 0
	v_mul_f32_e32 v66, v71, v66
	v_mul_f32_e32 v71, 0xbfb8aa3b, v67
	v_exp_f32_e32 v71, v71
	v_cvt_pk_bf16_f32 v66, v70, v66
	s_nop 0
	v_add_f32_e32 v71, 1.0, v71
	v_rcp_f32_e32 v71, v71
	s_nop 0
	v_mul_f32_e32 v71, v67, v71
	v_mul_f32_e32 v67, 0xbfb8aa3b, v72
	v_exp_f32_e32 v67, v67
	s_nop 0
	v_add_f32_e32 v67, 1.0, v67
	v_rcp_f32_e32 v67, v67
	s_nop 0
	v_mul_f32_e32 v67, v72, v67
	v_mul_f32_e32 v72, 0xbfb8aa3b, v68
	v_exp_f32_e32 v72, v72
	s_nop 0
	v_add_f32_e32 v72, 1.0, v72
	v_rcp_f32_e32 v72, v72
	s_nop 0
	v_mul_f32_e32 v72, v68, v72
	v_mul_f32_e32 v68, 0xbfb8aa3b, v73
	v_exp_f32_e32 v68, v68
	s_nop 0
	v_add_f32_e32 v68, 1.0, v68
	v_rcp_f32_e32 v68, v68
	s_nop 0
	v_mul_f32_e32 v68, v73, v68
	v_mul_f32_e32 v73, 0xbfb8aa3b, v69
	v_exp_f32_e32 v73, v73
	v_cvt_pk_bf16_f32 v67, v67, v68
	v_cvt_pk_bf16_f32 v68, v74, v71
	s_nop 0
	v_add_f32_e32 v73, 1.0, v73
	v_rcp_f32_e32 v73, v73
	s_nop 0
	v_mul_f32_e32 v69, v69, v73
	v_cvt_pk_bf16_f32 v69, v72, v69
	global_store_dwordx4 v[82:83], v[66:69], off offset:256 sc1
	s_nop 1
	v_mul_f32_e32 v68, 0xbfb8aa3b, v62
	v_exp_f32_e32 v68, v68
	v_lshl_add_u64 v[66:67], v[130:131], 0, s[0:1]
	s_mov_b32 s0, 0x80000
	v_add_f32_e32 v68, 1.0, v68
	v_rcp_f32_e32 v68, v68
	s_nop 0
	v_mul_f32_e32 v62, v62, v68
	v_mul_f32_e32 v68, 0xbfb8aa3b, v58
	v_exp_f32_e32 v68, v68
	s_nop 0
	v_add_f32_e32 v68, 1.0, v68
	v_rcp_f32_e32 v68, v68
	s_nop 0
	v_mul_f32_e32 v68, v58, v68
	v_mul_f32_e32 v58, 0xbfb8aa3b, v63
	v_exp_f32_e32 v58, v58
	s_nop 0
	v_add_f32_e32 v58, 1.0, v58
	v_rcp_f32_e32 v58, v58
	s_nop 0
	v_mul_f32_e32 v58, v63, v58
	v_mul_f32_e32 v63, 0xbfb8aa3b, v59
	v_exp_f32_e32 v63, v63
	v_cvt_pk_bf16_f32 v58, v62, v58
	v_add_co_u32_e32 v62, vcc, s0, v130
	v_add_f32_e32 v63, 1.0, v63
	v_rcp_f32_e32 v63, v63
	s_mov_b64 s[0:1], 0x90000
	v_mul_f32_e32 v63, v59, v63
	v_mul_f32_e32 v59, 0xbfb8aa3b, v64
	v_exp_f32_e32 v59, v59
	s_nop 0
	v_add_f32_e32 v59, 1.0, v59
	v_rcp_f32_e32 v59, v59
	s_nop 0
	v_mul_f32_e32 v59, v64, v59
	v_mul_f32_e32 v64, 0xbfb8aa3b, v60
	v_exp_f32_e32 v64, v64
	s_nop 0
	v_add_f32_e32 v64, 1.0, v64
	v_rcp_f32_e32 v64, v64
	s_nop 0
	v_mul_f32_e32 v64, v60, v64
	v_mul_f32_e32 v60, 0xbfb8aa3b, v65
	v_exp_f32_e32 v60, v60
	s_nop 0
	v_add_f32_e32 v60, 1.0, v60
	v_rcp_f32_e32 v60, v60
	s_nop 0
	v_mul_f32_e32 v60, v65, v60
	v_mul_f32_e32 v65, 0xbfb8aa3b, v61
	v_exp_f32_e32 v65, v65
	v_cvt_pk_bf16_f32 v59, v59, v60
	v_cvt_pk_bf16_f32 v60, v68, v63
	v_addc_co_u32_e32 v63, vcc, 0, v131, vcc
	v_add_f32_e32 v65, 1.0, v65
	v_rcp_f32_e32 v65, v65
	s_nop 0
	v_mul_f32_e32 v61, v61, v65
	v_cvt_pk_bf16_f32 v61, v64, v61
	global_store_dwordx4 v[62:63], v[58:61], off sc1
	s_nop 1
	v_mul_f32_e32 v58, 0xbfb8aa3b, v54
	v_exp_f32_e32 v58, v58
	s_nop 0
	v_add_f32_e32 v58, 1.0, v58
	v_rcp_f32_e32 v58, v58
	s_nop 0
	v_mul_f32_e32 v54, v54, v58
	v_mul_f32_e32 v58, 0xbfb8aa3b, v50
	v_exp_f32_e32 v58, v58
	s_nop 0
	v_add_f32_e32 v58, 1.0, v58
	v_rcp_f32_e32 v58, v58
	s_nop 0
	v_mul_f32_e32 v58, v50, v58
	v_mul_f32_e32 v50, 0xbfb8aa3b, v55
	v_exp_f32_e32 v50, v50
	s_nop 0
	v_add_f32_e32 v50, 1.0, v50
	v_rcp_f32_e32 v50, v50
	s_nop 0
	v_mul_f32_e32 v50, v55, v50
	v_mul_f32_e32 v55, 0xbfb8aa3b, v51
	v_exp_f32_e32 v55, v55
	v_cvt_pk_bf16_f32 v50, v54, v50
	s_nop 0
	v_add_f32_e32 v55, 1.0, v55
	v_rcp_f32_e32 v55, v55
	s_nop 0
	v_mul_f32_e32 v55, v51, v55
	v_mul_f32_e32 v51, 0xbfb8aa3b, v56
	v_exp_f32_e32 v51, v51
	s_nop 0
	v_add_f32_e32 v51, 1.0, v51
	v_rcp_f32_e32 v51, v51
	s_nop 0
	v_mul_f32_e32 v51, v56, v51
	v_mul_f32_e32 v56, 0xbfb8aa3b, v52
	v_exp_f32_e32 v56, v56
	s_nop 0
	v_add_f32_e32 v56, 1.0, v56
	v_rcp_f32_e32 v56, v56
	s_nop 0
	v_mul_f32_e32 v56, v52, v56
	v_mul_f32_e32 v52, 0xbfb8aa3b, v57
	v_exp_f32_e32 v52, v52
	s_nop 0
	v_add_f32_e32 v52, 1.0, v52
	v_rcp_f32_e32 v52, v52
	s_nop 0
	v_mul_f32_e32 v52, v57, v52
	v_mul_f32_e32 v57, 0xbfb8aa3b, v53
	v_exp_f32_e32 v57, v57
	v_cvt_pk_bf16_f32 v51, v51, v52
	v_cvt_pk_bf16_f32 v52, v58, v55
	s_nop 0
	v_add_f32_e32 v57, 1.0, v57
	v_rcp_f32_e32 v57, v57
	s_nop 0
	v_mul_f32_e32 v53, v53, v57
	v_cvt_pk_bf16_f32 v53, v56, v53
	global_store_dwordx4 v[66:67], v[50:53], off offset:256 sc1
	s_nop 1
	v_mul_f32_e32 v52, 0xbfb8aa3b, v46
	v_exp_f32_e32 v52, v52
	v_lshl_add_u64 v[50:51], v[130:131], 0, s[0:1]
	s_mov_b32 s0, 0x90000
	v_add_f32_e32 v52, 1.0, v52
	v_rcp_f32_e32 v52, v52
	s_nop 0
	v_mul_f32_e32 v46, v46, v52
	v_mul_f32_e32 v52, 0xbfb8aa3b, v42
	v_exp_f32_e32 v52, v52
	s_nop 0
	v_add_f32_e32 v52, 1.0, v52
	v_rcp_f32_e32 v52, v52
	s_nop 0
	v_mul_f32_e32 v52, v42, v52
	v_mul_f32_e32 v42, 0xbfb8aa3b, v47
	v_exp_f32_e32 v42, v42
	s_nop 0
	v_add_f32_e32 v42, 1.0, v42
	v_rcp_f32_e32 v42, v42
	s_nop 0
	v_mul_f32_e32 v42, v47, v42
	v_mul_f32_e32 v47, 0xbfb8aa3b, v43
	v_exp_f32_e32 v47, v47
	v_cvt_pk_bf16_f32 v42, v46, v42
	v_add_co_u32_e32 v46, vcc, s0, v130
	v_add_f32_e32 v47, 1.0, v47
	v_rcp_f32_e32 v47, v47
	s_mov_b64 s[0:1], 0xa0000
	v_mul_f32_e32 v47, v43, v47
	v_mul_f32_e32 v43, 0xbfb8aa3b, v48
	v_exp_f32_e32 v43, v43
	s_nop 0
	v_add_f32_e32 v43, 1.0, v43
	v_rcp_f32_e32 v43, v43
	s_nop 0
	v_mul_f32_e32 v43, v48, v43
	v_mul_f32_e32 v48, 0xbfb8aa3b, v44
	v_exp_f32_e32 v48, v48
	s_nop 0
	v_add_f32_e32 v48, 1.0, v48
	v_rcp_f32_e32 v48, v48
	s_nop 0
	v_mul_f32_e32 v48, v44, v48
	v_mul_f32_e32 v44, 0xbfb8aa3b, v49
	v_exp_f32_e32 v44, v44
	s_nop 0
	v_add_f32_e32 v44, 1.0, v44
	v_rcp_f32_e32 v44, v44
	s_nop 0
	v_mul_f32_e32 v44, v49, v44
	v_mul_f32_e32 v49, 0xbfb8aa3b, v45
	v_exp_f32_e32 v49, v49
	v_cvt_pk_bf16_f32 v43, v43, v44
	v_cvt_pk_bf16_f32 v44, v52, v47
	v_addc_co_u32_e32 v47, vcc, 0, v131, vcc
	v_add_f32_e32 v49, 1.0, v49
	v_rcp_f32_e32 v49, v49
	s_nop 0
	v_mul_f32_e32 v45, v45, v49
	v_cvt_pk_bf16_f32 v45, v48, v45
	global_store_dwordx4 v[46:47], v[42:45], off sc1
	s_nop 1
	v_mul_f32_e32 v42, 0xbfb8aa3b, v38
	v_exp_f32_e32 v42, v42
	s_nop 0
	v_add_f32_e32 v42, 1.0, v42
	v_rcp_f32_e32 v42, v42
	s_nop 0
	v_mul_f32_e32 v38, v38, v42
	v_mul_f32_e32 v42, 0xbfb8aa3b, v34
	v_exp_f32_e32 v42, v42
	s_nop 0
	v_add_f32_e32 v42, 1.0, v42
	v_rcp_f32_e32 v42, v42
	s_nop 0
	v_mul_f32_e32 v42, v34, v42
	v_mul_f32_e32 v34, 0xbfb8aa3b, v39
	v_exp_f32_e32 v34, v34
	s_nop 0
	v_add_f32_e32 v34, 1.0, v34
	v_rcp_f32_e32 v34, v34
	s_nop 0
	v_mul_f32_e32 v34, v39, v34
	v_mul_f32_e32 v39, 0xbfb8aa3b, v35
	v_exp_f32_e32 v39, v39
	v_cvt_pk_bf16_f32 v34, v38, v34
	s_nop 0
	v_add_f32_e32 v39, 1.0, v39
	v_rcp_f32_e32 v39, v39
	s_nop 0
	v_mul_f32_e32 v39, v35, v39
	v_mul_f32_e32 v35, 0xbfb8aa3b, v40
	v_exp_f32_e32 v35, v35
	s_nop 0
	v_add_f32_e32 v35, 1.0, v35
	v_rcp_f32_e32 v35, v35
	s_nop 0
	v_mul_f32_e32 v35, v40, v35
	v_mul_f32_e32 v40, 0xbfb8aa3b, v36
	v_exp_f32_e32 v40, v40
	s_nop 0
	v_add_f32_e32 v40, 1.0, v40
	v_rcp_f32_e32 v40, v40
	s_nop 0
	v_mul_f32_e32 v40, v36, v40
	v_mul_f32_e32 v36, 0xbfb8aa3b, v41
	v_exp_f32_e32 v36, v36
	s_nop 0
	v_add_f32_e32 v36, 1.0, v36
	v_rcp_f32_e32 v36, v36
	s_nop 0
	v_mul_f32_e32 v36, v41, v36
	v_mul_f32_e32 v41, 0xbfb8aa3b, v37
	v_exp_f32_e32 v41, v41
	v_cvt_pk_bf16_f32 v35, v35, v36
	v_cvt_pk_bf16_f32 v36, v42, v39
	s_nop 0
	v_add_f32_e32 v41, 1.0, v41
	v_rcp_f32_e32 v41, v41
	s_nop 0
	v_mul_f32_e32 v37, v37, v41
	v_cvt_pk_bf16_f32 v37, v40, v37
	global_store_dwordx4 v[50:51], v[34:37], off offset:256 sc1
	s_nop 1
	v_mul_f32_e32 v36, 0xbfb8aa3b, v30
	v_exp_f32_e32 v36, v36
	v_lshl_add_u64 v[34:35], v[130:131], 0, s[0:1]
	s_mov_b32 s0, 0xa0000
	v_add_f32_e32 v36, 1.0, v36
	v_rcp_f32_e32 v36, v36
	s_nop 0
	v_mul_f32_e32 v30, v30, v36
	v_mul_f32_e32 v36, 0xbfb8aa3b, v26
	v_exp_f32_e32 v36, v36
	s_nop 0
	v_add_f32_e32 v36, 1.0, v36
	v_rcp_f32_e32 v36, v36
	s_nop 0
	v_mul_f32_e32 v36, v26, v36
	v_mul_f32_e32 v26, 0xbfb8aa3b, v31
	v_exp_f32_e32 v26, v26
	s_nop 0
	v_add_f32_e32 v26, 1.0, v26
	v_rcp_f32_e32 v26, v26
	s_nop 0
	v_mul_f32_e32 v26, v31, v26
	v_mul_f32_e32 v31, 0xbfb8aa3b, v27
	v_exp_f32_e32 v31, v31
	v_cvt_pk_bf16_f32 v26, v30, v26
	v_add_co_u32_e32 v30, vcc, s0, v130
	v_add_f32_e32 v31, 1.0, v31
	v_rcp_f32_e32 v31, v31
	s_mov_b64 s[0:1], 0xb0000
	v_mul_f32_e32 v31, v27, v31
	v_mul_f32_e32 v27, 0xbfb8aa3b, v32
	v_exp_f32_e32 v27, v27
	s_nop 0
	v_add_f32_e32 v27, 1.0, v27
	v_rcp_f32_e32 v27, v27
	s_nop 0
	v_mul_f32_e32 v27, v32, v27
	v_mul_f32_e32 v32, 0xbfb8aa3b, v28
	v_exp_f32_e32 v32, v32
	s_nop 0
	v_add_f32_e32 v32, 1.0, v32
	v_rcp_f32_e32 v32, v32
	s_nop 0
	v_mul_f32_e32 v32, v28, v32
	v_mul_f32_e32 v28, 0xbfb8aa3b, v33
	v_exp_f32_e32 v28, v28
	s_nop 0
	v_add_f32_e32 v28, 1.0, v28
	v_rcp_f32_e32 v28, v28
	s_nop 0
	v_mul_f32_e32 v28, v33, v28
	v_mul_f32_e32 v33, 0xbfb8aa3b, v29
	v_exp_f32_e32 v33, v33
	v_cvt_pk_bf16_f32 v27, v27, v28
	v_cvt_pk_bf16_f32 v28, v36, v31
	v_addc_co_u32_e32 v31, vcc, 0, v131, vcc
	v_add_f32_e32 v33, 1.0, v33
	v_rcp_f32_e32 v33, v33
	s_nop 0
	v_mul_f32_e32 v29, v29, v33
	v_cvt_pk_bf16_f32 v29, v32, v29
	global_store_dwordx4 v[30:31], v[26:29], off sc1
	s_nop 1
	v_mul_f32_e32 v26, 0xbfb8aa3b, v22
	v_exp_f32_e32 v26, v26
	s_nop 0
	v_add_f32_e32 v26, 1.0, v26
	v_rcp_f32_e32 v26, v26
	s_nop 0
	v_mul_f32_e32 v22, v22, v26
	v_mul_f32_e32 v26, 0xbfb8aa3b, v18
	v_exp_f32_e32 v26, v26
	s_nop 0
	v_add_f32_e32 v26, 1.0, v26
	v_rcp_f32_e32 v26, v26
	s_nop 0
	v_mul_f32_e32 v26, v18, v26
	v_mul_f32_e32 v18, 0xbfb8aa3b, v23
	v_exp_f32_e32 v18, v18
	s_nop 0
	v_add_f32_e32 v18, 1.0, v18
	v_rcp_f32_e32 v18, v18
	s_nop 0
	v_mul_f32_e32 v18, v23, v18
	v_mul_f32_e32 v23, 0xbfb8aa3b, v19
	v_exp_f32_e32 v23, v23
	v_cvt_pk_bf16_f32 v18, v22, v18
	s_nop 0
	v_add_f32_e32 v23, 1.0, v23
	v_rcp_f32_e32 v23, v23
	s_nop 0
	v_mul_f32_e32 v23, v19, v23
	v_mul_f32_e32 v19, 0xbfb8aa3b, v24
	v_exp_f32_e32 v19, v19
	s_nop 0
	v_add_f32_e32 v19, 1.0, v19
	v_rcp_f32_e32 v19, v19
	s_nop 0
	v_mul_f32_e32 v19, v24, v19
	v_mul_f32_e32 v24, 0xbfb8aa3b, v20
	v_exp_f32_e32 v24, v24
	s_nop 0
	v_add_f32_e32 v24, 1.0, v24
	v_rcp_f32_e32 v24, v24
	s_nop 0
	v_mul_f32_e32 v24, v20, v24
	v_mul_f32_e32 v20, 0xbfb8aa3b, v25
	v_exp_f32_e32 v20, v20
	s_nop 0
	v_add_f32_e32 v20, 1.0, v20
	v_rcp_f32_e32 v20, v20
	s_nop 0
	v_mul_f32_e32 v20, v25, v20
	v_mul_f32_e32 v25, 0xbfb8aa3b, v21
	v_exp_f32_e32 v25, v25
	v_cvt_pk_bf16_f32 v19, v19, v20
	v_cvt_pk_bf16_f32 v20, v26, v23
	s_nop 0
	v_add_f32_e32 v25, 1.0, v25
	v_rcp_f32_e32 v25, v25
	s_nop 0
	v_mul_f32_e32 v21, v21, v25
	v_cvt_pk_bf16_f32 v21, v24, v21
	global_store_dwordx4 v[34:35], v[18:21], off offset:256 sc1
	s_nop 1
	v_mul_f32_e32 v20, 0xbfb8aa3b, v14
	v_exp_f32_e32 v20, v20
	v_lshl_add_u64 v[18:19], v[130:131], 0, s[0:1]
	s_mov_b32 s0, 0xb0000
	v_add_f32_e32 v20, 1.0, v20
	v_rcp_f32_e32 v20, v20
	s_nop 0
	v_mul_f32_e32 v14, v14, v20
	v_mul_f32_e32 v20, 0xbfb8aa3b, v10
	v_exp_f32_e32 v20, v20
	s_nop 0
	v_add_f32_e32 v20, 1.0, v20
	v_rcp_f32_e32 v20, v20
	s_nop 0
	v_mul_f32_e32 v20, v10, v20
	v_mul_f32_e32 v10, 0xbfb8aa3b, v15
	v_exp_f32_e32 v10, v10
	s_nop 0
	v_add_f32_e32 v10, 1.0, v10
	v_rcp_f32_e32 v10, v10
	s_nop 0
	v_mul_f32_e32 v10, v15, v10
	v_mul_f32_e32 v15, 0xbfb8aa3b, v11
	v_exp_f32_e32 v15, v15
	v_cvt_pk_bf16_f32 v10, v14, v10
	v_add_co_u32_e32 v14, vcc, s0, v130
	v_add_f32_e32 v15, 1.0, v15
	v_rcp_f32_e32 v15, v15
	s_nop 0
	v_mul_f32_e32 v15, v11, v15
	v_mul_f32_e32 v11, 0xbfb8aa3b, v16
	v_exp_f32_e32 v11, v11
	s_nop 0
	v_add_f32_e32 v11, 1.0, v11
	v_rcp_f32_e32 v11, v11
	s_nop 0
	v_mul_f32_e32 v11, v16, v11
	v_mul_f32_e32 v16, 0xbfb8aa3b, v12
	v_exp_f32_e32 v16, v16
	s_nop 0
	v_add_f32_e32 v16, 1.0, v16
	v_rcp_f32_e32 v16, v16
	s_nop 0
	v_mul_f32_e32 v16, v12, v16
	v_mul_f32_e32 v12, 0xbfb8aa3b, v17
	v_exp_f32_e32 v12, v12
	s_nop 0
	v_add_f32_e32 v12, 1.0, v12
	v_rcp_f32_e32 v12, v12
	s_nop 0
	v_mul_f32_e32 v12, v17, v12
	v_mul_f32_e32 v17, 0xbfb8aa3b, v13
	v_exp_f32_e32 v17, v17
	v_cvt_pk_bf16_f32 v11, v11, v12
	v_cvt_pk_bf16_f32 v12, v20, v15
	v_addc_co_u32_e32 v15, vcc, 0, v131, vcc
	v_add_f32_e32 v17, 1.0, v17
	v_rcp_f32_e32 v17, v17
	s_nop 0
	v_mul_f32_e32 v13, v13, v17
	v_cvt_pk_bf16_f32 v13, v16, v13
	global_store_dwordx4 v[14:15], v[10:13], off sc1
	s_nop 1
	v_mul_f32_e32 v10, 0xbfb8aa3b, v6
	v_exp_f32_e32 v10, v10
	s_nop 0
	v_add_f32_e32 v10, 1.0, v10
	v_rcp_f32_e32 v10, v10
	s_nop 0
	v_mul_f32_e32 v6, v6, v10
	v_mul_f32_e32 v10, 0xbfb8aa3b, v2
	v_exp_f32_e32 v10, v10
	s_nop 0
	v_add_f32_e32 v10, 1.0, v10
	v_rcp_f32_e32 v10, v10
	s_nop 0
	v_mul_f32_e32 v10, v2, v10
	v_mul_f32_e32 v2, 0xbfb8aa3b, v7
	v_exp_f32_e32 v2, v2
	s_nop 0
	v_add_f32_e32 v2, 1.0, v2
	v_rcp_f32_e32 v2, v2
	s_nop 0
	v_mul_f32_e32 v2, v7, v2
	v_mul_f32_e32 v7, 0xbfb8aa3b, v3
	v_exp_f32_e32 v7, v7
	v_cvt_pk_bf16_f32 v2, v6, v2
	s_nop 0
	v_add_f32_e32 v7, 1.0, v7
	v_rcp_f32_e32 v7, v7
	s_nop 0
	v_mul_f32_e32 v7, v3, v7
	v_mul_f32_e32 v3, 0xbfb8aa3b, v8
	v_exp_f32_e32 v3, v3
	s_nop 0
	v_add_f32_e32 v3, 1.0, v3
	v_rcp_f32_e32 v3, v3
	s_nop 0
	v_mul_f32_e32 v3, v8, v3
	v_mul_f32_e32 v8, 0xbfb8aa3b, v4
	v_exp_f32_e32 v8, v8
	s_nop 0
	v_add_f32_e32 v8, 1.0, v8
	v_rcp_f32_e32 v8, v8
	s_nop 0
	v_mul_f32_e32 v8, v4, v8
	v_mul_f32_e32 v4, 0xbfb8aa3b, v9
	v_exp_f32_e32 v4, v4
	s_nop 0
	v_add_f32_e32 v4, 1.0, v4
	v_rcp_f32_e32 v4, v4
	s_nop 0
	v_mul_f32_e32 v4, v9, v4
	v_mul_f32_e32 v9, 0xbfb8aa3b, v5
	v_exp_f32_e32 v9, v9
	v_cvt_pk_bf16_f32 v3, v3, v4
	v_cvt_pk_bf16_f32 v4, v10, v7
	s_nop 0
	v_add_f32_e32 v9, 1.0, v9
	v_rcp_f32_e32 v9, v9
	s_nop 0
	v_mul_f32_e32 v5, v5, v9
	v_cvt_pk_bf16_f32 v5, v8, v5
	global_store_dwordx4 v[18:19], v[2:5], off offset:256 sc1
	s_and_b64 vcc, exec, s[4:5]
	s_mov_b64 s[4:5], -1
	s_cbranch_vccnz .LBB0_728

.LBB0_829:
	s_or_b64 exec, exec, s[4:5]
	v_add_u32_e32 v4, 1, v4
	v_add_u32_e32 v2, v5, v2
	v_cmp_eq_u32_e32 vcc, v4, v2
	s_and_saveexec_b64 s[4:5], vcc
	s_cbranch_execz .LBB0_832
	s_mov_b64 s[8:9], exec
	v_mbcnt_lo_u32_b32 v2, s8, 0
	s_nop 0
	s_waitcnt lgkmcnt(0)
	s_waitcnt vmcnt(0)
	v_mbcnt_hi_u32_b32 v2, s9, v2
	v_cmp_eq_u32_e32 vcc, 0, v2
	s_and_b64 s[0:1], exec, vcc
	s_mov_b64 exec, s[0:1]
	s_cbranch_execz .LBB0_832
	s_bcnt1_i32_b64 s0, s[8:9]
	v_mov_b32_e32 v2, 0x3000
	v_mov_b32_e32 v4, s0
	global_atomic_add v2, v4, s[26:27] offset:1024
